# nt (non-temporal) hint on read-once streaming loads: weight-prep phase, norm passes, residual-epilogue loads; plus global_* ops and deferred SSQ atomics
# speedup vs baseline: 1.0016x; 1.0016x over previous
; #define p_cvec INP(1)
; #define p_w_ada INP(3)
; __global__ void __launch_bounds__(NTHR, 2) mk_fwd(Args args) {
;     ...
;             for (int r = g0; r < I_MOD; r += gn) { const int sl = r / 72, cb = r % 72, col = cb * 256 + lane * 4; f32x4 acc = {0.f, 0.f, 0.f, 0.f};
;                 const float* wp = p_w_ada + (size_t)(sl * 64) * NMOD + col; const float* cp = p_cvec + sl * 64;
; #pragma unroll 16
;                 for (int kk = 0; kk < 64; ++kk) { const float cv = cp[kk]; const float sv = cv / (1.0f + expf(-cv)); acc += *(const f32x4*)(wp + (size_t)kk * NMOD) * sv; }
;                 *(f32x4*)(p_modp + (size_t)sl * NMOD + col) = acc; } }
.LBB0_110:
	v_mov_b64_e32 v[4:5], s[36:37]
	global_load_dwordx4 v[28:31], v[4:5], off nt
	global_load_dwordx4 v[12:15], v[4:5], off offset:16 nt
	global_load_dwordx4 v[8:11], v[4:5], off offset:32 nt
	v_lshl_add_u64 v[36:37], v[86:87], 0, s[38:39]
	v_add_co_u32_e32 v38, vcc, s41, v36
	global_load_dwordx4 v[4:7], v[4:5], off offset:48 nt
	s_nop 0
	v_addc_co_u32_e32 v39, vcc, 0, v37, vcc
	v_add_co_u32_e32 v94, vcc, s45, v36
	s_add_u32 s38, s38, 0x120000
	s_nop 0
	v_addc_co_u32_e32 v95, vcc, 0, v37, vcc
	v_add_co_u32_e32 v96, vcc, s46, v36
	s_addc_u32 s39, s39, 0
	s_nop 0
	v_addc_co_u32_e32 v97, vcc, 0, v37, vcc
	v_add_co_u32_e32 v98, vcc, s47, v36
	s_add_u32 s36, s36, 64
	s_nop 0
	v_addc_co_u32_e32 v99, vcc, 0, v37, vcc
	v_add_co_u32_e32 v100, vcc, s48, v36
	s_addc_u32 s37, s37, 0
	s_nop 0
	v_addc_co_u32_e32 v101, vcc, 0, v37, vcc
	v_add_co_u32_e32 v102, vcc, s49, v36
	s_cmp_eq_u32 s38, 0x480000
	s_nop 0
	v_addc_co_u32_e32 v103, vcc, 0, v37, vcc
	v_add_co_u32_e32 v104, vcc, s50, v36
	s_waitcnt vmcnt(0) lgkmcnt(0)
	v_mul_f32_e32 v93, 0xbfb8aa3b, v28
	v_addc_co_u32_e32 v105, vcc, 0, v37, vcc
	v_add_co_u32_e32 v106, vcc, s51, v36
	v_cmp_nlt_f32_e64 s[30:31], s43, v28
	s_nop 0
	v_addc_co_u32_e32 v107, vcc, 0, v37, vcc
	v_add_co_u32_e32 v108, vcc, s52, v36
	v_cmp_nlt_f32_e64 s[0:1], s43, v30
	s_nop 0
	v_addc_co_u32_e32 v109, vcc, 0, v37, vcc
	v_add_co_u32_e32 v110, vcc, s53, v36
	v_cmp_nlt_f32_e64 s[4:5], s43, v31
	s_nop 0
	v_addc_co_u32_e32 v111, vcc, 0, v37, vcc
	v_add_co_u32_e32 v112, vcc, s54, v36
	v_cmp_nlt_f32_e64 s[6:7], s43, v12
	s_nop 0
	v_addc_co_u32_e32 v113, vcc, 0, v37, vcc
	v_add_co_u32_e32 v114, vcc, s55, v36
	v_cmp_nlt_f32_e64 s[8:9], s43, v13
	s_nop 0
	v_addc_co_u32_e32 v115, vcc, 0, v37, vcc
	v_add_co_u32_e32 v116, vcc, s56, v36
	v_cmp_nlt_f32_e64 s[10:11], s43, v14
	s_nop 0
	v_addc_co_u32_e32 v117, vcc, 0, v37, vcc
	v_add_co_u32_e32 v118, vcc, s57, v36
	v_cmp_nlt_f32_e64 s[28:29], s43, v15
	s_nop 0
	v_addc_co_u32_e32 v119, vcc, 0, v37, vcc
	v_add_co_u32_e32 v120, vcc, s58, v36
	v_cmp_nlt_f32_e64 s[12:13], s43, v8
	s_nop 0
	v_addc_co_u32_e32 v121, vcc, 0, v37, vcc
	global_load_dwordx4 v[80:83], v[36:37], off nt
	global_load_dwordx4 v[76:79], v[38:39], off nt
	global_load_dwordx4 v[72:75], v[94:95], off nt
	global_load_dwordx4 v[68:71], v[96:97], off nt
	global_load_dwordx4 v[64:67], v[98:99], off nt
	global_load_dwordx4 v[60:63], v[100:101], off nt
	global_load_dwordx4 v[56:59], v[102:103], off nt
	global_load_dwordx4 v[52:55], v[104:105], off nt
	global_load_dwordx4 v[48:51], v[106:107], off nt
	global_load_dwordx4 v[44:47], v[108:109], off nt
	global_load_dwordx4 v[40:43], v[110:111], off nt
	global_load_dwordx4 v[32:35], v[112:113], off nt
	global_load_dwordx4 v[24:27], v[114:115], off nt
	global_load_dwordx4 v[20:23], v[116:117], off nt
	global_load_dwordx4 v[16:19], v[118:119], off nt
	global_load_dwordx4 v[36:39], v[120:121], off nt
	v_mul_f32_e32 v94, 0xbfb8aa3b, v29
	v_rndne_f32_e32 v109, v93
	v_fma_f32 v110, v28, s42, -v93
	v_mul_f32_e32 v95, 0xbfb8aa3b, v30
	v_rndne_f32_e32 v111, v94
	v_fma_f32 v112, v29, s42, -v94
	v_sub_f32_e32 v93, v93, v109
	v_fmac_f32_e32 v110, 0xb2a5705f, v28
	v_mul_f32_e32 v96, 0xbfb8aa3b, v31
	v_rndne_f32_e32 v113, v95
	v_fma_f32 v114, v30, s42, -v95
	v_sub_f32_e32 v94, v94, v111
	v_fmac_f32_e32 v112, 0xb2a5705f, v29
	v_add_f32_e32 v93, v93, v110
	v_mul_f32_e32 v97, 0xbfb8aa3b, v12
	v_rndne_f32_e32 v115, v96
	v_fma_f32 v116, v31, s42, -v96
	v_cvt_i32_f32_e32 v109, v109
	v_sub_f32_e32 v95, v95, v113
	v_fmac_f32_e32 v114, 0xb2a5705f, v30
	v_add_f32_e32 v94, v94, v112
	v_exp_f32_e32 v93, v93
	v_mul_f32_e32 v98, 0xbfb8aa3b, v13
	v_rndne_f32_e32 v117, v97
	v_fma_f32 v118, v12, s42, -v97
	v_cvt_i32_f32_e32 v111, v111
	v_sub_f32_e32 v96, v96, v115
	v_fmac_f32_e32 v116, 0xb2a5705f, v31
	v_add_f32_e32 v95, v95, v114
	v_exp_f32_e32 v94, v94
	v_mul_f32_e32 v99, 0xbfb8aa3b, v14
	v_rndne_f32_e32 v119, v98
	v_fma_f32 v120, v13, s42, -v98
	v_cvt_i32_f32_e32 v113, v113
	v_sub_f32_e32 v97, v97, v117
	v_fmac_f32_e32 v118, 0xb2a5705f, v12
	v_add_f32_e32 v96, v96, v116
	v_exp_f32_e32 v95, v95
	v_mul_f32_e32 v100, 0xbfb8aa3b, v15
	v_rndne_f32_e32 v121, v99
	v_fma_f32 v122, v14, s42, -v99
	v_cvt_i32_f32_e32 v115, v115
	v_sub_f32_e32 v98, v98, v119
	v_fmac_f32_e32 v120, 0xb2a5705f, v13
	v_add_f32_e32 v97, v97, v118
	v_exp_f32_e32 v96, v96
	v_mul_f32_e32 v101, 0xbfb8aa3b, v8
	v_rndne_f32_e32 v123, v100
	v_fma_f32 v124, v15, s42, -v100
	v_cvt_i32_f32_e32 v117, v117
	v_sub_f32_e32 v99, v99, v121
	v_fmac_f32_e32 v122, 0xb2a5705f, v14
	v_add_f32_e32 v98, v98, v120
	v_exp_f32_e32 v97, v97
	v_ldexp_f32 v93, v93, v109
	v_mul_f32_e32 v102, 0xbfb8aa3b, v9
	v_rndne_f32_e32 v125, v101
	v_fma_f32 v126, v8, s42, -v101
	v_cvt_i32_f32_e32 v119, v119
	v_sub_f32_e32 v100, v100, v123
	v_fmac_f32_e32 v124, 0xb2a5705f, v15
	v_add_f32_e32 v99, v99, v122
	v_exp_f32_e32 v98, v98
	v_ldexp_f32 v94, v94, v111
	v_cmp_nlt_f32_e32 vcc, s43, v29
	v_cndmask_b32_e64 v93, 0, v93, s[30:31]
	v_cmp_ngt_f32_e64 s[30:31], s44, v28
	v_mul_f32_e32 v103, 0xbfb8aa3b, v10
	v_rndne_f32_e32 v127, v102
	v_fma_f32 v128, v9, s42, -v102
	v_sub_f32_e32 v101, v101, v125
	v_fmac_f32_e32 v126, 0xb2a5705f, v8
	v_cvt_i32_f32_e32 v121, v121
	v_add_f32_e32 v100, v100, v124
	v_exp_f32_e32 v99, v99
	v_ldexp_f32 v95, v95, v113
	v_cndmask_b32_e32 v94, 0, v94, vcc
	v_cmp_ngt_f32_e32 vcc, s44, v29
	v_cndmask_b32_e64 v93, v92, v93, s[30:31]
	v_mul_f32_e32 v104, 0xbfb8aa3b, v11
	v_mul_f32_e32 v108, 0xbfb8aa3b, v7
	v_rndne_f32_e32 v129, v103
	v_fma_f32 v130, v10, s42, -v103
	v_sub_f32_e32 v102, v102, v127
	v_fmac_f32_e32 v128, 0xb2a5705f, v9
	v_cvt_i32_f32_e32 v123, v123
; __global__ void __launch_bounds__(NTHR, 2) mk_fwd(Args args) {
;     ...
;                 for (int kk = 0; kk < 64; ++kk) { const float cv = cp[kk]; const float sv = cv / (1.0f + expf(-cv)); acc += *(const f32x4*)(wp + (size_t)kk * NMOD) * sv; }
	v_add_f32_e32 v101, v101, v126
	v_exp_f32_e32 v100, v100
	v_ldexp_f32 v96, v96, v115
	v_cndmask_b32_e64 v95, 0, v95, s[0:1]
	v_cmp_ngt_f32_e64 s[0:1], s44, v30
	v_cndmask_b32_e32 v94, v92, v94, vcc
	v_add_f32_e32 v93, 1.0, v93
	v_mul_f32_e32 v105, 0xbfb8aa3b, v4
	v_mul_f32_e32 v107, 0xbfb8aa3b, v6
	v_rndne_f32_e32 v131, v104
	v_fma_f32 v132, v11, s42, -v104
	v_rndne_f32_e32 v139, v108
	v_fma_f32 v140, v7, s42, -v108
	v_sub_f32_e32 v103, v103, v129
	v_fmac_f32_e32 v130, 0xb2a5705f, v10
	v_cvt_i32_f32_e32 v125, v125
	v_add_f32_e32 v102, v102, v128
	v_exp_f32_e32 v101, v101
	v_ldexp_f32 v97, v97, v117
	v_cndmask_b32_e64 v96, 0, v96, s[4:5]
	v_cmp_ngt_f32_e64 s[4:5], s44, v31
	v_cndmask_b32_e64 v95, v92, v95, s[0:1]
	v_add_f32_e32 v94, 1.0, v94
	v_div_scale_f32 v109, s[0:1], v93, v93, v28
	v_mul_f32_e32 v106, 0xbfb8aa3b, v5
	v_rndne_f32_e32 v133, v105
	v_fma_f32 v134, v4, s42, -v105
	v_rndne_f32_e32 v137, v107
	v_fma_f32 v138, v6, s42, -v107
	v_sub_f32_e32 v104, v104, v131
	v_fmac_f32_e32 v132, 0xb2a5705f, v11
	v_sub_f32_e32 v108, v108, v139
	v_fmac_f32_e32 v140, 0xb2a5705f, v7
	v_cvt_i32_f32_e32 v127, v127
	v_add_f32_e32 v103, v103, v130
	v_exp_f32_e32 v102, v102
	v_ldexp_f32 v98, v98, v119
	v_cndmask_b32_e64 v97, 0, v97, s[6:7]
	v_cmp_ngt_f32_e64 s[6:7], s44, v12
	v_cndmask_b32_e64 v96, v92, v96, s[4:5]
	v_add_f32_e32 v95, 1.0, v95
	v_div_scale_f32 v111, s[0:1], v94, v94, v29
	v_rcp_f32_e32 v141, v109
	v_rndne_f32_e32 v135, v106
	v_fma_f32 v136, v5, s42, -v106
	v_sub_f32_e32 v105, v105, v133
	v_fmac_f32_e32 v134, 0xb2a5705f, v4
	v_sub_f32_e32 v107, v107, v137
	v_fmac_f32_e32 v138, 0xb2a5705f, v6
	v_cvt_i32_f32_e32 v129, v129
	v_add_f32_e32 v104, v104, v132
	v_add_f32_e32 v108, v108, v140
	v_exp_f32_e32 v103, v103
	v_ldexp_f32 v99, v99, v121
	v_cndmask_b32_e64 v98, 0, v98, s[8:9]
	v_cmp_ngt_f32_e64 s[8:9], s44, v13
	v_cndmask_b32_e64 v97, v92, v97, s[6:7]
	v_add_f32_e32 v96, 1.0, v96
	v_div_scale_f32 v113, s[0:1], v95, v95, v30
	v_rcp_f32_e32 v142, v111
	v_sub_f32_e32 v106, v106, v135
	v_fmac_f32_e32 v136, 0xb2a5705f, v5
	v_cvt_i32_f32_e32 v131, v131
	v_cvt_i32_f32_e32 v139, v139
	v_add_f32_e32 v105, v105, v134
	v_add_f32_e32 v107, v107, v138
	v_exp_f32_e32 v104, v104
	v_exp_f32_e32 v108, v108
	v_ldexp_f32 v100, v100, v123
	v_cndmask_b32_e64 v99, 0, v99, s[10:11]
	v_cmp_ngt_f32_e64 s[10:11], s44, v14
	v_cndmask_b32_e64 v98, v92, v98, s[8:9]
	v_add_f32_e32 v97, 1.0, v97
	v_div_scale_f32 v115, s[0:1], v96, v96, v31
	v_rcp_f32_e32 v143, v113
	v_cvt_i32_f32_e32 v133, v133
	v_cvt_i32_f32_e32 v137, v137
	v_add_f32_e32 v106, v106, v136
	v_exp_f32_e32 v105, v105
	v_exp_f32_e32 v107, v107
	v_ldexp_f32 v101, v101, v125
	v_cndmask_b32_e64 v100, 0, v100, s[28:29]
	v_cmp_ngt_f32_e64 s[28:29], s44, v15
	v_cndmask_b32_e64 v99, v92, v99, s[10:11]
	v_add_f32_e32 v98, 1.0, v98
	v_div_scale_f32 v117, s[0:1], v97, v97, v12
	v_rcp_f32_e32 v144, v115
	v_cvt_i32_f32_e32 v135, v135
	v_exp_f32_e32 v106, v106
	v_ldexp_f32 v102, v102, v127
	v_cmp_nlt_f32_e64 s[14:15], s43, v9
	v_cndmask_b32_e64 v101, 0, v101, s[12:13]
	v_cmp_ngt_f32_e64 s[12:13], s44, v8
	v_cndmask_b32_e64 v100, v92, v100, s[28:29]
	v_add_f32_e32 v99, 1.0, v99
	v_div_scale_f32 v119, s[0:1], v98, v98, v13
	v_rcp_f32_e32 v145, v117
	v_fma_f32 v157, -v109, v141, 1.0
	v_ldexp_f32 v103, v103, v129
	v_cmp_nlt_f32_e64 s[16:17], s43, v10
	v_cndmask_b32_e64 v102, 0, v102, s[14:15]
	v_cmp_ngt_f32_e64 s[14:15], s44, v9
	v_cndmask_b32_e64 v101, v92, v101, s[12:13]
	v_add_f32_e32 v100, 1.0, v100
	v_div_scale_f32 v110, vcc, v28, v93, v28
	v_div_scale_f32 v121, s[0:1], v99, v99, v14
	v_rcp_f32_e32 v146, v119
	v_fma_f32 v158, -v111, v142, 1.0
	v_fmac_f32_e32 v141, v157, v141
	v_ldexp_f32 v104, v104, v131
	v_ldexp_f32 v108, v108, v139
	v_cmp_nlt_f32_e64 s[18:19], s43, v11
	v_cmp_nlt_f32_e64 s[26:27], s43, v7
	v_cndmask_b32_e64 v103, 0, v103, s[16:17]
	v_cmp_ngt_f32_e64 s[16:17], s44, v10
	v_cndmask_b32_e64 v102, v92, v102, s[14:15]
	v_add_f32_e32 v101, 1.0, v101
	v_div_scale_f32 v112, s[30:31], v29, v94, v29
	v_div_scale_f32 v123, s[0:1], v100, v100, v15
	v_rcp_f32_e32 v147, v121
	v_fma_f32 v159, -v113, v143, 1.0
	v_fmac_f32_e32 v142, v158, v142
	v_mul_f32_e32 v157, v110, v141
	v_ldexp_f32 v105, v105, v133
	v_ldexp_f32 v107, v107, v137
	v_cmp_nlt_f32_e64 s[20:21], s43, v4
	v_cmp_nlt_f32_e64 s[24:25], s43, v6
	v_cndmask_b32_e64 v104, 0, v104, s[18:19]
	v_cmp_ngt_f32_e64 s[18:19], s44, v11
	v_cndmask_b32_e64 v108, 0, v108, s[26:27]
	v_cmp_ngt_f32_e64 s[26:27], s44, v7
	v_cndmask_b32_e64 v103, v92, v103, s[16:17]
	v_add_f32_e32 v102, 1.0, v102
	v_div_scale_f32 v114, s[28:29], v30, v95, v30
	v_div_scale_f32 v125, s[0:1], v101, v101, v8
	v_rcp_f32_e32 v148, v123
	v_fma_f32 v160, -v115, v144, 1.0
	v_fmac_f32_e32 v143, v159, v143
	v_mul_f32_e32 v158, v112, v142
	v_fma_f32 v173, -v109, v157, v110
	v_ldexp_f32 v106, v106, v135
	v_cmp_nlt_f32_e64 s[22:23], s43, v5
	v_cndmask_b32_e64 v105, 0, v105, s[20:21]
	v_cmp_ngt_f32_e64 s[20:21], s44, v4
	v_cndmask_b32_e64 v107, 0, v107, s[24:25]
	v_cmp_ngt_f32_e64 s[24:25], s44, v6
	v_cndmask_b32_e64 v104, v92, v104, s[18:19]
	v_cndmask_b32_e64 v108, v92, v108, s[26:27]
	v_add_f32_e32 v103, 1.0, v103
	v_div_scale_f32 v116, s[26:27], v31, v96, v31
	v_div_scale_f32 v127, s[0:1], v102, v102, v9
	v_rcp_f32_e32 v149, v125
	v_fma_f32 v161, -v117, v145, 1.0
	v_fmac_f32_e32 v144, v160, v144
	v_mul_f32_e32 v159, v114, v143
	v_fma_f32 v174, -v111, v158, v112
	v_fmac_f32_e32 v157, v173, v141
	v_cndmask_b32_e64 v106, 0, v106, s[22:23]
	v_cmp_ngt_f32_e64 s[22:23], s44, v5
	v_cndmask_b32_e64 v105, v92, v105, s[20:21]
	v_cndmask_b32_e64 v107, v92, v107, s[24:25]
	v_add_f32_e32 v104, 1.0, v104
; __global__ void __launch_bounds__(NTHR, 2) mk_fwd(Args args) {
;     ...
;                 for (int kk = 0; kk < 64; ++kk) { const float cv = cp[kk]; const float sv = cv / (1.0f + expf(-cv)); acc += *(const f32x4*)(wp + (size_t)kk * NMOD) * sv; }
	v_div_scale_f32 v118, s[24:25], v12, v97, v12
	v_div_scale_f32 v129, s[0:1], v103, v103, v10
	v_rcp_f32_e32 v150, v127
	v_fma_f32 v162, -v119, v146, 1.0
	v_fmac_f32_e32 v145, v161, v145
	v_mul_f32_e32 v160, v116, v144
	v_fma_f32 v175, -v113, v159, v114
	v_fmac_f32_e32 v158, v174, v142
	v_fma_f32 v109, -v109, v157, v110
	v_cndmask_b32_e64 v106, v92, v106, s[22:23]
	v_add_f32_e32 v105, 1.0, v105
	v_div_scale_f32 v120, s[22:23], v13, v98, v13
	v_div_scale_f32 v131, s[0:1], v104, v104, v11
	v_rcp_f32_e32 v151, v129
	v_fma_f32 v163, -v121, v147, 1.0
	v_fmac_f32_e32 v146, v162, v146
	v_mul_f32_e32 v161, v118, v145
	v_fma_f32 v176, -v115, v160, v116
	v_fmac_f32_e32 v159, v175, v143
	v_fma_f32 v110, -v111, v158, v112
	v_div_fmas_f32 v109, v109, v141, v157
	s_mov_b64 vcc, s[30:31]
	v_add_f32_e32 v106, 1.0, v106
	v_div_scale_f32 v122, s[20:21], v14, v99, v14
	v_div_scale_f32 v133, s[0:1], v105, v105, v4
	v_rcp_f32_e32 v152, v131
	v_fma_f32 v164, -v123, v148, 1.0
	v_fmac_f32_e32 v147, v163, v147
	v_mul_f32_e32 v162, v120, v146
	v_fma_f32 v177, -v117, v161, v118
	v_fmac_f32_e32 v160, v176, v144
	v_fma_f32 v111, -v113, v159, v114
	v_div_fixup_f32 v28, v109, v93, v28
	v_div_fmas_f32 v93, v110, v142, v158
	s_mov_b64 vcc, s[28:29]
	v_add_f32_e32 v107, 1.0, v107
	v_div_scale_f32 v124, s[18:19], v15, v100, v15
	v_div_scale_f32 v135, s[0:1], v106, v106, v5
	v_rcp_f32_e32 v153, v133
	v_fma_f32 v165, -v125, v149, 1.0
	v_fmac_f32_e32 v148, v164, v148
	v_mul_f32_e32 v163, v122, v147
	v_fma_f32 v178, -v119, v162, v120
	v_fmac_f32_e32 v161, v177, v145
	v_fma_f32 v112, -v115, v160, v116
	s_waitcnt vmcnt(0) lgkmcnt(0)
; #define p_cvec INP(1)
; #define p_w_ada INP(3)
; __global__ void __launch_bounds__(NTHR, 2) mk_fwd(Args args) {
;     ...
;             for (int r = g0; r < I_MOD; r += gn) { const int sl = r / 72, cb = r % 72, col = cb * 256 + lane * 4; f32x4 acc = {0.f, 0.f, 0.f, 0.f};
;                 const float* wp = p_w_ada + (size_t)(sl * 64) * NMOD + col; const float* cp = p_cvec + sl * 64;
; #pragma unroll 16
;                 for (int kk = 0; kk < 64; ++kk) { const float cv = cp[kk]; const float sv = cv / (1.0f + expf(-cv)); acc += *(const f32x4*)(wp + (size_t)kk * NMOD) * sv; }
;                 *(f32x4*)(p_modp + (size_t)sl * NMOD + col) = acc; } }
	v_pk_fma_f32 v[0:1], v[80:81], v[28:29], v[0:1] op_sel_hi:[1,0,1]
	v_pk_fma_f32 v[2:3], v[82:83], v[28:29], v[2:3] op_sel_hi:[1,0,1]
	v_div_fixup_f32 v28, v93, v94, v29
	v_div_fmas_f32 v29, v111, v143, v159
	s_mov_b64 vcc, s[26:27]
	v_add_f32_e32 v108, 1.0, v108
	v_div_scale_f32 v126, s[16:17], v8, v101, v8
	v_div_scale_f32 v137, s[0:1], v107, v107, v6
	v_rcp_f32_e32 v154, v135
	v_fma_f32 v166, -v127, v150, 1.0
	v_fmac_f32_e32 v149, v165, v149
	v_mul_f32_e32 v164, v124, v148
	v_fma_f32 v179, -v121, v163, v122
	v_fmac_f32_e32 v162, v178, v146
	v_fma_f32 v113, -v117, v161, v118
	v_pk_fma_f32 v[2:3], v[78:79], v[28:29], v[2:3] op_sel_hi:[1,0,1]
	v_pk_fma_f32 v[0:1], v[76:77], v[28:29], v[0:1] op_sel_hi:[1,0,1]
	v_div_fixup_f32 v28, v29, v95, v30
	v_div_fmas_f32 v29, v112, v144, v160
	s_mov_b64 vcc, s[24:25]
	v_div_scale_f32 v128, s[14:15], v9, v102, v9
	v_div_scale_f32 v139, s[0:1], v108, v108, v7
	v_rcp_f32_e32 v155, v137
	v_fma_f32 v167, -v129, v151, 1.0
	v_fmac_f32_e32 v150, v166, v150
	v_mul_f32_e32 v165, v126, v149
	v_fma_f32 v180, -v123, v164, v124
	v_fmac_f32_e32 v163, v179, v147
	v_fma_f32 v114, -v119, v162, v120
	v_pk_fma_f32 v[0:1], v[72:73], v[28:29], v[0:1] op_sel_hi:[1,0,1]
	v_pk_fma_f32 v[2:3], v[74:75], v[28:29], v[2:3] op_sel_hi:[1,0,1]
	v_div_fixup_f32 v28, v29, v96, v31
	v_div_fmas_f32 v29, v113, v145, v161
	s_mov_b64 vcc, s[22:23]
	v_div_scale_f32 v130, s[12:13], v10, v103, v10
	v_rcp_f32_e32 v156, v139
	v_fma_f32 v168, -v131, v152, 1.0
	v_fmac_f32_e32 v151, v167, v151
	v_mul_f32_e32 v166, v128, v150
	v_fma_f32 v181, -v125, v165, v126
	v_fmac_f32_e32 v164, v180, v148
	v_fma_f32 v115, -v121, v163, v122
	v_pk_fma_f32 v[2:3], v[70:71], v[28:29], v[2:3] op_sel_hi:[1,0,1]
	v_pk_fma_f32 v[0:1], v[68:69], v[28:29], v[0:1] op_sel_hi:[1,0,1]
	v_div_fixup_f32 v12, v29, v97, v12
	v_div_fmas_f32 v28, v114, v146, v162
	s_mov_b64 vcc, s[20:21]
	v_div_scale_f32 v132, s[10:11], v11, v104, v11
	v_fma_f32 v169, -v133, v153, 1.0
	v_fmac_f32_e32 v152, v168, v152
	v_mul_f32_e32 v167, v130, v151
	v_fma_f32 v182, -v127, v166, v128
	v_fmac_f32_e32 v165, v181, v149
	v_fma_f32 v116, -v123, v164, v124
	v_pk_fma_f32 v[0:1], v[64:65], v[12:13], v[0:1] op_sel_hi:[1,0,1]
	v_pk_fma_f32 v[2:3], v[66:67], v[12:13], v[2:3] op_sel_hi:[1,0,1]
	v_div_fixup_f32 v12, v28, v98, v13
	v_div_fmas_f32 v13, v115, v147, v163
	s_mov_b64 vcc, s[18:19]
	v_div_scale_f32 v134, s[8:9], v4, v105, v4
	v_fma_f32 v170, -v135, v154, 1.0
	v_fmac_f32_e32 v153, v169, v153
	v_mul_f32_e32 v168, v132, v152
	v_fma_f32 v183, -v129, v167, v130
	v_fmac_f32_e32 v166, v182, v150
	v_fma_f32 v117, -v125, v165, v126
	v_pk_fma_f32 v[2:3], v[62:63], v[12:13], v[2:3] op_sel_hi:[1,0,1]
	v_pk_fma_f32 v[0:1], v[60:61], v[12:13], v[0:1] op_sel_hi:[1,0,1]
	v_div_fixup_f32 v12, v13, v99, v14
	v_div_fmas_f32 v13, v116, v148, v164
	s_mov_b64 vcc, s[16:17]
	v_div_scale_f32 v136, s[6:7], v5, v106, v5
	v_fma_f32 v171, -v137, v155, 1.0
	v_fmac_f32_e32 v154, v170, v154
	v_mul_f32_e32 v169, v134, v153
	v_fma_f32 v184, -v131, v168, v132
	v_fmac_f32_e32 v167, v183, v151
	v_fma_f32 v118, -v127, v166, v128
	v_pk_fma_f32 v[0:1], v[56:57], v[12:13], v[0:1] op_sel_hi:[1,0,1]
	v_pk_fma_f32 v[2:3], v[58:59], v[12:13], v[2:3] op_sel_hi:[1,0,1]
	v_div_fixup_f32 v12, v13, v100, v15
	v_div_fmas_f32 v13, v117, v149, v165
	s_mov_b64 vcc, s[14:15]
	v_div_scale_f32 v138, s[4:5], v6, v107, v6
	v_fma_f32 v172, -v139, v156, 1.0
	v_fmac_f32_e32 v155, v171, v155
	v_mul_f32_e32 v170, v136, v154
	v_fma_f32 v185, -v133, v169, v134
	v_fmac_f32_e32 v168, v184, v152
	v_fma_f32 v119, -v129, v167, v130
	v_pk_fma_f32 v[2:3], v[54:55], v[12:13], v[2:3] op_sel_hi:[1,0,1]
	v_pk_fma_f32 v[0:1], v[52:53], v[12:13], v[0:1] op_sel_hi:[1,0,1]
	v_div_fixup_f32 v8, v13, v101, v8
	v_div_fmas_f32 v12, v118, v150, v166
	s_mov_b64 vcc, s[12:13]
	v_div_scale_f32 v140, s[0:1], v7, v108, v7
	v_fmac_f32_e32 v156, v172, v156
	v_mul_f32_e32 v171, v138, v155
	v_fma_f32 v186, -v135, v170, v136
	v_fmac_f32_e32 v169, v185, v153
	v_fma_f32 v120, -v131, v168, v132
	v_pk_fma_f32 v[0:1], v[48:49], v[8:9], v[0:1] op_sel_hi:[1,0,1]
	v_pk_fma_f32 v[2:3], v[50:51], v[8:9], v[2:3] op_sel_hi:[1,0,1]
	v_div_fixup_f32 v8, v12, v102, v9
	v_div_fmas_f32 v9, v119, v151, v167
	s_mov_b64 vcc, s[10:11]
	v_mul_f32_e32 v172, v140, v156
	v_fma_f32 v187, -v137, v171, v138
	v_fmac_f32_e32 v170, v186, v154
	v_fma_f32 v121, -v133, v169, v134
	v_pk_fma_f32 v[2:3], v[46:47], v[8:9], v[2:3] op_sel_hi:[1,0,1]
	v_pk_fma_f32 v[0:1], v[44:45], v[8:9], v[0:1] op_sel_hi:[1,0,1]
	v_div_fmas_f32 v12, v120, v152, v168
	v_div_fixup_f32 v8, v9, v103, v10
	s_mov_b64 vcc, s[8:9]
	v_fma_f32 v188, -v139, v172, v140
	v_fmac_f32_e32 v171, v187, v155
	v_fma_f32 v122, -v135, v170, v136
	v_pk_fma_f32 v[0:1], v[40:41], v[8:9], v[0:1] op_sel_hi:[1,0,1]
	v_pk_fma_f32 v[2:3], v[42:43], v[8:9], v[2:3] op_sel_hi:[1,0,1]
	v_div_fixup_f32 v8, v12, v104, v11
	v_div_fmas_f32 v9, v121, v153, v169
	s_mov_b64 vcc, s[6:7]
	v_fmac_f32_e32 v172, v188, v156
	v_fma_f32 v123, -v137, v171, v138
	v_pk_fma_f32 v[2:3], v[34:35], v[8:9], v[2:3] op_sel_hi:[1,0,1]
	v_pk_fma_f32 v[0:1], v[32:33], v[8:9], v[0:1] op_sel_hi:[1,0,1]
	v_div_fixup_f32 v4, v9, v105, v4
	v_div_fmas_f32 v8, v122, v154, v170
	s_mov_b64 vcc, s[4:5]
	v_fma_f32 v124, -v139, v172, v140
	v_pk_fma_f32 v[0:1], v[24:25], v[4:5], v[0:1] op_sel_hi:[1,0,1]
	v_pk_fma_f32 v[2:3], v[26:27], v[4:5], v[2:3] op_sel_hi:[1,0,1]
	v_div_fixup_f32 v4, v8, v106, v5
	v_div_fmas_f32 v5, v123, v155, v171
	s_mov_b64 vcc, s[0:1]
	v_pk_fma_f32 v[2:3], v[22:23], v[4:5], v[2:3] op_sel_hi:[1,0,1]
	v_pk_fma_f32 v[0:1], v[20:21], v[4:5], v[0:1] op_sel_hi:[1,0,1]
	v_div_fixup_f32 v4, v5, v107, v6
	v_div_fmas_f32 v5, v124, v156, v172
	v_pk_fma_f32 v[0:1], v[16:17], v[4:5], v[0:1] op_sel_hi:[1,0,1]
	v_pk_fma_f32 v[2:3], v[18:19], v[4:5], v[2:3] op_sel_hi:[1,0,1]
	v_div_fixup_f32 v4, v5, v108, v7
	v_pk_fma_f32 v[2:3], v[38:39], v[4:5], v[2:3] op_sel_hi:[1,0,1]
	v_pk_fma_f32 v[0:1], v[36:37], v[4:5], v[0:1] op_sel_hi:[1,0,1]
	s_cbranch_scc0 .LBB0_110
	v_mov_b32_e32 v4, s59
	ds_read_b64 v[4:5], v4
	s_mul_hi_i32 s1, s60, 0x12000
	s_mul_i32 s60, s60, 0x12000
	s_waitcnt lgkmcnt(0)
	v_readfirstlane_b32 s0, v4
	v_readfirstlane_b32 s4, v5
	s_add_u32 s0, s0, s60
	s_addc_u32 s1, s4, s1
	v_lshl_add_u64 v[4:5], v[84:85], 2, s[0:1]
	v_add_co_u32_e32 v4, vcc, 0x100000, v4
	s_add_i32 s3, s3, s40
	s_nop 0
	v_addc_co_u32_e32 v5, vcc, 0, v5, vcc
	s_cmpk_gt_i32 s3, 0x8ff
	global_store_dwordx4 v[4:5], v[0:3], off
	s_cbranch_scc0 .LBB0_109

; #define LAS __attribute__((address_space(3)))
; #define LDS_WAIT() asm volatile("s_waitcnt lgkmcnt(0)" ::: "memory")
; __device__ __forceinline__ void tr_load(const TrItem& t, int lane, f32x4 (&r)[8]) {
;     const int nblk = t.N / 32, kb = t.item / nblk, nb = t.item % nblk;
;     const float* p = t.W + (size_t)(64 * kb + (lane >> 3)) * t.N + 32 * nb + (lane & 7) * 4;
; #pragma unroll
;     for (int i = 0; i < 8; ++i) r[i] = *(const f32x4*)(p + (size_t)(8 * i) * t.N);
; }
; __device__ __forceinline__ void tr_store(const TrItem& t, int lane, const f32x4 (&r)[8], LAS float* scr) {
;     const int nblk = t.N / 32, kb = t.item / nblk, nb = t.item % nblk, k0 = 64 * kb, n0 = 32 * nb;
; #pragma unroll
;     for (int i = 0; i < 8; ++i) { LAS float* d = scr + (8 * i + (lane >> 3)) * 33 + (lane & 7) * 4; d[0] = r[i].x; d[1] = r[i].y; d[2] = r[i].z; d[3] = r[i].w; }
;     LDS_WAIT(); asm volatile("" ::: "memory");
;     const int c = lane & 7;
; #pragma unroll
;     for (int j = 0; j < 4; ++j) { const int n = (lane >> 3) + 8 * j; const LAS float* s = scr + (8 * c) * 33 + n;
.LBB0_152:
	s_lshl_b32 s8, s93, 14
	s_add_i32 s11, s8, 0
	s_add_u32 s8, s7, s4
	s_addc_u32 s9, s10, s5
	s_lshr_b32 s4, s6, 5
	s_waitcnt lgkmcnt(0)
	v_cvt_f32_u32_e32 v0, s4
	s_sub_i32 s12, 0, s4
	s_abs_i32 s10, s3
	s_ashr_i32 s5, s3, 31
	v_rcp_iflag_f32_e32 v0, v0
	v_ashrrev_i32_e32 v76, 3, v88
	s_mov_b32 s7, 0
	v_mov_b32_e32 v65, 0
	v_mul_f32_e32 v0, 0x4f7ffffe, v0
	v_cvt_u32_f32_e32 v0, v0
	v_add_u32_e32 v77, 8, v76
	v_add_u32_e32 v78, 16, v76
	v_add_u32_e32 v79, 24, v76
	v_readfirstlane_b32 s13, v0
	s_mul_i32 s12, s12, s13
	s_mul_hi_u32 s12, s13, s12
	s_add_i32 s13, s13, s12
	s_mul_hi_u32 s12, s10, s13
	s_mul_i32 s13, s12, s4
	s_sub_i32 s10, s10, s13
	s_add_i32 s14, s12, 1
	s_sub_i32 s13, s10, s4
	s_cmp_ge_u32 s10, s4
	s_cselect_b32 s12, s14, s12
	s_cselect_b32 s10, s13, s10
	s_add_i32 s13, s12, 1
	s_cmp_ge_u32 s10, s4
	s_cselect_b32 s10, s13, s12
	s_xor_b32 s10, s10, s5
	s_sub_i32 s5, s10, s5
	s_mul_i32 s4, s5, s4
	v_lshl_add_u32 v0, s5, 6, v76
	s_sub_i32 s10, s3, s4
	v_ashrrev_i32_e32 v3, 31, v0
	v_mad_u64_u32 v[0:1], s[4:5], v0, s6, 0
	v_mov_b32_e32 v2, v1
	v_mad_u64_u32 v[2:3], s[4:5], v3, s6, v[2:3]
	v_mov_b32_e32 v1, v2
	v_lshl_add_u64 v[0:1], v[0:1], 2, s[0:1]
	s_lshl_b32 s0, s10, 5
	v_lshlrev_b32_e32 v2, 2, v88
	s_ashr_i32 s1, s0, 31
	v_and_b32_e32 v32, 28, v2
	v_lshl_add_u64 v[0:1], s[0:1], 2, v[0:1]
	v_lshlrev_b32_e32 v64, 2, v32
	v_lshl_add_u64 v[8:9], v[0:1], 0, v[64:65]
	s_lshl_b64 s[0:1], s[6:7], 5
	v_lshl_add_u64 v[10:11], v[8:9], 0, s[0:1]
	v_lshl_add_u64 v[16:17], v[10:11], 0, s[0:1]
	v_lshl_add_u64 v[18:19], v[16:17], 0, s[0:1]
	v_lshl_add_u64 v[24:25], v[18:19], 0, s[0:1]
	v_lshl_add_u64 v[26:27], v[24:25], 0, s[0:1]
	v_lshl_add_u64 v[34:35], v[26:27], 0, s[0:1]
	global_load_dwordx4 v[0:3], v[8:9], off nt
	global_load_dwordx4 v[4:7], v[10:11], off nt
	s_nop 0
	global_load_dwordx4 v[8:11], v[16:17], off nt
	global_load_dwordx4 v[12:15], v[18:19], off nt
	s_nop 0
	global_load_dwordx4 v[16:19], v[24:25], off nt
	global_load_dwordx4 v[20:23], v[26:27], off nt
	v_lshl_add_u64 v[36:37], v[34:35], 0, s[0:1]
	global_load_dwordx4 v[24:27], v[34:35], off nt
	global_load_dwordx4 v[28:31], v[36:37], off nt
	v_lshlrev_b32_e32 v34, 3, v88
	s_movk_i32 s0, 0x84
	v_and_b32_e32 v34, 56, v34
	v_add_u32_e32 v33, s11, v64
	v_mul_lo_u32 v35, v76, s0
	v_mul_u32_u24_e32 v36, 0x84, v34
	v_lshlrev_b32_e32 v37, 2, v76
	v_add3_u32 v80, s11, v36, v37
	v_and_b32_e32 v81, 31, v76
	v_and_b32_e32 v82, 31, v77
	v_and_b32_e32 v83, 31, v78
	v_and_b32_e32 v84, 31, v79
	s_add_i32 s22, 0, 0x20118
	s_add_i32 s23, 0, 0x20108
	s_add_i32 s24, 0, 0x20100
	s_add_i32 s25, 0, 0x200f8
	s_add_i32 s26, 0, 0x200e8
	s_add_i32 s27, 0, 0x200d0
	s_add_i32 s28, 0, 0x20050
	s_add_i32 s29, 0, 0x20040
	s_add_i32 s30, 0, 0x20038
	s_add_i32 s31, 0, 0x20030
	v_lshlrev_b32_e32 v66, 2, v32
	v_add_u32_e32 v85, v33, v35
	s_movk_i32 s36, 0xff00
	s_movk_i32 s37, 0x800
	s_movk_i32 s38, 0x7fff
	s_mov_b32 s39, 0xffff0000
	v_lshlrev_b32_e32 v64, 1, v34
	s_mov_b32 s40, s6
	s_mov_b32 s41, s72
	s_branch .LBB0_154

; __device__ __forceinline__ void tr_load(const TrItem& t, int lane, f32x4 (&r)[8]) {
;     const int nblk = t.N / 32, kb = t.item / nblk, nb = t.item % nblk;
;     const float* p = t.W + (size_t)(64 * kb + (lane >> 3)) * t.N + 32 * nb + (lane & 7) * 4;
; #pragma unroll
;     for (int i = 0; i < 8; ++i) r[i] = *(const f32x4*)(p + (size_t)(8 * i) * t.N);
.LBB0_188:
	s_add_u32 s14, s16, s4
	s_addc_u32 s15, s17, s5
	s_lshr_b32 s4, s6, 5
	s_waitcnt lgkmcnt(0)
	v_cvt_f32_u32_e32 v32, s4
	s_sub_i32 s17, 0, s4
	s_abs_i32 s16, s43
	s_ashr_i32 s5, s43, 31
	v_rcp_iflag_f32_e32 v32, v32
	v_mov_b32_e32 v67, v65
	v_mul_f32_e32 v32, 0x4f7ffffe, v32
	v_cvt_u32_f32_e32 v32, v32
	s_nop 0
	v_readfirstlane_b32 s18, v32
	s_mul_i32 s17, s17, s18
	s_mul_hi_u32 s17, s18, s17
	s_add_i32 s18, s18, s17
	s_mul_hi_u32 s17, s16, s18
	s_mul_i32 s18, s17, s4
	s_sub_i32 s16, s16, s18
	s_add_i32 s19, s17, 1
	s_sub_i32 s18, s16, s4
	s_cmp_ge_u32 s16, s4
	s_cselect_b32 s17, s19, s17
	s_cselect_b32 s16, s18, s16
	s_add_i32 s18, s17, 1
	s_cmp_ge_u32 s16, s4
	s_cselect_b32 s16, s18, s17
	s_xor_b32 s16, s16, s5
	s_sub_i32 s5, s16, s5
	s_mul_i32 s4, s5, s4
	v_lshl_add_u32 v32, s5, 6, v76
	s_sub_i32 s16, s43, s4
	v_ashrrev_i32_e32 v35, 31, v32
	v_mad_u64_u32 v[32:33], s[4:5], v32, s6, 0
	v_mov_b32_e32 v34, v33
	v_mad_u64_u32 v[34:35], s[4:5], v35, s6, v[34:35]
	v_mov_b32_e32 v33, v34
	v_lshl_add_u64 v[32:33], v[32:33], 2, s[0:1]
	s_lshl_b32 s0, s16, 5
	s_ashr_i32 s1, s0, 31
	v_lshl_add_u64 v[32:33], s[0:1], 2, v[32:33]
	v_lshl_add_u64 v[40:41], v[32:33], 0, v[66:67]
	s_lshl_b64 s[0:1], s[6:7], 5
	v_lshl_add_u64 v[42:43], v[40:41], 0, s[0:1]
	v_lshl_add_u64 v[48:49], v[42:43], 0, s[0:1]
	v_lshl_add_u64 v[50:51], v[48:49], 0, s[0:1]
	v_lshl_add_u64 v[56:57], v[50:51], 0, s[0:1]
	v_lshl_add_u64 v[58:59], v[56:57], 0, s[0:1]
	v_lshl_add_u64 v[68:69], v[58:59], 0, s[0:1]
	global_load_dwordx4 v[32:35], v[40:41], off nt
	global_load_dwordx4 v[36:39], v[42:43], off nt
	s_nop 0
	global_load_dwordx4 v[40:43], v[48:49], off nt
	global_load_dwordx4 v[44:47], v[50:51], off nt
	s_nop 0
	global_load_dwordx4 v[48:51], v[56:57], off nt
	global_load_dwordx4 v[52:55], v[58:59], off nt
	v_lshl_add_u64 v[70:71], v[68:69], 0, s[0:1]
	global_load_dwordx4 v[56:59], v[68:69], off nt
	global_load_dwordx4 v[60:63], v[70:71], off nt

; __device__ __forceinline__ void norm_mod_pass(const float* X, const float* gam, const float* sc, const float* sh, bf16* O, int gw, int NGW, int lane) {
;     f32x4 va[2][8], vb[2][8];
;     norm_load2(X, gw, gw + NGW, lane, va);
;     f32x4 gm[8], hs[8];
; #pragma unroll
;     for (int j = 0; j < 8; ++j) { const int col = 4 * (lane + 64 * j); gm[j] = *(const f32x4*)(gam + col) * (*(const f32x4*)(sc + col) + 1.0f); hs[j] = *(const f32x4*)(sh + col); }
.LBB0_321:
	s_cmp_lt_i32 s68, 3
	s_cselect_b64 s[0:1], -1, 0
	s_and_b64 s[6:7], s[0:1], s[34:35]
	s_andn2_b64 vcc, exec, s[6:7]
	s_cbranch_vccnz .LBB0_360
	s_add_i32 s0, 0, 0x20000
	v_mov_b32_e32 v0, s0
	s_add_i32 s0, 0, 0x20028
	v_mov_b32_e32 v2, s0
	s_add_i32 s0, 0, 0x20118
	v_mov_b32_e32 v4, s0
	v_mbcnt_lo_u32_b32 v160, -1, 0
	v_mbcnt_hi_u32_b32 v160, -1, v160
	ds_read_b64 v[0:1], v0
	ds_read_b64 v[2:3], v2
	ds_read_b64 v[4:5], v4
	s_cmpk_gt_i32 s72, 0x3fff
	v_ashrrev_i32_e32 v161, 31, v160
	s_waitcnt lgkmcnt(0)
	v_readfirstlane_b32 s4, v0
	v_readfirstlane_b32 s5, v1
	v_readfirstlane_b32 s8, v2
	v_readfirstlane_b32 s9, v3
	v_readfirstlane_b32 s0, v4
	v_readfirstlane_b32 s1, v5
	s_mul_i32 s3, s70, 24
	s_cbranch_scc1 .LBB0_331
	v_lshlrev_b32_e32 v96, 2, v160
	s_add_u32 s10, s0, 0x402000
	v_ashrrev_i32_e32 v97, 31, v96
	s_addc_u32 s11, s1, 0
	v_lshlrev_b64 v[0:1], 2, v[96:97]
	v_lshl_add_u64 v[4:5], s[10:11], 0, v[0:1]
	global_load_dwordx4 v[36:39], v[4:5], off nt
	v_add_u32_e32 v4, 0x100, v96
	v_ashrrev_i32_e32 v5, 31, v4
	v_lshlrev_b64 v[4:5], 2, v[4:5]
	v_lshl_add_u64 v[6:7], s[10:11], 0, v[4:5]
	global_load_dwordx4 v[40:43], v[6:7], off nt
	v_add_u32_e32 v6, 0x200, v96
	v_ashrrev_i32_e32 v7, 31, v6
	v_lshlrev_b64 v[6:7], 2, v[6:7]
	v_lshl_add_u64 v[8:9], s[10:11], 0, v[6:7]
	global_load_dwordx4 v[44:47], v[8:9], off nt
	v_add_u32_e32 v8, 0x300, v96
	v_ashrrev_i32_e32 v9, 31, v8
	v_lshlrev_b64 v[8:9], 2, v[8:9]
	v_lshl_add_u64 v[10:11], s[10:11], 0, v[8:9]
	global_load_dwordx4 v[48:51], v[10:11], off nt
	v_add_u32_e32 v10, 0x400, v96
	v_ashrrev_i32_e32 v11, 31, v10
	v_lshl_add_u64 v[2:3], s[8:9], 0, v[0:1]
	v_lshlrev_b64 v[10:11], 2, v[10:11]
	global_load_dwordx4 v[32:35], v[2:3], off nt
	v_lshl_add_u64 v[12:13], s[10:11], 0, v[10:11]
	global_load_dwordx4 v[52:55], v[12:13], off nt
	global_load_dwordx4 v[88:91], v[2:3], off offset:1024 nt
	v_add_u32_e32 v12, 0x500, v96
	v_add_u32_e32 v14, 0x600, v96
	v_ashrrev_i32_e32 v13, 31, v12
	v_add_u32_e32 v16, 0x700, v96
	v_ashrrev_i32_e32 v15, 31, v14
	v_lshlrev_b64 v[12:13], 2, v[12:13]
	v_ashrrev_i32_e32 v17, 31, v16
	v_lshlrev_b64 v[14:15], 2, v[14:15]
	v_lshl_add_u64 v[20:21], s[10:11], 0, v[12:13]
	v_lshlrev_b64 v[16:17], 2, v[16:17]
	global_load_dwordx4 v[98:101], v[2:3], off offset:2048 nt
	global_load_dwordx4 v[108:111], v[2:3], off offset:3072 nt
	v_lshl_add_u64 v[2:3], s[8:9], 0, v[10:11]
	v_lshl_add_u64 v[18:19], s[8:9], 0, v[12:13]
	v_lshl_add_u64 v[24:25], s[10:11], 0, v[14:15]
	global_load_dwordx4 v[116:119], v[20:21], off nt
	v_lshl_add_u64 v[22:23], s[8:9], 0, v[14:15]
	v_lshl_add_u64 v[26:27], s[10:11], 0, v[16:17]
	global_load_dwordx4 v[112:115], v[2:3], off nt
	global_load_dwordx4 v[120:123], v[18:19], off nt
	global_load_dwordx4 v[124:127], v[24:25], off nt
	global_load_dwordx4 v[132:135], v[26:27], off nt
	v_lshl_add_u64 v[2:3], s[8:9], 0, v[16:17]
	global_load_dwordx4 v[128:131], v[22:23], off nt
	global_load_dwordx4 v[136:139], v[2:3], off nt
	s_add_u32 s12, s0, 0x400000
	s_addc_u32 s13, s1, 0
	s_add_i32 s8, s80, s72
	s_cmpk_lt_i32 s8, 0x4000
	s_cselect_b32 s8, s8, 0
	s_ashr_i32 s9, s8, 31
	s_lshl_b64 s[8:9], s[8:9], 13
	s_add_u32 s8, s4, s8
	v_lshlrev_b64 v[102:103], 4, v[160:161]
	v_lshl_add_u64 v[56:57], s[12:13], 0, v[0:1]
	v_lshl_add_u64 v[60:61], s[12:13], 0, v[6:7]
	s_addc_u32 s9, s5, s9
	s_ashr_i32 s73, s72, 31
	v_lshl_add_u64 v[58:59], s[12:13], 0, v[4:5]
	v_lshl_add_u64 v[62:63], s[12:13], 0, v[8:9]
	v_lshl_add_u64 v[64:65], s[12:13], 0, v[10:11]
	v_lshl_add_u64 v[66:67], s[12:13], 0, v[12:13]
	v_lshl_add_u64 v[68:69], s[12:13], 0, v[14:15]
	v_lshl_add_u64 v[70:71], s[12:13], 0, v[16:17]
	global_load_dwordx4 v[0:3], v[56:57], off nt
	global_load_dwordx4 v[4:7], v[58:59], off nt
	global_load_dwordx4 v[8:11], v[60:61], off nt
	global_load_dwordx4 v[12:15], v[62:63], off nt
	global_load_dwordx4 v[16:19], v[64:65], off nt
	global_load_dwordx4 v[20:23], v[66:67], off nt
	global_load_dwordx4 v[24:27], v[68:69], off nt
	global_load_dwordx4 v[28:31], v[70:71], off nt
	v_lshl_add_u64 v[60:61], s[8:9], 0, v[102:103]
	s_lshl_b64 s[8:9], s[72:73], 13
	s_movk_i32 s22, 0x1000
	s_add_u32 s8, s4, s8
	s_addc_u32 s9, s5, s9
	v_lshlrev_b64 v[196:197], 1, v[96:97]
	v_lshl_add_u64 v[194:195], s[4:5], 0, v[102:103]
	s_lshl_b32 s4, s70, 5
	s_mul_i32 s23, s70, 40
	s_lshl_b32 s26, s70, 4
	s_add_i32 s23, s23, s33
	s_add_i32 s24, s4, s33
	v_mov_b32_e32 v206, 0x358637bd
	s_waitcnt vmcnt(0) lgkmcnt(0)
; __device__ __forceinline__ void norm_load2(const float* X, int r0, int r1, int lane, f32x4 (&v)[2][8]) {
;     const f32x4* x0 = (const f32x4*)(X + (size_t)(r0 < M ? r0 : 0) * DMODEL) + lane; const f32x4* x1 = (const f32x4*)(X + (size_t)(r1 < M ? r1 : 0) * DMODEL) + lane;
; #pragma unroll
;     for (int j = 0; j < 8; ++j) { v[0][j] = x0[64 * j]; v[1][j] = x1[64 * j]; }
; }
; __device__ __forceinline__ void norm_mod_pass(const float* X, const float* gam, const float* sc, const float* sh, bf16* O, int gw, int NGW, int lane) {
;     ...
;     norm_load2(X, gw, gw + NGW, lane, va);
;     f32x4 gm[8], hs[8];
; #pragma unroll
;     for (int j = 0; j < 8; ++j) { const int col = 4 * (lane + 64 * j); gm[j] = *(const f32x4*)(gam + col) * (*(const f32x4*)(sc + col) + 1.0f); hs[j] = *(const f32x4*)(sh + col); }
;     for (int row = gw; row < M; row += 4 * NGW) {
;         norm_load2(X, row + 2 * NGW, row + 3 * NGW, lane, vb);
	v_pk_add_f32 v[36:37], v[36:37], 1.0 op_sel_hi:[1,0]
	v_pk_add_f32 v[38:39], v[38:39], 1.0 op_sel_hi:[1,0]
	s_mov_b32 s27, 0xf800000
	v_mov_b32_e32 v207, 0x260
	s_movk_i32 s28, 0x7fff
	v_pk_add_f32 v[140:141], v[40:41], 1.0 op_sel_hi:[1,0]
	s_mov_b32 s29, 0xffff0000
	s_mov_b32 s30, 0xc600000
	s_mov_b32 s31, s93
	v_pk_add_f32 v[142:143], v[46:47], 1.0 op_sel_hi:[1,0]
	v_pk_add_f32 v[144:145], v[44:45], 1.0 op_sel_hi:[1,0]
	v_pk_add_f32 v[148:149], v[48:49], 1.0 op_sel_hi:[1,0]
	v_add_co_u32_e32 v48, vcc, s22, v60
	v_pk_add_f32 v[146:147], v[50:51], 1.0 op_sel_hi:[1,0]
	s_nop 0
	v_addc_co_u32_e32 v49, vcc, 0, v61, vcc
	v_pk_mul_f32 v[164:165], v[32:33], v[36:37]
	v_pk_add_f32 v[32:33], v[42:43], 1.0 op_sel_hi:[1,0]
	v_pk_mul_f32 v[162:163], v[34:35], v[38:39]
	v_pk_mul_f32 v[166:167], v[90:91], v[32:33]
	v_lshl_add_u64 v[90:91], s[8:9], 0, v[102:103]
	v_add_co_u32_e32 v50, vcc, s22, v90
	v_pk_add_f32 v[150:151], v[54:55], 1.0 op_sel_hi:[1,0]
	s_nop 0
	v_addc_co_u32_e32 v51, vcc, 0, v91, vcc
	v_pk_add_f32 v[152:153], v[52:53], 1.0 op_sel_hi:[1,0]
	global_load_dwordx4 v[32:35], v[48:49], off offset:3072 nt
	global_load_dwordx4 v[36:39], v[48:49], off offset:2048 nt
	global_load_dwordx4 v[40:43], v[48:49], off offset:1024 nt
	global_load_dwordx4 v[44:47], v[48:49], off nt
	global_load_dwordx4 v[64:67], v[50:51], off offset:3072 nt
	global_load_dwordx4 v[68:71], v[50:51], off offset:2048 nt
	global_load_dwordx4 v[72:75], v[50:51], off offset:1024 nt
	global_load_dwordx4 v[76:79], v[50:51], off nt
	s_nop 0
	global_load_dwordx4 v[48:51], v[60:61], off offset:3072 nt
	global_load_dwordx4 v[52:55], v[60:61], off offset:2048 nt
	global_load_dwordx4 v[56:59], v[60:61], off offset:1024 nt
	s_nop 0
	global_load_dwordx4 v[60:63], v[60:61], off nt
	s_nop 0
	global_load_dwordx4 v[80:83], v[90:91], off offset:3072 nt
	global_load_dwordx4 v[84:87], v[90:91], off offset:2048 nt
	global_load_dwordx4 v[92:95], v[90:91], off offset:1024 nt
	global_load_dwordx4 v[104:107], v[90:91], off nt
	v_pk_mul_f32 v[168:169], v[88:89], v[140:141]
	s_mov_b64 s[8:9], 0xc600000
	v_pk_mul_f32 v[170:171], v[100:101], v[142:143]
	v_pk_mul_f32 v[172:173], v[98:99], v[144:145]
	v_pk_add_f32 v[88:89], v[118:119], 1.0 op_sel_hi:[1,0]
	v_pk_add_f32 v[90:91], v[116:117], 1.0 op_sel_hi:[1,0]
	v_pk_mul_f32 v[174:175], v[110:111], v[146:147]
	v_pk_mul_f32 v[176:177], v[108:109], v[148:149]
	v_pk_mul_f32 v[182:183], v[122:123], v[88:89]
	v_pk_add_f32 v[88:89], v[126:127], 1.0 op_sel_hi:[1,0]
	v_pk_mul_f32 v[184:185], v[120:121], v[90:91]
	v_pk_add_f32 v[90:91], v[124:125], 1.0 op_sel_hi:[1,0]
	v_pk_mul_f32 v[186:187], v[130:131], v[88:89]
	v_pk_add_f32 v[88:89], v[134:135], 1.0 op_sel_hi:[1,0]
	v_pk_mul_f32 v[188:189], v[128:129], v[90:91]
	v_pk_mul_f32 v[190:191], v[138:139], v[88:89]
	v_mbcnt_lo_u32_b32 v88, -1, 0
	v_mbcnt_hi_u32_b32 v88, -1, v88
	v_pk_add_f32 v[90:91], v[132:133], 1.0 op_sel_hi:[1,0]
	v_and_b32_e32 v89, 64, v88
	v_pk_mul_f32 v[192:193], v[136:137], v[90:91]
	v_add_u32_e32 v89, 64, v89
	v_xor_b32_e32 v90, 1, v88
	v_cmp_lt_i32_e32 vcc, v90, v89
	v_pk_mul_f32 v[178:179], v[114:115], v[150:151]
	v_pk_mul_f32 v[180:181], v[112:113], v[152:153]
	v_cndmask_b32_e32 v90, v88, v90, vcc
	v_lshlrev_b32_e32 v200, 2, v90
	v_xor_b32_e32 v90, 2, v88
	v_cmp_lt_i32_e32 vcc, v90, v89
	s_nop 1
	v_cndmask_b32_e32 v90, v88, v90, vcc
	v_lshlrev_b32_e32 v201, 2, v90
	v_xor_b32_e32 v90, 4, v88
	v_cmp_lt_i32_e32 vcc, v90, v89
	s_nop 1
	v_cndmask_b32_e32 v90, v88, v90, vcc
	v_lshlrev_b32_e32 v202, 2, v90
	v_xor_b32_e32 v90, 8, v88
	v_cmp_lt_i32_e32 vcc, v90, v89
	s_nop 1
	v_cndmask_b32_e32 v90, v88, v90, vcc
	v_lshlrev_b32_e32 v203, 2, v90
	v_xor_b32_e32 v90, 16, v88
	v_cmp_lt_i32_e32 vcc, v90, v89
	s_nop 1
	v_cndmask_b32_e32 v90, v88, v90, vcc
	v_lshlrev_b32_e32 v204, 2, v90
	v_xor_b32_e32 v90, 32, v88
	v_cmp_lt_i32_e32 vcc, v90, v89
	s_nop 1
	v_cndmask_b32_e32 v88, v88, v90, vcc
	v_lshlrev_b32_e32 v205, 2, v88
	v_lshl_add_u64 v[88:89], s[0:1], 0, v[196:197]
	v_lshl_add_u64 v[198:199], v[88:89], 0, s[8:9]
	s_lshl_b64 s[8:9], s[72:73], 12
	s_add_u32 s8, s0, s8
	s_addc_u32 s9, s1, s9
	s_add_i32 s12, s2, s70
	s_add_i32 s26, s26, s33
	s_lshl_b32 s25, s12, 3
	s_add_i32 s12, s26, s93
	s_ashr_i32 s5, s4, 31
	s_ashr_i32 s13, s12, 31
	s_lshl_b64 s[10:11], s[4:5], 12
	s_add_i32 s5, s3, s33
	s_lshl_b64 s[12:13], s[12:13], 12
	s_add_u32 s12, s0, s12
	s_addc_u32 s13, s1, s13
	s_branch .LBB0_325

; __device__ __forceinline__ unsigned pk2(float lo, float hi) { return f2bf(lo) | (f2bf(hi) << 16); }
; __device__ __forceinline__ void norm_store2(bf16* O, int r0, int r1, int lane, const f32x4 (&v)[2][8], const f32x4 (&gm)[8], const f32x4 (&hs)[8]) {
; #pragma unroll
;     for (int q = 0; q < 2; ++q) { const int r = q == 0 ? r0 : r1; float s = 0.f;
; #pragma unroll
;         for (int j = 0; j < 8; ++j) s += (v[q][j].x * v[q][j].x + v[q][j].y * v[q][j].y) + (v[q][j].z * v[q][j].z + v[q][j].w * v[q][j].w);
;         const float rstd = 1.0f / sqrtf(wave_sum(s) * (1.0f / DMODEL) + 1e-6f);
;         if (r < M) { bf16* orow = O + (size_t)r * DMODEL;
; #pragma unroll
;             for (int j = 0; j < 8; ++j) { const f32x4 y = (v[q][j] * rstd) * gm[j] + hs[j]; v2u o; o.x = pk2(y.x, y.y); o.y = pk2(y.z, y.w); *(v2u*)(orow + 4 * (lane + 64 * j)) = o; } } }
; __device__ __forceinline__ void norm_mod_pass(const float* X, const float* gam, const float* sc, const float* sh, bf16* O, int gw, int NGW, int lane) {
;     ...
;     for (int row = gw; row < M; row += 4 * NGW) {
;         norm_load2(X, row + 2 * NGW, row + 3 * NGW, lane, vb);
;         norm_store2(O, row, row + NGW, lane, va, gm, hs);
.LBB0_325:
	s_waitcnt vmcnt(0) lgkmcnt(0)
	v_mov_b32_e32 v90, v93
	v_mov_b32_e32 v91, v105
	v_mov_b32_e32 v88, v92
	v_mov_b32_e32 v89, v104
	v_pk_mul_f32 v[90:91], v[90:91], v[90:91]
	v_mov_b32_e32 v96, v95
	v_mov_b32_e32 v97, v107
	v_pk_fma_f32 v[88:89], v[88:89], v[88:89], v[90:91]
	v_mov_b32_e32 v90, v94
	v_mov_b32_e32 v91, v106
	v_pk_mul_f32 v[96:97], v[96:97], v[96:97]
	s_add_i32 s15, s26, s31
	v_pk_fma_f32 v[90:91], v[90:91], v[90:91], v[96:97]
	v_pk_mul_f32 v[96:97], v[84:85], v[84:85]
	v_pk_add_f32 v[88:89], v[88:89], v[90:91]
	v_pk_mul_f32 v[90:91], v[86:87], v[86:87]
	v_pk_add_f32 v[88:89], v[88:89], v[88:89] op_sel_hi:[0,1]
	v_pk_mov_b32 v[98:99], v[96:97], v[90:91] op_sel:[1,0]
	v_mov_b32_e32 v97, v91
	v_mul_f32_e32 v88, v80, v80
	v_pk_add_f32 v[90:91], v[98:99], v[96:97]
	v_pk_fma_f32 v[96:97], v[80:81], v[80:81], v[88:89] op_sel_hi:[1,1,0]
	v_mul_f32_e32 v88, v82, v82
	v_pk_add_f32 v[90:91], v[90:91], v[90:91] op_sel_hi:[0,1]
	v_pk_fma_f32 v[98:99], v[82:83], v[82:83], v[88:89] op_sel_hi:[1,1,0]
	v_mul_f32_e32 v96, v76, v76
	v_mul_f32_e32 v98, v77, v77
	v_mul_f32_e32 v90, v78, v78
	v_mul_f32_e32 v88, v79, v79
	v_pk_add_f32 v[96:97], v[96:97], v[98:99]
	v_pk_add_f32 v[88:89], v[90:91], v[88:89]
	v_pk_mul_f32 v[90:91], v[74:75], v[74:75]
	v_pk_add_f32 v[88:89], v[96:97], v[88:89]
	v_pk_mul_f32 v[96:97], v[72:73], v[72:73]
	v_pk_add_f32 v[88:89], v[88:89], v[88:89] op_sel_hi:[0,1]
	v_pk_mov_b32 v[98:99], v[96:97], v[90:91] op_sel:[1,0]
	v_mov_b32_e32 v97, v91
	v_mul_f32_e32 v88, v68, v68
	v_pk_add_f32 v[90:91], v[98:99], v[96:97]
	v_pk_fma_f32 v[96:97], v[68:69], v[68:69], v[88:89] op_sel_hi:[1,1,0]
	v_mul_f32_e32 v88, v70, v70
	v_pk_add_f32 v[90:91], v[90:91], v[90:91] op_sel_hi:[0,1]
	v_pk_fma_f32 v[98:99], v[70:71], v[70:71], v[88:89] op_sel_hi:[1,1,0]
	v_mul_f32_e32 v96, v64, v64
	v_mul_f32_e32 v98, v65, v65
	v_mul_f32_e32 v90, v66, v66
	v_mul_f32_e32 v88, v67, v67
	v_pk_add_f32 v[96:97], v[96:97], v[98:99]
	v_pk_add_f32 v[88:89], v[90:91], v[88:89]
	s_add_i32 s14, s5, s31
	v_pk_add_f32 v[88:89], v[96:97], v[88:89]
	s_cmpk_lt_i32 s15, 0x4000
	v_add_f32_e32 v88, v88, v89
	ds_bpermute_b32 v89, v200, v88
	s_cselect_b64 s[18:19], -1, 0
	s_and_b64 s[0:1], s[18:19], exec
	s_cselect_b32 s0, s15, 0
	s_ashr_i32 s1, s0, 31
	s_waitcnt lgkmcnt(0)
	v_add_f32_e32 v88, v88, v89
	ds_bpermute_b32 v89, v201, v88
	s_lshl_b64 s[0:1], s[0:1], 13
	s_cmpk_lt_i32 s14, 0x4000
	s_cselect_b64 s[16:17], -1, 0
	s_waitcnt lgkmcnt(0)
	v_add_f32_e32 v88, v88, v89
	ds_bpermute_b32 v89, v202, v88
	s_waitcnt lgkmcnt(0)
	v_add_f32_e32 v88, v88, v89
	ds_bpermute_b32 v89, v203, v88
	s_waitcnt lgkmcnt(0)
	v_add_f32_e32 v88, v88, v89
	ds_bpermute_b32 v89, v204, v88
	s_waitcnt lgkmcnt(0)
	v_add_f32_e32 v90, v88, v89
	ds_bpermute_b32 v91, v205, v90
	v_lshl_add_u64 v[88:89], v[194:195], 0, s[0:1]
	s_and_b64 s[0:1], s[16:17], exec
	s_cselect_b32 s20, s14, 0
	s_ashr_i32 s21, s20, 31
	s_waitcnt lgkmcnt(0)
	v_add_f32_e32 v90, v90, v91
	v_fmamk_f32 v90, v90, 0x3a000000, v206
	v_mul_f32_e32 v91, 0x4f800000, v90
	v_cmp_gt_f32_e32 vcc, s27, v90
	global_load_dwordx4 v[132:135], v[88:89], off nt
	global_load_dwordx4 v[128:131], v[88:89], off offset:1024 nt
	v_cndmask_b32_e32 v90, v90, v91, vcc
	v_sqrt_f32_e32 v91, v90
	s_nop 0
	v_add_u32_e32 v96, -1, v91
	v_fma_f32 v97, -v96, v91, v90
	v_cmp_ge_f32_e64 s[0:1], 0, v97
	v_add_u32_e32 v97, 1, v91
	s_nop 0
	v_cndmask_b32_e64 v96, v91, v96, s[0:1]
	v_fma_f32 v91, -v97, v91, v90
	v_cmp_lt_f32_e64 s[0:1], 0, v91
	s_nop 1
	v_cndmask_b32_e64 v91, v96, v97, s[0:1]
	v_mul_f32_e32 v96, 0x37800000, v91
	v_cndmask_b32_e32 v91, v91, v96, vcc
	v_cmp_class_f32_e32 vcc, v90, v207
	s_nop 1
	v_cndmask_b32_e32 v96, v91, v90, vcc
	v_div_scale_f32 v97, s[0:1], v96, v96, 1.0
	v_rcp_f32_e32 v98, v97
	s_lshl_b64 s[0:1], s[20:21], 13
	v_lshl_add_u64 v[90:91], v[194:195], 0, s[0:1]
	s_add_i32 s20, s25, s31
	v_fma_f32 v99, -v97, v98, 1.0
	v_fmac_f32_e32 v98, v99, v98
	v_div_scale_f32 v99, vcc, 1.0, v96, 1.0
	v_mul_f32_e32 v100, v99, v98
	v_fma_f32 v101, -v97, v100, v99
	v_fmac_f32_e32 v100, v101, v98
	v_fma_f32 v97, -v97, v100, v99
	v_div_fmas_f32 v97, v97, v98, v100
	v_div_fixup_f32 v96, v97, v96, 1.0
	v_pk_mul_f32 v[98:99], v[104:105], v[96:97] op_sel_hi:[1,0]
	v_pk_mul_f32 v[100:101], v[106:107], v[96:97] op_sel_hi:[1,0]
	v_pk_fma_f32 v[98:99], v[164:165], v[98:99], v[0:1]
	v_pk_fma_f32 v[100:101], v[162:163], v[100:101], v[2:3]
	v_bfe_u32 v97, v98, 16, 1
	v_add3_u32 v97, v98, v97, s28
	v_bfe_u32 v98, v99, 16, 1
	v_add3_u32 v102, v99, v98, s28
	v_bfe_u32 v98, v100, 16, 1
	v_add3_u32 v100, v100, v98, s28
	v_bfe_u32 v98, v101, 16, 1
	v_lshrrev_b32_e32 v97, 16, v97
	v_add3_u32 v101, v101, v98, s28
	v_add_co_u32_e32 v98, vcc, s22, v88
	v_and_or_b32 v104, v102, s29, v97
	v_lshrrev_b32_e32 v97, 16, v100
	v_addc_co_u32_e32 v99, vcc, 0, v89, vcc
	v_and_or_b32 v105, v101, s29, v97
	v_pk_mul_f32 v[92:93], v[92:93], v[96:97] op_sel_hi:[1,0]
	v_pk_mul_f32 v[94:95], v[94:95], v[96:97] op_sel_hi:[1,0]
	v_pk_mul_f32 v[84:85], v[84:85], v[96:97] op_sel_hi:[1,0]
	v_pk_mul_f32 v[86:87], v[86:87], v[96:97] op_sel_hi:[1,0]
	v_pk_mul_f32 v[80:81], v[80:81], v[96:97] op_sel_hi:[1,0]
	v_pk_mul_f32 v[82:83], v[82:83], v[96:97] op_sel_hi:[1,0]
	v_pk_mul_f32 v[76:77], v[76:77], v[96:97] op_sel_hi:[1,0]
	v_pk_mul_f32 v[78:79], v[78:79], v[96:97] op_sel_hi:[1,0]
	v_pk_mul_f32 v[72:73], v[72:73], v[96:97] op_sel_hi:[1,0]
	v_pk_mul_f32 v[74:75], v[74:75], v[96:97] op_sel_hi:[1,0]
	v_pk_mul_f32 v[68:69], v[68:69], v[96:97] op_sel_hi:[1,0]
	v_pk_mul_f32 v[70:71], v[70:71], v[96:97] op_sel_hi:[1,0]
	v_pk_mul_f32 v[64:65], v[64:65], v[96:97] op_sel_hi:[1,0]
; __device__ __forceinline__ unsigned pk2(float lo, float hi) { return f2bf(lo) | (f2bf(hi) << 16); }
; __device__ __forceinline__ void norm_load2(const float* X, int r0, int r1, int lane, f32x4 (&v)[2][8]) {
;     const f32x4* x0 = (const f32x4*)(X + (size_t)(r0 < M ? r0 : 0) * DMODEL) + lane; const f32x4* x1 = (const f32x4*)(X + (size_t)(r1 < M ? r1 : 0) * DMODEL) + lane;
; #pragma unroll
;     for (int j = 0; j < 8; ++j) { v[0][j] = x0[64 * j]; v[1][j] = x1[64 * j]; }
; }
; __device__ __forceinline__ void norm_store2(bf16* O, int r0, int r1, int lane, const f32x4 (&v)[2][8], const f32x4 (&gm)[8], const f32x4 (&hs)[8]) {
; #pragma unroll
;     for (int q = 0; q < 2; ++q) { const int r = q == 0 ? r0 : r1; float s = 0.f;
; #pragma unroll
;         for (int j = 0; j < 8; ++j) s += (v[q][j].x * v[q][j].x + v[q][j].y * v[q][j].y) + (v[q][j].z * v[q][j].z + v[q][j].w * v[q][j].w);
;         const float rstd = 1.0f / sqrtf(wave_sum(s) * (1.0f / DMODEL) + 1e-6f);
;         if (r < M) { bf16* orow = O + (size_t)r * DMODEL;
; #pragma unroll
;             for (int j = 0; j < 8; ++j) { const f32x4 y = (v[q][j] * rstd) * gm[j] + hs[j]; v2u o; o.x = pk2(y.x, y.y); o.y = pk2(y.z, y.w); *(v2u*)(orow + 4 * (lane + 64 * j)) = o; } } }
	v_pk_mul_f32 v[66:67], v[66:67], v[96:97] op_sel_hi:[1,0]
	v_lshl_add_u64 v[96:97], s[8:9], 0, v[196:197]
	v_add_co_u32_e32 v106, vcc, s30, v96
	v_pk_fma_f32 v[92:93], v[168:169], v[92:93], v[4:5]
	s_nop 0
	v_addc_co_u32_e32 v107, vcc, 0, v97, vcc
	v_add_co_u32_e32 v208, vcc, s22, v90
	v_pk_fma_f32 v[84:85], v[172:173], v[84:85], v[8:9]
	s_nop 0
	v_addc_co_u32_e32 v209, vcc, 0, v91, vcc
	global_load_dwordx4 v[156:159], v[88:89], off offset:2048 nt
	global_load_dwordx4 v[152:155], v[88:89], off offset:3072 nt
	global_load_dwordx4 v[124:127], v[90:91], off nt
	global_load_dwordx4 v[120:123], v[90:91], off offset:1024 nt
	global_load_dwordx4 v[116:119], v[90:91], off offset:2048 nt
	global_load_dwordx4 v[112:115], v[90:91], off offset:3072 nt
	global_load_dwordx4 v[148:151], v[98:99], off nt
	global_load_dwordx4 v[144:147], v[98:99], off offset:1024 nt
	global_load_dwordx4 v[140:143], v[98:99], off offset:2048 nt
	global_load_dwordx4 v[136:139], v[98:99], off offset:3072 nt
	global_load_dwordx4 v[108:111], v[208:209], off nt
	global_load_dwordx4 v[100:103], v[208:209], off offset:1024 nt
	s_nop 0
	global_load_dwordx4 v[96:99], v[208:209], off offset:2048 nt
	global_load_dwordx4 v[88:91], v[208:209], off offset:3072 nt
	v_pk_fma_f32 v[80:81], v[176:177], v[80:81], v[12:13]
	global_store_dwordx2 v[106:107], v[104:105], off
	v_bfe_u32 v104, v92, 16, 1
	v_add3_u32 v104, v92, v104, s28
	v_bfe_u32 v92, v93, 16, 1
	v_add3_u32 v105, v93, v92, s28
	v_pk_fma_f32 v[92:93], v[166:167], v[94:95], v[6:7]
	v_pk_fma_f32 v[76:77], v[180:181], v[76:77], v[16:17]
	v_bfe_u32 v94, v92, 16, 1
	v_add3_u32 v94, v92, v94, s28
	v_bfe_u32 v92, v93, 16, 1
	v_add3_u32 v93, v93, v92, s28
	v_lshrrev_b32_e32 v92, 16, v104
	v_lshrrev_b32_e32 v94, 16, v94
	v_and_or_b32 v92, v105, s29, v92
	v_and_or_b32 v93, v93, s29, v94
	global_store_dwordx2 v[106:107], v[92:93], off offset:512
	v_bfe_u32 v92, v84, 16, 1
	v_add3_u32 v92, v84, v92, s28
	v_bfe_u32 v84, v85, 16, 1
	v_add3_u32 v93, v85, v84, s28
	v_pk_fma_f32 v[84:85], v[170:171], v[86:87], v[10:11]
	v_pk_fma_f32 v[72:73], v[184:185], v[72:73], v[20:21]
	v_bfe_u32 v86, v84, 16, 1
	v_add3_u32 v86, v84, v86, s28
	v_bfe_u32 v84, v85, 16, 1
	v_add3_u32 v85, v85, v84, s28
	v_lshrrev_b32_e32 v84, 16, v92
	v_lshrrev_b32_e32 v86, 16, v86
	v_and_or_b32 v84, v93, s29, v84
	v_and_or_b32 v85, v85, s29, v86
	global_store_dwordx2 v[106:107], v[84:85], off offset:1024
	v_bfe_u32 v84, v80, 16, 1
	v_add3_u32 v84, v80, v84, s28
	v_bfe_u32 v80, v81, 16, 1
	v_add3_u32 v85, v81, v80, s28
	v_pk_fma_f32 v[80:81], v[174:175], v[82:83], v[14:15]
	v_pk_fma_f32 v[68:69], v[188:189], v[68:69], v[24:25]
	v_bfe_u32 v82, v80, 16, 1
	v_add3_u32 v82, v80, v82, s28
	v_bfe_u32 v80, v81, 16, 1
	v_add3_u32 v81, v81, v80, s28
	v_lshrrev_b32_e32 v80, 16, v84
	v_lshrrev_b32_e32 v82, 16, v82
	v_and_or_b32 v80, v85, s29, v80
	v_and_or_b32 v81, v81, s29, v82
	global_store_dwordx2 v[106:107], v[80:81], off offset:1536
	v_bfe_u32 v80, v76, 16, 1
	v_add3_u32 v80, v76, v80, s28
	v_bfe_u32 v76, v77, 16, 1
	v_add3_u32 v81, v77, v76, s28
	v_pk_fma_f32 v[76:77], v[178:179], v[78:79], v[18:19]
	v_pk_fma_f32 v[64:65], v[192:193], v[64:65], v[28:29]
	v_bfe_u32 v78, v76, 16, 1
	v_add3_u32 v78, v76, v78, s28
	v_bfe_u32 v76, v77, 16, 1
	v_add3_u32 v77, v77, v76, s28
	v_lshrrev_b32_e32 v76, 16, v80
	v_lshrrev_b32_e32 v78, 16, v78
	v_and_or_b32 v76, v81, s29, v76
	v_and_or_b32 v77, v77, s29, v78
	global_store_dwordx2 v[106:107], v[76:77], off offset:2048
	v_bfe_u32 v76, v72, 16, 1
	v_add3_u32 v76, v72, v76, s28
	v_bfe_u32 v72, v73, 16, 1
	v_add3_u32 v77, v73, v72, s28
	v_pk_fma_f32 v[72:73], v[182:183], v[74:75], v[22:23]
	s_cmpk_gt_i32 s20, 0x3fff
	v_bfe_u32 v74, v72, 16, 1
	v_add3_u32 v74, v72, v74, s28
	v_bfe_u32 v72, v73, 16, 1
	v_add3_u32 v73, v73, v72, s28
	v_lshrrev_b32_e32 v72, 16, v76
	v_lshrrev_b32_e32 v74, 16, v74
	v_and_or_b32 v72, v77, s29, v72
	v_and_or_b32 v73, v73, s29, v74
	global_store_dwordx2 v[106:107], v[72:73], off offset:2560
	v_bfe_u32 v72, v68, 16, 1
	v_add3_u32 v72, v68, v72, s28
	v_bfe_u32 v68, v69, 16, 1
	v_add3_u32 v73, v69, v68, s28
	v_pk_fma_f32 v[68:69], v[186:187], v[70:71], v[26:27]
	v_mul_f32_e32 v71, v63, v63
	v_bfe_u32 v70, v68, 16, 1
	v_add3_u32 v70, v68, v70, s28
	v_mul_f32_e32 v68, v61, v61
	v_fmac_f32_e32 v68, v60, v60
	v_fmac_f32_e32 v71, v62, v62
	v_add_f32_e32 v68, v68, v71
	v_mul_f32_e32 v71, v57, v57
	v_mul_f32_e32 v74, v59, v59
	v_fmac_f32_e32 v71, v56, v56
	v_fmac_f32_e32 v74, v58, v58
	v_add_f32_e32 v71, v71, v74
	v_add_f32_e32 v68, v71, v68
	v_mul_f32_e32 v71, v53, v53
	v_mul_f32_e32 v74, v55, v55
	v_fmac_f32_e32 v71, v52, v52
	v_fmac_f32_e32 v74, v54, v54
	v_add_f32_e32 v71, v71, v74
	v_add_f32_e32 v68, v71, v68
	v_mul_f32_e32 v71, v49, v49
	v_mul_f32_e32 v74, v51, v51
	v_fmac_f32_e32 v71, v48, v48
	v_fmac_f32_e32 v74, v50, v50
	v_add_f32_e32 v71, v71, v74
	v_add_f32_e32 v68, v71, v68
	v_mul_f32_e32 v71, v45, v45
	v_mul_f32_e32 v74, v47, v47
	v_fmac_f32_e32 v71, v44, v44
	v_fmac_f32_e32 v74, v46, v46
	v_add_f32_e32 v71, v71, v74
	v_add_f32_e32 v68, v71, v68
	v_mul_f32_e32 v71, v41, v41
	v_mul_f32_e32 v74, v43, v43
	v_fmac_f32_e32 v71, v40, v40
	v_fmac_f32_e32 v74, v42, v42
	v_add_f32_e32 v71, v71, v74
	v_add_f32_e32 v68, v71, v68
	v_mul_f32_e32 v71, v37, v37
	v_mul_f32_e32 v74, v39, v39
	v_fmac_f32_e32 v71, v36, v36
	v_fmac_f32_e32 v74, v38, v38
	v_add_f32_e32 v71, v71, v74
	v_add_f32_e32 v68, v71, v68
	v_mul_f32_e32 v71, v33, v33
	v_mul_f32_e32 v74, v35, v35
	v_fmac_f32_e32 v71, v32, v32
	v_fmac_f32_e32 v74, v34, v34
	v_add_f32_e32 v71, v71, v74
	v_add_f32_e32 v71, v71, v68
	ds_bpermute_b32 v74, v200, v71
	v_bfe_u32 v68, v69, 16, 1
	v_add3_u32 v69, v69, v68, s28
	v_lshrrev_b32_e32 v68, 16, v72
	v_lshrrev_b32_e32 v70, 16, v70
	s_waitcnt lgkmcnt(0)
	v_add_f32_e32 v71, v71, v74
	ds_bpermute_b32 v72, v201, v71
	v_and_or_b32 v68, v73, s29, v68
	v_and_or_b32 v69, v69, s29, v70
	global_store_dwordx2 v[106:107], v[68:69], off offset:3072
	v_bfe_u32 v70, v64, 16, 1
	s_waitcnt lgkmcnt(0)
	v_add_f32_e32 v68, v71, v72
	ds_bpermute_b32 v69, v202, v68
	v_add3_u32 v70, v64, v70, s28
	v_bfe_u32 v64, v65, 16, 1
	v_add3_u32 v71, v65, v64, s28
	v_pk_fma_f32 v[64:65], v[190:191], v[66:67], v[30:31]
	s_waitcnt lgkmcnt(0)
	v_add_f32_e32 v68, v68, v69
	ds_bpermute_b32 v69, v203, v68
	v_bfe_u32 v66, v64, 16, 1
	v_add3_u32 v64, v64, v66, s28
	v_bfe_u32 v66, v65, 16, 1
	s_waitcnt lgkmcnt(0)
	v_add_f32_e32 v67, v68, v69
	ds_bpermute_b32 v68, v204, v67
	v_add3_u32 v69, v65, v66, s28
	v_lshrrev_b32_e32 v65, 16, v70
	v_lshrrev_b32_e32 v70, 16, v64
	v_and_or_b32 v66, v71, s29, v65
	s_waitcnt lgkmcnt(0)
	v_add_f32_e32 v64, v67, v68
	ds_bpermute_b32 v65, v205, v64
	v_and_or_b32 v67, v69, s29, v70
	global_store_dwordx2 v[106:107], v[66:67], off offset:3584
	s_cbranch_scc1 .LBB0_327
; __device__ __forceinline__ unsigned pk2(float lo, float hi) { return f2bf(lo) | (f2bf(hi) << 16); }
; __device__ __forceinline__ void norm_store2(bf16* O, int r0, int r1, int lane, const f32x4 (&v)[2][8], const f32x4 (&gm)[8], const f32x4 (&hs)[8]) {
;     ...
;     for (int q = 0; q < 2; ++q) { const int r = q == 0 ? r0 : r1; float s = 0.f;
; #pragma unroll
;         for (int j = 0; j < 8; ++j) s += (v[q][j].x * v[q][j].x + v[q][j].y * v[q][j].y) + (v[q][j].z * v[q][j].z + v[q][j].w * v[q][j].w);
;         const float rstd = 1.0f / sqrtf(wave_sum(s) * (1.0f / DMODEL) + 1e-6f);
;         if (r < M) { bf16* orow = O + (size_t)r * DMODEL;
; #pragma unroll
;             for (int j = 0; j < 8; ++j) { const f32x4 y = (v[q][j] * rstd) * gm[j] + hs[j]; v2u o; o.x = pk2(y.x, y.y); o.y = pk2(y.z, y.w); *(v2u*)(orow + 4 * (lane + 64 * j)) = o; } } }
	s_waitcnt lgkmcnt(0)
	v_add_f32_e32 v64, v64, v65
	v_fmamk_f32 v64, v64, 0x3a000000, v206
	v_mul_f32_e32 v65, 0x4f800000, v64
	v_cmp_gt_f32_e32 vcc, s27, v64
	s_ashr_i32 s21, s20, 31
	s_nop 0
	v_cndmask_b32_e32 v64, v64, v65, vcc
	v_sqrt_f32_e32 v65, v64
	s_nop 0
	v_add_u32_e32 v66, -1, v65
	v_fma_f32 v68, -v66, v65, v64
	v_add_u32_e32 v67, 1, v65
	v_cmp_ge_f32_e64 s[0:1], 0, v68
	s_nop 1
	v_cndmask_b32_e64 v66, v65, v66, s[0:1]
	v_fma_f32 v65, -v67, v65, v64
	v_cmp_lt_f32_e64 s[0:1], 0, v65
	s_nop 1
	v_cndmask_b32_e64 v65, v66, v67, s[0:1]
	v_mul_f32_e32 v66, 0x37800000, v65
	v_cndmask_b32_e32 v65, v65, v66, vcc
	v_cmp_class_f32_e32 vcc, v64, v207
	s_nop 1
	v_cndmask_b32_e32 v64, v65, v64, vcc
	v_div_scale_f32 v65, s[0:1], v64, v64, 1.0
	v_rcp_f32_e32 v66, v65
	s_lshl_b64 s[0:1], s[20:21], 12
	v_fma_f32 v67, -v65, v66, 1.0
	v_fmac_f32_e32 v66, v67, v66
	v_div_scale_f32 v67, vcc, 1.0, v64, 1.0
	v_mul_f32_e32 v68, v67, v66
	v_fma_f32 v69, -v65, v68, v67
	v_fmac_f32_e32 v68, v69, v66
	v_fma_f32 v65, -v65, v68, v67
	v_div_fmas_f32 v65, v65, v66, v68
	v_div_fixup_f32 v64, v65, v64, 1.0
	v_pk_mul_f32 v[60:61], v[60:61], v[64:65] op_sel_hi:[1,0]
	v_pk_mul_f32 v[62:63], v[62:63], v[64:65] op_sel_hi:[1,0]
	v_pk_fma_f32 v[60:61], v[164:165], v[60:61], v[0:1]
	v_pk_fma_f32 v[62:63], v[162:163], v[62:63], v[2:3]
	v_bfe_u32 v65, v60, 16, 1
	v_add3_u32 v60, v60, v65, s28
	v_bfe_u32 v65, v61, 16, 1
	v_lshrrev_b32_e32 v60, 16, v60
	v_add3_u32 v61, v61, v65, s28
	v_and_or_b32 v60, v61, s29, v60
	v_bfe_u32 v61, v62, 16, 1
	v_add3_u32 v61, v62, v61, s28
	v_bfe_u32 v62, v63, 16, 1
	v_lshrrev_b32_e32 v61, 16, v61
	v_add3_u32 v62, v63, v62, s28
	v_pk_mul_f32 v[56:57], v[56:57], v[64:65] op_sel_hi:[1,0]
	v_and_or_b32 v61, v62, s29, v61
	v_lshl_add_u64 v[62:63], v[198:199], 0, s[0:1]
	v_pk_fma_f32 v[56:57], v[168:169], v[56:57], v[4:5]
	global_store_dwordx2 v[62:63], v[60:61], off
	v_bfe_u32 v60, v56, 16, 1
	v_pk_mul_f32 v[58:59], v[58:59], v[64:65] op_sel_hi:[1,0]
	v_add3_u32 v56, v56, v60, s28
	v_bfe_u32 v60, v57, 16, 1
	v_pk_fma_f32 v[58:59], v[166:167], v[58:59], v[6:7]
	v_lshrrev_b32_e32 v56, 16, v56
	v_add3_u32 v57, v57, v60, s28
	v_and_or_b32 v56, v57, s29, v56
	v_bfe_u32 v57, v58, 16, 1
	v_add3_u32 v57, v58, v57, s28
	v_bfe_u32 v58, v59, 16, 1
	v_lshrrev_b32_e32 v57, 16, v57
	v_add3_u32 v58, v59, v58, s28
	v_pk_mul_f32 v[52:53], v[52:53], v[64:65] op_sel_hi:[1,0]
	v_and_or_b32 v57, v58, s29, v57
	v_pk_fma_f32 v[52:53], v[172:173], v[52:53], v[8:9]
	global_store_dwordx2 v[62:63], v[56:57], off offset:512
	v_bfe_u32 v56, v52, 16, 1
	v_pk_mul_f32 v[54:55], v[54:55], v[64:65] op_sel_hi:[1,0]
	v_add3_u32 v52, v52, v56, s28
	v_bfe_u32 v56, v53, 16, 1
	v_pk_fma_f32 v[54:55], v[170:171], v[54:55], v[10:11]
	v_lshrrev_b32_e32 v52, 16, v52
	v_add3_u32 v53, v53, v56, s28
	v_and_or_b32 v52, v53, s29, v52
	v_bfe_u32 v53, v54, 16, 1
	v_add3_u32 v53, v54, v53, s28
	v_bfe_u32 v54, v55, 16, 1
	v_lshrrev_b32_e32 v53, 16, v53
	v_add3_u32 v54, v55, v54, s28
	v_pk_mul_f32 v[48:49], v[48:49], v[64:65] op_sel_hi:[1,0]
	v_and_or_b32 v53, v54, s29, v53
	v_pk_fma_f32 v[48:49], v[176:177], v[48:49], v[12:13]
	global_store_dwordx2 v[62:63], v[52:53], off offset:1024
	v_bfe_u32 v52, v48, 16, 1
	v_pk_mul_f32 v[50:51], v[50:51], v[64:65] op_sel_hi:[1,0]
	v_add3_u32 v48, v48, v52, s28
	v_bfe_u32 v52, v49, 16, 1
	v_pk_fma_f32 v[50:51], v[174:175], v[50:51], v[14:15]
	v_lshrrev_b32_e32 v48, 16, v48
	v_add3_u32 v49, v49, v52, s28
	v_and_or_b32 v48, v49, s29, v48
	v_bfe_u32 v49, v50, 16, 1
	v_add3_u32 v49, v50, v49, s28
	v_bfe_u32 v50, v51, 16, 1
	v_lshrrev_b32_e32 v49, 16, v49
	v_add3_u32 v50, v51, v50, s28
	v_pk_mul_f32 v[44:45], v[44:45], v[64:65] op_sel_hi:[1,0]
	v_and_or_b32 v49, v50, s29, v49
	v_pk_fma_f32 v[44:45], v[180:181], v[44:45], v[16:17]
	global_store_dwordx2 v[62:63], v[48:49], off offset:1536
	v_bfe_u32 v48, v44, 16, 1
	v_pk_mul_f32 v[46:47], v[46:47], v[64:65] op_sel_hi:[1,0]
	v_add3_u32 v44, v44, v48, s28
	v_bfe_u32 v48, v45, 16, 1
	v_pk_fma_f32 v[46:47], v[178:179], v[46:47], v[18:19]
	v_lshrrev_b32_e32 v44, 16, v44
	v_add3_u32 v45, v45, v48, s28
	v_and_or_b32 v44, v45, s29, v44
	v_bfe_u32 v45, v46, 16, 1
	v_add3_u32 v45, v46, v45, s28
	v_bfe_u32 v46, v47, 16, 1
	v_lshrrev_b32_e32 v45, 16, v45
	v_add3_u32 v46, v47, v46, s28
	v_pk_mul_f32 v[40:41], v[40:41], v[64:65] op_sel_hi:[1,0]
	v_and_or_b32 v45, v46, s29, v45
	v_pk_fma_f32 v[40:41], v[184:185], v[40:41], v[20:21]
	global_store_dwordx2 v[62:63], v[44:45], off offset:2048
	v_bfe_u32 v44, v40, 16, 1
	v_pk_mul_f32 v[42:43], v[42:43], v[64:65] op_sel_hi:[1,0]
	v_add3_u32 v40, v40, v44, s28
	v_bfe_u32 v44, v41, 16, 1
	v_pk_fma_f32 v[42:43], v[182:183], v[42:43], v[22:23]
	v_lshrrev_b32_e32 v40, 16, v40
	v_add3_u32 v41, v41, v44, s28
	v_and_or_b32 v40, v41, s29, v40
	v_bfe_u32 v41, v42, 16, 1
	v_add3_u32 v41, v42, v41, s28
	v_bfe_u32 v42, v43, 16, 1
	v_lshrrev_b32_e32 v41, 16, v41
	v_add3_u32 v42, v43, v42, s28
	v_pk_mul_f32 v[36:37], v[36:37], v[64:65] op_sel_hi:[1,0]
	v_and_or_b32 v41, v42, s29, v41
	v_pk_fma_f32 v[36:37], v[188:189], v[36:37], v[24:25]
	global_store_dwordx2 v[62:63], v[40:41], off offset:2560
	v_bfe_u32 v40, v36, 16, 1
	v_pk_mul_f32 v[38:39], v[38:39], v[64:65] op_sel_hi:[1,0]
	v_add3_u32 v36, v36, v40, s28
	v_bfe_u32 v40, v37, 16, 1
	v_pk_fma_f32 v[38:39], v[186:187], v[38:39], v[26:27]
	v_lshrrev_b32_e32 v36, 16, v36
	v_add3_u32 v37, v37, v40, s28
	v_and_or_b32 v36, v37, s29, v36
	v_bfe_u32 v37, v38, 16, 1
	v_add3_u32 v37, v38, v37, s28
	v_bfe_u32 v38, v39, 16, 1
	v_lshrrev_b32_e32 v37, 16, v37
	v_add3_u32 v38, v39, v38, s28
	v_pk_mul_f32 v[32:33], v[32:33], v[64:65] op_sel_hi:[1,0]
	v_and_or_b32 v37, v38, s29, v37
	v_pk_fma_f32 v[32:33], v[192:193], v[32:33], v[28:29]
	global_store_dwordx2 v[62:63], v[36:37], off offset:3072
	v_bfe_u32 v36, v32, 16, 1
	v_pk_mul_f32 v[34:35], v[34:35], v[64:65] op_sel_hi:[1,0]
	v_add3_u32 v32, v32, v36, s28
	v_bfe_u32 v36, v33, 16, 1
	v_pk_fma_f32 v[34:35], v[190:191], v[34:35], v[30:31]
	v_lshrrev_b32_e32 v32, 16, v32
	v_add3_u32 v33, v33, v36, s28
	v_and_or_b32 v32, v33, s29, v32
	v_bfe_u32 v33, v34, 16, 1
	v_add3_u32 v33, v34, v33, s28
	v_bfe_u32 v34, v35, 16, 1
	v_lshrrev_b32_e32 v33, 16, v33
	v_add3_u32 v34, v35, v34, s28
	v_and_or_b32 v33, v34, s29, v33
	global_store_dwordx2 v[62:63], v[32:33], off offset:3584
; __device__ __forceinline__ void norm_load2(const float* X, int r0, int r1, int lane, f32x4 (&v)[2][8]) {
;     const f32x4* x0 = (const f32x4*)(X + (size_t)(r0 < M ? r0 : 0) * DMODEL) + lane; const f32x4* x1 = (const f32x4*)(X + (size_t)(r1 < M ? r1 : 0) * DMODEL) + lane;
; #pragma unroll
;     for (int j = 0; j < 8; ++j) { v[0][j] = x0[64 * j]; v[1][j] = x1[64 * j]; }
; }
; __device__ __forceinline__ void norm_store2(bf16* O, int r0, int r1, int lane, const f32x4 (&v)[2][8], const f32x4 (&gm)[8], const f32x4 (&hs)[8]) {
; #pragma unroll
;     for (int q = 0; q < 2; ++q) { const int r = q == 0 ? r0 : r1; float s = 0.f;
; #pragma unroll
;         for (int j = 0; j < 8; ++j) s += (v[q][j].x * v[q][j].x + v[q][j].y * v[q][j].y) + (v[q][j].z * v[q][j].z + v[q][j].w * v[q][j].w);
;         const float rstd = 1.0f / sqrtf(wave_sum(s) * (1.0f / DMODEL) + 1e-6f);
; __device__ __forceinline__ void norm_mod_pass(const float* X, const float* gam, const float* sc, const float* sh, bf16* O, int gw, int NGW, int lane) {
;     ...
;         norm_load2(X, row + 4 * NGW, row + 5 * NGW, lane, va);
.LBB0_327:
	s_add_i32 s0, s24, s31
	s_add_i32 s15, s23, s31
	s_cmpk_lt_i32 s0, 0x4000
	s_cselect_b32 s0, s0, 0
	s_ashr_i32 s1, s0, 31
	s_lshl_b64 s[0:1], s[0:1], 13
	s_cmpk_lt_i32 s15, 0x4000
	v_lshl_add_u64 v[32:33], v[194:195], 0, s[0:1]
	s_cselect_b32 s0, s15, 0
	s_ashr_i32 s1, s0, 31
	s_lshl_b64 s[0:1], s[0:1], 13
	v_lshl_add_u64 v[34:35], v[194:195], 0, s[0:1]
	global_load_dwordx4 v[104:107], v[32:33], off nt
	global_load_dwordx4 v[92:95], v[32:33], off offset:1024 nt
	global_load_dwordx4 v[60:63], v[34:35], off nt
	global_load_dwordx4 v[56:59], v[34:35], off offset:1024 nt
	global_load_dwordx4 v[84:87], v[32:33], off offset:2048 nt
	global_load_dwordx4 v[80:83], v[32:33], off offset:3072 nt
	global_load_dwordx4 v[52:55], v[34:35], off offset:2048 nt
	global_load_dwordx4 v[48:51], v[34:35], off offset:3072 nt
	v_add_co_u32_e32 v32, vcc, s22, v32
	s_waitcnt vmcnt(0)
	v_mul_f32_e32 v208, v133, v133
	v_addc_co_u32_e32 v33, vcc, 0, v33, vcc
	v_add_co_u32_e32 v34, vcc, s22, v34
	v_mul_f32_e32 v209, v135, v135
	s_nop 0
	v_addc_co_u32_e32 v35, vcc, 0, v35, vcc
	global_load_dwordx4 v[76:79], v[32:33], off nt
	global_load_dwordx4 v[72:75], v[32:33], off offset:1024 nt
	global_load_dwordx4 v[44:47], v[34:35], off nt
	global_load_dwordx4 v[40:43], v[34:35], off offset:1024 nt
	global_load_dwordx4 v[68:71], v[32:33], off offset:2048 nt
	s_waitcnt lgkmcnt(0)
	global_load_dwordx4 v[64:67], v[32:33], off offset:3072 nt
	global_load_dwordx4 v[36:39], v[34:35], off offset:2048 nt
	s_nop 0
	global_load_dwordx4 v[32:35], v[34:35], off offset:3072 nt
	v_fmac_f32_e32 v208, v132, v132
	v_fmac_f32_e32 v209, v134, v134
	v_add_f32_e32 v208, v208, v209
	v_mul_f32_e32 v209, v129, v129
	v_mul_f32_e32 v210, v131, v131
	v_fmac_f32_e32 v209, v128, v128
	v_fmac_f32_e32 v210, v130, v130
	v_add_f32_e32 v209, v209, v210
	v_add_f32_e32 v208, v208, v209
	v_mul_f32_e32 v209, v157, v157
	v_mul_f32_e32 v210, v159, v159
	v_fmac_f32_e32 v209, v156, v156
	v_fmac_f32_e32 v210, v158, v158
	v_add_f32_e32 v209, v209, v210
	v_add_f32_e32 v208, v208, v209
	v_mul_f32_e32 v209, v153, v153
	v_mul_f32_e32 v210, v155, v155
	v_fmac_f32_e32 v209, v152, v152
	v_fmac_f32_e32 v210, v154, v154
	v_add_f32_e32 v209, v209, v210
	v_add_f32_e32 v208, v208, v209
	v_mul_f32_e32 v209, v149, v149
	v_mul_f32_e32 v210, v151, v151
	v_fmac_f32_e32 v209, v148, v148
	v_fmac_f32_e32 v210, v150, v150
	v_add_f32_e32 v209, v209, v210
	v_add_f32_e32 v208, v208, v209
	v_mul_f32_e32 v209, v145, v145
	v_mul_f32_e32 v210, v147, v147
	v_fmac_f32_e32 v209, v144, v144
	v_fmac_f32_e32 v210, v146, v146
	v_add_f32_e32 v209, v209, v210
	v_add_f32_e32 v208, v208, v209
	v_mul_f32_e32 v209, v141, v141
	v_mul_f32_e32 v210, v143, v143
	v_fmac_f32_e32 v209, v140, v140
	v_fmac_f32_e32 v210, v142, v142
	v_add_f32_e32 v209, v209, v210
	v_add_f32_e32 v208, v208, v209
	v_mul_f32_e32 v209, v137, v137
	v_mul_f32_e32 v210, v139, v139
	v_fmac_f32_e32 v209, v136, v136
	v_fmac_f32_e32 v210, v138, v138
	v_add_f32_e32 v209, v209, v210
	v_add_f32_e32 v208, v208, v209
	ds_bpermute_b32 v209, v200, v208
	s_andn2_b64 vcc, exec, s[18:19]
	s_waitcnt lgkmcnt(0)
	v_add_f32_e32 v208, v208, v209
	ds_bpermute_b32 v209, v201, v208
	s_waitcnt lgkmcnt(0)
	v_add_f32_e32 v208, v208, v209
	ds_bpermute_b32 v209, v202, v208
	s_waitcnt lgkmcnt(0)
	v_add_f32_e32 v208, v208, v209
	ds_bpermute_b32 v209, v203, v208
	s_waitcnt lgkmcnt(0)
	v_add_f32_e32 v208, v208, v209
	ds_bpermute_b32 v209, v204, v208
	s_waitcnt lgkmcnt(0)
	v_add_f32_e32 v208, v208, v209
	ds_bpermute_b32 v209, v205, v208
	s_cbranch_vccnz .LBB0_329
; __device__ __forceinline__ unsigned pk2(float lo, float hi) { return f2bf(lo) | (f2bf(hi) << 16); }
; __device__ __forceinline__ void norm_store2(bf16* O, int r0, int r1, int lane, const f32x4 (&v)[2][8], const f32x4 (&gm)[8], const f32x4 (&hs)[8]) {
;     ...
;     for (int q = 0; q < 2; ++q) { const int r = q == 0 ? r0 : r1; float s = 0.f;
; #pragma unroll
;         for (int j = 0; j < 8; ++j) s += (v[q][j].x * v[q][j].x + v[q][j].y * v[q][j].y) + (v[q][j].z * v[q][j].z + v[q][j].w * v[q][j].w);
;         const float rstd = 1.0f / sqrtf(wave_sum(s) * (1.0f / DMODEL) + 1e-6f);
;         if (r < M) { bf16* orow = O + (size_t)r * DMODEL;
; #pragma unroll
;             for (int j = 0; j < 8; ++j) { const f32x4 y = (v[q][j] * rstd) * gm[j] + hs[j]; v2u o; o.x = pk2(y.x, y.y); o.y = pk2(y.z, y.w); *(v2u*)(orow + 4 * (lane + 64 * j)) = o; } } }
	s_waitcnt lgkmcnt(0)
	v_add_f32_e32 v208, v208, v209
	v_fmamk_f32 v208, v208, 0x3a000000, v206
	v_mul_f32_e32 v209, 0x4f800000, v208
	v_cmp_gt_f32_e32 vcc, s27, v208
	s_nop 1
	v_cndmask_b32_e32 v208, v208, v209, vcc
	v_sqrt_f32_e32 v209, v208
	s_nop 0
	v_add_u32_e32 v210, -1, v209
	v_fma_f32 v212, -v210, v209, v208
	v_add_u32_e32 v211, 1, v209
	v_cmp_ge_f32_e64 s[0:1], 0, v212
	s_nop 1
	v_cndmask_b32_e64 v210, v209, v210, s[0:1]
	v_fma_f32 v209, -v211, v209, v208
	v_cmp_lt_f32_e64 s[0:1], 0, v209
	s_nop 1
	v_cndmask_b32_e64 v209, v210, v211, s[0:1]
	v_mul_f32_e32 v210, 0x37800000, v209
	v_cndmask_b32_e32 v209, v209, v210, vcc
	v_cmp_class_f32_e32 vcc, v208, v207
	s_nop 1
	v_cndmask_b32_e32 v208, v209, v208, vcc
	v_div_scale_f32 v209, s[0:1], v208, v208, 1.0
	v_rcp_f32_e32 v210, v209
	s_nop 0
	v_fma_f32 v211, -v209, v210, 1.0
	v_fmac_f32_e32 v210, v211, v210
	v_div_scale_f32 v211, vcc, 1.0, v208, 1.0
	v_mul_f32_e32 v212, v211, v210
	v_fma_f32 v213, -v209, v212, v211
	v_fmac_f32_e32 v212, v213, v210
	v_fma_f32 v209, -v209, v212, v211
	v_div_fmas_f32 v209, v209, v210, v212
	v_div_fixup_f32 v208, v209, v208, 1.0
	v_pk_mul_f32 v[132:133], v[132:133], v[208:209] op_sel_hi:[1,0]
	v_pk_mul_f32 v[134:135], v[134:135], v[208:209] op_sel_hi:[1,0]
	v_pk_fma_f32 v[132:133], v[164:165], v[132:133], v[0:1]
	v_pk_fma_f32 v[134:135], v[162:163], v[134:135], v[2:3]
	v_bfe_u32 v209, v132, 16, 1
	v_add3_u32 v132, v132, v209, s28
	v_bfe_u32 v209, v133, 16, 1
	v_lshrrev_b32_e32 v132, 16, v132
	v_add3_u32 v133, v133, v209, s28
	v_and_or_b32 v132, v133, s29, v132
	v_bfe_u32 v133, v134, 16, 1
	v_add3_u32 v133, v134, v133, s28
	v_bfe_u32 v134, v135, 16, 1
	v_lshrrev_b32_e32 v133, 16, v133
	v_add3_u32 v134, v135, v134, s28
	v_and_or_b32 v133, v134, s29, v133
	v_lshl_add_u64 v[134:135], s[12:13], 0, v[196:197]
	v_add_co_u32_e32 v134, vcc, s30, v134
	v_pk_mul_f32 v[128:129], v[128:129], v[208:209] op_sel_hi:[1,0]
	s_nop 0
	v_addc_co_u32_e32 v135, vcc, 0, v135, vcc
	v_pk_fma_f32 v[128:129], v[168:169], v[128:129], v[4:5]
	global_store_dwordx2 v[134:135], v[132:133], off
	v_bfe_u32 v132, v128, 16, 1
	v_pk_mul_f32 v[130:131], v[130:131], v[208:209] op_sel_hi:[1,0]
	v_add3_u32 v128, v128, v132, s28
	v_bfe_u32 v132, v129, 16, 1
	v_pk_fma_f32 v[130:131], v[166:167], v[130:131], v[6:7]
	v_lshrrev_b32_e32 v128, 16, v128
	v_add3_u32 v129, v129, v132, s28
	v_and_or_b32 v128, v129, s29, v128
	v_bfe_u32 v129, v130, 16, 1
	v_add3_u32 v129, v130, v129, s28
	v_bfe_u32 v130, v131, 16, 1
	v_lshrrev_b32_e32 v129, 16, v129
	v_add3_u32 v130, v131, v130, s28
	v_and_or_b32 v129, v130, s29, v129
	global_store_dwordx2 v[134:135], v[128:129], off offset:512
	v_pk_mul_f32 v[128:129], v[156:157], v[208:209] op_sel_hi:[1,0]
	v_pk_mul_f32 v[130:131], v[158:159], v[208:209] op_sel_hi:[1,0]
	v_pk_fma_f32 v[128:129], v[172:173], v[128:129], v[8:9]
	v_pk_fma_f32 v[130:131], v[170:171], v[130:131], v[10:11]
	v_bfe_u32 v132, v128, 16, 1
	v_add3_u32 v128, v128, v132, s28
	v_bfe_u32 v132, v129, 16, 1
	v_lshrrev_b32_e32 v128, 16, v128
	v_add3_u32 v129, v129, v132, s28
	v_and_or_b32 v128, v129, s29, v128
	v_bfe_u32 v129, v130, 16, 1
	v_add3_u32 v129, v130, v129, s28
	v_bfe_u32 v130, v131, 16, 1
	v_lshrrev_b32_e32 v129, 16, v129
	v_add3_u32 v130, v131, v130, s28
	v_and_or_b32 v129, v130, s29, v129
	global_store_dwordx2 v[134:135], v[128:129], off offset:1024
	v_pk_mul_f32 v[128:129], v[152:153], v[208:209] op_sel_hi:[1,0]
	v_pk_mul_f32 v[130:131], v[154:155], v[208:209] op_sel_hi:[1,0]
	v_pk_fma_f32 v[128:129], v[176:177], v[128:129], v[12:13]
	v_pk_fma_f32 v[130:131], v[174:175], v[130:131], v[14:15]
	v_bfe_u32 v132, v128, 16, 1
	v_add3_u32 v128, v128, v132, s28
	v_bfe_u32 v132, v129, 16, 1
	v_lshrrev_b32_e32 v128, 16, v128
	v_add3_u32 v129, v129, v132, s28
	v_and_or_b32 v128, v129, s29, v128
	v_bfe_u32 v129, v130, 16, 1
	v_add3_u32 v129, v130, v129, s28
	v_bfe_u32 v130, v131, 16, 1
	v_lshrrev_b32_e32 v129, 16, v129
	v_add3_u32 v130, v131, v130, s28
	v_and_or_b32 v129, v130, s29, v129
	global_store_dwordx2 v[134:135], v[128:129], off offset:1536
	v_pk_mul_f32 v[128:129], v[148:149], v[208:209] op_sel_hi:[1,0]
	v_pk_mul_f32 v[130:131], v[150:151], v[208:209] op_sel_hi:[1,0]
	v_pk_fma_f32 v[128:129], v[180:181], v[128:129], v[16:17]
	v_pk_fma_f32 v[130:131], v[178:179], v[130:131], v[18:19]
	v_bfe_u32 v132, v128, 16, 1
	v_add3_u32 v128, v128, v132, s28
	v_bfe_u32 v132, v129, 16, 1
	v_lshrrev_b32_e32 v128, 16, v128
	v_add3_u32 v129, v129, v132, s28
	v_and_or_b32 v128, v129, s29, v128
	v_bfe_u32 v129, v130, 16, 1
	v_add3_u32 v129, v130, v129, s28
	v_bfe_u32 v130, v131, 16, 1
	v_lshrrev_b32_e32 v129, 16, v129
	v_add3_u32 v130, v131, v130, s28
	v_and_or_b32 v129, v130, s29, v129
	global_store_dwordx2 v[134:135], v[128:129], off offset:2048
	v_pk_mul_f32 v[128:129], v[144:145], v[208:209] op_sel_hi:[1,0]
	v_pk_mul_f32 v[130:131], v[146:147], v[208:209] op_sel_hi:[1,0]
	v_pk_fma_f32 v[128:129], v[184:185], v[128:129], v[20:21]
	v_pk_fma_f32 v[130:131], v[182:183], v[130:131], v[22:23]
	v_bfe_u32 v132, v128, 16, 1
	v_add3_u32 v128, v128, v132, s28
	v_bfe_u32 v132, v129, 16, 1
	v_lshrrev_b32_e32 v128, 16, v128
	v_add3_u32 v129, v129, v132, s28
	v_and_or_b32 v128, v129, s29, v128
	v_bfe_u32 v129, v130, 16, 1
	v_add3_u32 v129, v130, v129, s28
	v_bfe_u32 v130, v131, 16, 1
	v_lshrrev_b32_e32 v129, 16, v129
	v_add3_u32 v130, v131, v130, s28
	v_and_or_b32 v129, v130, s29, v129
	global_store_dwordx2 v[134:135], v[128:129], off offset:2560
	v_pk_mul_f32 v[128:129], v[140:141], v[208:209] op_sel_hi:[1,0]
	v_pk_mul_f32 v[130:131], v[142:143], v[208:209] op_sel_hi:[1,0]
	v_pk_fma_f32 v[128:129], v[188:189], v[128:129], v[24:25]
	v_pk_fma_f32 v[130:131], v[186:187], v[130:131], v[26:27]
	v_bfe_u32 v132, v128, 16, 1
	v_add3_u32 v128, v128, v132, s28
	v_bfe_u32 v132, v129, 16, 1
	v_lshrrev_b32_e32 v128, 16, v128
	v_add3_u32 v129, v129, v132, s28
	v_and_or_b32 v128, v129, s29, v128
	v_bfe_u32 v129, v130, 16, 1
	v_add3_u32 v129, v130, v129, s28
	v_bfe_u32 v130, v131, 16, 1
	v_lshrrev_b32_e32 v129, 16, v129
	v_add3_u32 v130, v131, v130, s28
	v_and_or_b32 v129, v130, s29, v129
	global_store_dwordx2 v[134:135], v[128:129], off offset:3072
	v_pk_mul_f32 v[128:129], v[136:137], v[208:209] op_sel_hi:[1,0]
	v_pk_mul_f32 v[130:131], v[138:139], v[208:209] op_sel_hi:[1,0]
	v_pk_fma_f32 v[128:129], v[192:193], v[128:129], v[28:29]
	v_pk_fma_f32 v[130:131], v[190:191], v[130:131], v[30:31]
	v_bfe_u32 v132, v128, 16, 1
	v_add3_u32 v128, v128, v132, s28
	v_bfe_u32 v132, v129, 16, 1
	v_lshrrev_b32_e32 v128, 16, v128
	v_add3_u32 v129, v129, v132, s28
	v_and_or_b32 v128, v129, s29, v128
	v_bfe_u32 v129, v130, 16, 1
	v_add3_u32 v129, v130, v129, s28
	v_bfe_u32 v130, v131, 16, 1
	v_lshrrev_b32_e32 v129, 16, v129
	v_add3_u32 v130, v131, v130, s28
	v_and_or_b32 v129, v130, s29, v129
	global_store_dwordx2 v[134:135], v[128:129], off offset:3584

; __global__ void __launch_bounds__(NTHR, 2) mk_fwd(Args args) {
;     ...
;         for (int which = 0; which < 2; ++which) { const bf16* Wt = which == 0 ? p_WIN : p_W2U; const float* shv = p_mod + (which == 0 ? 3 : 6) * DMODEL; float* bvo = p_BV + (which == 0 ? 0 : NIN); const int nrows = which == 0 ? NIN : NUP;
;             float shr[32];
; #pragma unroll
;             for (int j = 0; j < 4; ++j)
; #pragma unroll
;                 for (int e = 0; e < 8; ++e) shr[j * 8 + e] = shv[j * 512 + lane * 8 + e];
.LBB0_337:
	s_add_i32 s0, 0, 0x20118
	v_mov_b32_e32 v0, s0
	ds_read_b64 v[82:83], v0
	v_lshlrev_b32_e32 v80, 3, v160
	v_or_b32_e32 v84, 4, v80
	v_cmp_ne_u32_e64 s[0:1], 0, v160
	v_cmp_eq_u32_e64 s[4:5], 0, v160
	v_ashrrev_i32_e32 v81, 31, v80
	s_waitcnt lgkmcnt(0)
	v_readfirstlane_b32 s8, v82
	v_readfirstlane_b32 s9, v83
	v_ashrrev_i32_e32 v85, 31, v84
	s_movk_i32 s10, 0x1000
	s_cmpk_lt_i32 s72, 0x1000
	v_mov_b32_e32 v0, v82
	v_mov_b32_e32 v1, v83
	s_cbranch_scc0 .LBB0_349
	s_add_u32 s12, s8, 0x406000
	s_addc_u32 s13, s9, 0
	v_lshl_add_u64 v[16:17], v[80:81], 2, s[12:13]
	s_waitcnt vmcnt(0)
	v_add_co_u32_e32 v32, vcc, s10, v16
	v_lshl_add_u64 v[18:19], v[84:85], 2, s[12:13]
	s_nop 0
	v_addc_co_u32_e32 v33, vcc, 0, v17, vcc
	global_load_dwordx4 v[0:3], v[16:17], off nt
	global_load_dwordx4 v[4:7], v[16:17], off offset:2048 nt
	global_load_dwordx4 v[8:11], v[18:19], off nt
	global_load_dwordx4 v[12:15], v[16:17], off offset:2064 nt
	s_nop 0
	global_load_dwordx4 v[16:19], v[32:33], off nt
	global_load_dwordx4 v[20:23], v[32:33], off offset:16 nt
	global_load_dwordx4 v[24:27], v[32:33], off offset:2048 nt
	global_load_dwordx4 v[28:31], v[32:33], off offset:2064 nt
	s_add_u32 s24, s8, 0x800000
	s_addc_u32 s25, s9, 0
	v_lshl_add_u64 v[32:33], v[80:81], 1, s[8:9]
	s_mov_b64 s[8:9], 0x9400000
	v_lshl_add_u64 v[86:87], v[32:33], 0, s[8:9]
	v_mbcnt_lo_u32_b32 v32, -1, 0
	v_mbcnt_hi_u32_b32 v32, -1, v32
	v_and_b32_e32 v33, 64, v32
	v_add_u32_e32 v33, 64, v33
	v_xor_b32_e32 v34, 1, v32
	v_cmp_lt_i32_e32 vcc, v34, v33
	s_lshl_b32 s26, s70, 5
	s_lshl_b32 s27, s70, 4
	v_cndmask_b32_e32 v34, v32, v34, vcc
	v_lshlrev_b32_e32 v88, 2, v34
	v_xor_b32_e32 v34, 2, v32
	v_cmp_lt_i32_e32 vcc, v34, v33
	s_mov_b32 s8, s72
	s_nop 0
	v_cndmask_b32_e32 v34, v32, v34, vcc
	v_lshlrev_b32_e32 v89, 2, v34
	v_xor_b32_e32 v34, 4, v32
	v_cmp_lt_i32_e32 vcc, v34, v33
	s_nop 1
	v_cndmask_b32_e32 v34, v32, v34, vcc
	v_lshlrev_b32_e32 v90, 2, v34
	v_xor_b32_e32 v34, 8, v32
	v_cmp_lt_i32_e32 vcc, v34, v33
	s_nop 1
	v_cndmask_b32_e32 v34, v32, v34, vcc
	v_lshlrev_b32_e32 v91, 2, v34
	v_xor_b32_e32 v34, 16, v32
	v_cmp_lt_i32_e32 vcc, v34, v33
	s_nop 1
	v_cndmask_b32_e32 v34, v32, v34, vcc
	v_lshlrev_b32_e32 v92, 2, v34
	v_xor_b32_e32 v34, 32, v32
	v_cmp_lt_i32_e32 vcc, v34, v33
	s_nop 1
	v_cndmask_b32_e32 v32, v32, v34, vcc
	v_lshlrev_b32_e32 v93, 2, v32
	s_branch .LBB0_340

; __device__ __forceinline__ float blo(unsigned w) { return __uint_as_float(w << 16); }
; __device__ __forceinline__ float bhi(unsigned w) { return __uint_as_float(w & 0xffff0000u); }
; __global__ void __launch_bounds__(NTHR, 2) mk_fwd(Args args) {
;     ...
;             for (int r = gw; r < nrows; r += 4 * NGW) {
;                 v4u w[4][4];
; #pragma unroll
;                 for (int q = 0; q < 4; ++q) { const int rq = (r + q * NGW < nrows) ? r + q * NGW : r; const bf16* wr_ = Wt + (size_t)rq * DMODEL + lane * 8;
; #pragma unroll
;                     for (int j = 0; j < 4; ++j) w[q][j] = *(const v4u*)(wr_ + j * 512); }
; #pragma unroll
;                 for (int q = 0; q < 4; ++q) { float acc = 0.f;
; #pragma unroll
;                     for (int j = 0; j < 4; ++j) { const v4u x = w[q][j];
;                         acc += blo(x.x) * shr[j * 8 + 0] + bhi(x.x) * shr[j * 8 + 1] + blo(x.y) * shr[j * 8 + 2] + bhi(x.y) * shr[j * 8 + 3] + blo(x.z) * shr[j * 8 + 4] + bhi(x.z) * shr[j * 8 + 5] + blo(x.w) * shr[j * 8 + 6] + bhi(x.w) * shr[j * 8 + 7]; }
;                     acc = wave_sum(acc); if (lane == 0 && r + q * NGW < nrows) bvo[r + q * NGW] = acc; } } }
.LBB0_340:
	s_ashr_i32 s9, s8, 31
	s_lshl_b64 s[10:11], s[8:9], 12
	s_waitcnt lgkmcnt(0)
	v_lshl_add_u64 v[32:33], v[86:87], 0, s[10:11]
	global_load_dwordx4 v[94:97], v[32:33], off nt
	global_load_dwordx4 v[98:101], v[32:33], off offset:1024 nt
	global_load_dwordx4 v[102:105], v[32:33], off offset:2048 nt
	global_load_dwordx4 v[106:109], v[32:33], off offset:3072 nt
	s_add_i32 s18, s80, s8
	s_cmpk_gt_i32 s18, 0xfff
	s_cselect_b64 s[20:21], -1, 0
	s_and_b64 s[10:11], s[20:21], exec
	s_cselect_b32 s10, s8, s18
	s_ashr_i32 s11, s10, 31
	s_add_i32 s14, s27, s8
	s_lshl_b64 s[10:11], s[10:11], 12
	s_cmpk_gt_i32 s14, 0xfff
	s_cselect_b64 s[16:17], -1, 0
	v_lshl_add_u64 v[32:33], v[86:87], 0, s[10:11]
	s_and_b64 s[10:11], s[16:17], exec
	s_cselect_b32 s12, s8, s14
	s_ashr_i32 s13, s12, 31
	s_add_i32 s10, s3, s8
	s_lshl_b64 s[12:13], s[12:13], 12
	s_cmpk_gt_i32 s10, 0xfff
	global_load_dwordx4 v[76:79], v[32:33], off nt
	global_load_dwordx4 v[72:75], v[32:33], off offset:1024 nt
	global_load_dwordx4 v[68:71], v[32:33], off offset:2048 nt
	global_load_dwordx4 v[64:67], v[32:33], off offset:3072 nt
	v_lshl_add_u64 v[32:33], v[86:87], 0, s[12:13]
	s_cselect_b64 s[12:13], -1, 0
	s_and_b64 s[22:23], s[12:13], exec
	s_cselect_b32 s22, s8, s10
	s_ashr_i32 s23, s22, 31
	s_lshl_b64 s[22:23], s[22:23], 12
	v_lshl_add_u64 v[110:111], v[86:87], 0, s[22:23]
	global_load_dwordx4 v[60:63], v[32:33], off nt
	global_load_dwordx4 v[56:59], v[32:33], off offset:1024 nt
	global_load_dwordx4 v[52:55], v[32:33], off offset:2048 nt
	global_load_dwordx4 v[48:51], v[32:33], off offset:3072 nt
	global_load_dwordx4 v[44:47], v[110:111], off nt
	global_load_dwordx4 v[40:43], v[110:111], off offset:1024 nt
	global_load_dwordx4 v[36:39], v[110:111], off offset:2048 nt
	s_nop 0
	global_load_dwordx4 v[32:35], v[110:111], off offset:3072 nt
	s_waitcnt vmcnt(0) lgkmcnt(0)
	v_lshlrev_b32_e32 v110, 16, v94
	v_and_b32_e32 v94, 0xffff0000, v94
	v_mul_f32_e32 v94, v1, v94
	v_lshlrev_b32_e32 v111, 16, v95
	v_lshlrev_b32_e32 v114, 16, v98
	v_and_b32_e32 v98, 0xffff0000, v98
	v_fmac_f32_e32 v94, v0, v110
	v_and_b32_e32 v95, 0xffff0000, v95
	v_lshlrev_b32_e32 v118, 16, v102
	v_and_b32_e32 v102, 0xffff0000, v102
	v_mul_f32_e32 v98, v5, v98
	v_fmac_f32_e32 v94, v2, v111
	v_lshlrev_b32_e32 v112, 16, v96
	v_lshlrev_b32_e32 v115, 16, v99
	v_mul_f32_e32 v102, v17, v102
	v_fmac_f32_e32 v98, v4, v114
	v_fmac_f32_e32 v94, v3, v95
	v_and_b32_e32 v95, 0xffff0000, v106
	v_and_b32_e32 v96, 0xffff0000, v96
	v_and_b32_e32 v99, 0xffff0000, v99
	v_lshlrev_b32_e32 v119, 16, v103
	v_lshlrev_b32_e32 v122, 16, v106
	v_fmac_f32_e32 v102, v16, v118
	v_fmac_f32_e32 v98, v6, v115
	v_fmac_f32_e32 v94, v8, v112
	v_mul_f32_e32 v95, v25, v95
	v_lshlrev_b32_e32 v116, 16, v100
	v_and_b32_e32 v103, 0xffff0000, v103
	v_fmac_f32_e32 v102, v18, v119
	v_fmac_f32_e32 v98, v7, v99
	v_fmac_f32_e32 v94, v9, v96
	v_fmac_f32_e32 v95, v24, v122
	v_lshlrev_b32_e32 v96, 16, v107
	v_lshlrev_b32_e32 v113, 16, v97
	v_and_b32_e32 v100, 0xffff0000, v100
	v_lshlrev_b32_e32 v120, 16, v104
	v_fmac_f32_e32 v102, v19, v103
	v_fmac_f32_e32 v98, v12, v116
	v_fmac_f32_e32 v95, v26, v96
	v_and_b32_e32 v96, 0xffff0000, v107
	v_and_b32_e32 v97, 0xffff0000, v97
	v_lshlrev_b32_e32 v117, 16, v101
	v_and_b32_e32 v104, 0xffff0000, v104
	v_fmac_f32_e32 v102, v20, v120
	v_fmac_f32_e32 v98, v13, v100
	v_fmac_f32_e32 v94, v10, v113
	v_fmac_f32_e32 v95, v27, v96
	v_lshlrev_b32_e32 v96, 16, v108
	v_and_b32_e32 v101, 0xffff0000, v101
	v_lshlrev_b32_e32 v121, 16, v105
	v_fmac_f32_e32 v102, v21, v104
	v_fmac_f32_e32 v98, v14, v117
	v_fmac_f32_e32 v94, v11, v97
	v_fmac_f32_e32 v95, v28, v96
	v_and_b32_e32 v96, 0xffff0000, v108
	v_and_b32_e32 v105, 0xffff0000, v105
	v_fmac_f32_e32 v102, v22, v121
	v_fmac_f32_e32 v98, v15, v101
	v_add_f32_e32 v94, 0, v94
	v_fmac_f32_e32 v95, v29, v96
	v_lshlrev_b32_e32 v96, 16, v109
	v_fmac_f32_e32 v102, v23, v105
	v_add_f32_e32 v94, v94, v98
	v_fmac_f32_e32 v95, v30, v96
	v_and_b32_e32 v96, 0xffff0000, v109
	v_add_f32_e32 v94, v94, v102
	v_fmac_f32_e32 v95, v31, v96
	v_add_f32_e32 v94, v94, v95
	ds_bpermute_b32 v95, v88, v94
	s_waitcnt lgkmcnt(0)
	v_add_f32_e32 v94, v94, v95
	ds_bpermute_b32 v95, v89, v94
	s_waitcnt lgkmcnt(0)
	v_add_f32_e32 v94, v94, v95
	ds_bpermute_b32 v95, v90, v94
	s_waitcnt lgkmcnt(0)
	v_add_f32_e32 v94, v94, v95
	ds_bpermute_b32 v95, v91, v94
	s_waitcnt lgkmcnt(0)
	v_add_f32_e32 v94, v94, v95
	ds_bpermute_b32 v95, v92, v94
	s_waitcnt lgkmcnt(0)
	v_add_f32_e32 v94, v94, v95
	ds_bpermute_b32 v95, v93, v94
	s_and_saveexec_b64 s[22:23], s[4:5]
	s_cbranch_execz .LBB0_342
	s_lshl_b64 s[28:29], s[8:9], 2
	s_add_u32 s28, s24, s28
	s_addc_u32 s29, s25, s29
	s_waitcnt lgkmcnt(0)
	v_add_f32_e32 v96, v94, v95
	v_mov_b64_e32 v[94:95], s[28:29]
	global_store_dword v[94:95], v96, off

; __global__ void __launch_bounds__(NTHR, 2) mk_fwd(Args args) {
;     ...
;         for (int which = 0; which < 2; ++which) { const bf16* Wt = which == 0 ? p_WIN : p_W2U; const float* shv = p_mod + (which == 0 ? 3 : 6) * DMODEL; float* bvo = p_BV + (which == 0 ? 0 : NIN); const int nrows = which == 0 ? NIN : NUP;
;             float shr[32];
; #pragma unroll
;             for (int j = 0; j < 4; ++j)
; #pragma unroll
;                 for (int e = 0; e < 8; ++e) shr[j * 8 + e] = shv[j * 512 + lane * 8 + e];
;             for (int r = gw; r < nrows; r += 4 * NGW) {
;                 v4u w[4][4];
; #pragma unroll
;                 for (int q = 0; q < 4; ++q) { const int rq = (r + q * NGW < nrows) ? r + q * NGW : r; const bf16* wr_ = Wt + (size_t)rq * DMODEL + lane * 8;
; #pragma unroll
;                     for (int j = 0; j < 4; ++j) w[q][j] = *(const v4u*)(wr_ + j * 512); }
.LBB0_349:
	s_waitcnt lgkmcnt(0)
	v_readfirstlane_b32 s8, v0
	v_readfirstlane_b32 s9, v1
	v_readfirstlane_b32 s10, v82
	s_cmpk_gt_i32 s72, 0x2bff
	v_readfirstlane_b32 s11, v83
	s_cbranch_scc1 .LBB0_360
	s_add_u32 s12, s10, 0x40c000
	s_addc_u32 s13, s11, 0
	v_lshl_add_u64 v[16:17], v[80:81], 2, s[12:13]
	s_waitcnt vmcnt(0)
	v_add_co_u32_e32 v32, vcc, 0x1000, v16
	v_lshl_add_u64 v[18:19], v[84:85], 2, s[12:13]
	s_nop 0
	v_addc_co_u32_e32 v33, vcc, 0, v17, vcc
	global_load_dwordx4 v[0:3], v[16:17], off nt
	global_load_dwordx4 v[4:7], v[16:17], off offset:2048 nt
	global_load_dwordx4 v[8:11], v[18:19], off nt
	global_load_dwordx4 v[12:15], v[16:17], off offset:2064 nt
	s_nop 0
	global_load_dwordx4 v[16:19], v[32:33], off nt
	global_load_dwordx4 v[20:23], v[32:33], off offset:16 nt
	global_load_dwordx4 v[24:27], v[32:33], off offset:2048 nt
	global_load_dwordx4 v[28:31], v[32:33], off offset:2064 nt
	v_mov_b32_e32 v32, s8
	v_mov_b32_e32 v33, s9
	v_lshl_add_u64 v[32:33], v[80:81], 1, v[32:33]
	s_mov_b64 s[8:9], 0x5200000
	v_lshl_add_u64 v[80:81], v[32:33], 0, s[8:9]
	v_mbcnt_lo_u32_b32 v32, -1, 0
	v_mbcnt_hi_u32_b32 v32, -1, v32
	v_and_b32_e32 v33, 64, v32
	v_add_u32_e32 v33, 64, v33
	v_xor_b32_e32 v34, 1, v32
	v_cmp_lt_i32_e32 vcc, v34, v33
	s_add_u32 s24, s10, 0x804000
	s_addc_u32 s25, s11, 0
	v_cndmask_b32_e32 v34, v32, v34, vcc
	v_lshlrev_b32_e32 v82, 2, v34
	v_xor_b32_e32 v34, 2, v32
	v_cmp_lt_i32_e32 vcc, v34, v33
	s_lshl_b32 s26, s70, 5
	s_lshl_b32 s27, s70, 4
	v_cndmask_b32_e32 v34, v32, v34, vcc
	v_lshlrev_b32_e32 v83, 2, v34
	v_xor_b32_e32 v34, 4, v32
	v_cmp_lt_i32_e32 vcc, v34, v33
	s_mov_b32 s8, s72
	s_nop 0
	v_cndmask_b32_e32 v34, v32, v34, vcc
	v_lshlrev_b32_e32 v84, 2, v34
	v_xor_b32_e32 v34, 8, v32
	v_cmp_lt_i32_e32 vcc, v34, v33
	s_nop 1
	v_cndmask_b32_e32 v34, v32, v34, vcc
	v_lshlrev_b32_e32 v85, 2, v34
	v_xor_b32_e32 v34, 16, v32
	v_cmp_lt_i32_e32 vcc, v34, v33
	s_nop 1
	v_cndmask_b32_e32 v34, v32, v34, vcc
	v_lshlrev_b32_e32 v86, 2, v34
	v_xor_b32_e32 v34, 32, v32
	v_cmp_lt_i32_e32 vcc, v34, v33
	s_nop 1
	v_cndmask_b32_e32 v32, v32, v34, vcc
	v_lshlrev_b32_e32 v87, 2, v32
	s_branch .LBB0_352

; __device__ __forceinline__ float blo(unsigned w) { return __uint_as_float(w << 16); }
; __device__ __forceinline__ float bhi(unsigned w) { return __uint_as_float(w & 0xffff0000u); }
; __global__ void __launch_bounds__(NTHR, 2) mk_fwd(Args args) {
;     ...
;             for (int r = gw; r < nrows; r += 4 * NGW) {
;                 v4u w[4][4];
; #pragma unroll
;                 for (int q = 0; q < 4; ++q) { const int rq = (r + q * NGW < nrows) ? r + q * NGW : r; const bf16* wr_ = Wt + (size_t)rq * DMODEL + lane * 8;
; #pragma unroll
;                     for (int j = 0; j < 4; ++j) w[q][j] = *(const v4u*)(wr_ + j * 512); }
; #pragma unroll
;                 for (int q = 0; q < 4; ++q) { float acc = 0.f;
; #pragma unroll
;                     for (int j = 0; j < 4; ++j) { const v4u x = w[q][j];
;                         acc += blo(x.x) * shr[j * 8 + 0] + bhi(x.x) * shr[j * 8 + 1] + blo(x.y) * shr[j * 8 + 2] + bhi(x.y) * shr[j * 8 + 3] + blo(x.z) * shr[j * 8 + 4] + bhi(x.z) * shr[j * 8 + 5] + blo(x.w) * shr[j * 8 + 6] + bhi(x.w) * shr[j * 8 + 7]; }
;                     acc = wave_sum(acc); if (lane == 0 && r + q * NGW < nrows) bvo[r + q * NGW] = acc; } } }
.LBB0_352:
	s_ashr_i32 s9, s8, 31
	s_lshl_b64 s[10:11], s[8:9], 12
	s_waitcnt lgkmcnt(0)
	v_lshl_add_u64 v[32:33], v[80:81], 0, s[10:11]
	global_load_dwordx4 v[88:91], v[32:33], off nt
	global_load_dwordx4 v[92:95], v[32:33], off offset:1024 nt
	global_load_dwordx4 v[96:99], v[32:33], off offset:2048 nt
	global_load_dwordx4 v[100:103], v[32:33], off offset:3072 nt
	s_add_i32 s18, s80, s8
	s_cmpk_gt_i32 s18, 0x2bff
	s_cselect_b64 s[20:21], -1, 0
	s_and_b64 s[10:11], s[20:21], exec
	s_cselect_b32 s10, s8, s18
	s_ashr_i32 s11, s10, 31
	s_add_i32 s14, s27, s8
	s_lshl_b64 s[10:11], s[10:11], 12
	s_cmpk_gt_i32 s14, 0x2bff
	s_cselect_b64 s[16:17], -1, 0
	v_lshl_add_u64 v[32:33], v[80:81], 0, s[10:11]
	s_and_b64 s[10:11], s[16:17], exec
	s_cselect_b32 s12, s8, s14
	s_ashr_i32 s13, s12, 31
	s_add_i32 s10, s3, s8
	s_lshl_b64 s[12:13], s[12:13], 12
	s_cmpk_gt_i32 s10, 0x2bff
	global_load_dwordx4 v[76:79], v[32:33], off nt
	global_load_dwordx4 v[72:75], v[32:33], off offset:1024 nt
	global_load_dwordx4 v[68:71], v[32:33], off offset:2048 nt
	global_load_dwordx4 v[64:67], v[32:33], off offset:3072 nt
	v_lshl_add_u64 v[32:33], v[80:81], 0, s[12:13]
	s_cselect_b64 s[12:13], -1, 0
	s_and_b64 s[22:23], s[12:13], exec
	s_cselect_b32 s22, s8, s10
	s_ashr_i32 s23, s22, 31
	s_lshl_b64 s[22:23], s[22:23], 12
	v_lshl_add_u64 v[104:105], v[80:81], 0, s[22:23]
	global_load_dwordx4 v[60:63], v[32:33], off nt
	global_load_dwordx4 v[56:59], v[32:33], off offset:1024 nt
	global_load_dwordx4 v[52:55], v[32:33], off offset:2048 nt
	global_load_dwordx4 v[48:51], v[32:33], off offset:3072 nt
	global_load_dwordx4 v[44:47], v[104:105], off nt
	global_load_dwordx4 v[40:43], v[104:105], off offset:1024 nt
	global_load_dwordx4 v[36:39], v[104:105], off offset:2048 nt
	s_nop 0
	global_load_dwordx4 v[32:35], v[104:105], off offset:3072 nt
	s_waitcnt vmcnt(0) lgkmcnt(0)
	v_lshlrev_b32_e32 v104, 16, v88
	v_and_b32_e32 v88, 0xffff0000, v88
	v_mul_f32_e32 v88, v1, v88
	v_lshlrev_b32_e32 v105, 16, v89
	v_lshlrev_b32_e32 v108, 16, v92
	v_and_b32_e32 v92, 0xffff0000, v92
	v_fmac_f32_e32 v88, v0, v104
	v_and_b32_e32 v89, 0xffff0000, v89
	v_lshlrev_b32_e32 v112, 16, v96
	v_and_b32_e32 v96, 0xffff0000, v96
	v_mul_f32_e32 v92, v5, v92
	v_fmac_f32_e32 v88, v2, v105
	v_lshlrev_b32_e32 v106, 16, v90
	v_lshlrev_b32_e32 v109, 16, v93
	v_mul_f32_e32 v96, v17, v96
	v_fmac_f32_e32 v92, v4, v108
	v_fmac_f32_e32 v88, v3, v89
	v_and_b32_e32 v89, 0xffff0000, v100
	v_and_b32_e32 v90, 0xffff0000, v90
	v_and_b32_e32 v93, 0xffff0000, v93
	v_lshlrev_b32_e32 v113, 16, v97
	v_lshlrev_b32_e32 v116, 16, v100
	v_fmac_f32_e32 v96, v16, v112
	v_fmac_f32_e32 v92, v6, v109
	v_fmac_f32_e32 v88, v8, v106
	v_mul_f32_e32 v89, v25, v89
	v_lshlrev_b32_e32 v110, 16, v94
	v_and_b32_e32 v97, 0xffff0000, v97
	v_fmac_f32_e32 v96, v18, v113
	v_fmac_f32_e32 v92, v7, v93
	v_fmac_f32_e32 v88, v9, v90
	v_fmac_f32_e32 v89, v24, v116
	v_lshlrev_b32_e32 v90, 16, v101
	v_lshlrev_b32_e32 v107, 16, v91
	v_and_b32_e32 v94, 0xffff0000, v94
	v_lshlrev_b32_e32 v114, 16, v98
	v_fmac_f32_e32 v96, v19, v97
	v_fmac_f32_e32 v92, v12, v110
	v_fmac_f32_e32 v89, v26, v90
	v_and_b32_e32 v90, 0xffff0000, v101
	v_and_b32_e32 v91, 0xffff0000, v91
	v_lshlrev_b32_e32 v111, 16, v95
	v_and_b32_e32 v98, 0xffff0000, v98
	v_fmac_f32_e32 v96, v20, v114
	v_fmac_f32_e32 v92, v13, v94
	v_fmac_f32_e32 v88, v10, v107
	v_fmac_f32_e32 v89, v27, v90
	v_lshlrev_b32_e32 v90, 16, v102
	v_and_b32_e32 v95, 0xffff0000, v95
	v_lshlrev_b32_e32 v115, 16, v99
	v_fmac_f32_e32 v96, v21, v98
	v_fmac_f32_e32 v92, v14, v111
	v_fmac_f32_e32 v88, v11, v91
	v_fmac_f32_e32 v89, v28, v90
	v_and_b32_e32 v90, 0xffff0000, v102
	v_and_b32_e32 v99, 0xffff0000, v99
	v_fmac_f32_e32 v96, v22, v115
	v_fmac_f32_e32 v92, v15, v95
	v_add_f32_e32 v88, 0, v88
	v_fmac_f32_e32 v89, v29, v90
	v_lshlrev_b32_e32 v90, 16, v103
	v_fmac_f32_e32 v96, v23, v99
	v_add_f32_e32 v88, v88, v92
	v_fmac_f32_e32 v89, v30, v90
	v_and_b32_e32 v90, 0xffff0000, v103
	v_add_f32_e32 v88, v88, v96
	v_fmac_f32_e32 v89, v31, v90
	v_add_f32_e32 v88, v88, v89
	ds_bpermute_b32 v89, v82, v88
	s_waitcnt lgkmcnt(0)
	v_add_f32_e32 v88, v88, v89
	ds_bpermute_b32 v89, v83, v88
	s_waitcnt lgkmcnt(0)
	v_add_f32_e32 v88, v88, v89
	ds_bpermute_b32 v89, v84, v88
	s_waitcnt lgkmcnt(0)
	v_add_f32_e32 v88, v88, v89
	ds_bpermute_b32 v89, v85, v88
	s_waitcnt lgkmcnt(0)
	v_add_f32_e32 v88, v88, v89
	ds_bpermute_b32 v89, v86, v88
	s_waitcnt lgkmcnt(0)
	v_add_f32_e32 v88, v88, v89
	ds_bpermute_b32 v89, v87, v88
	s_and_saveexec_b64 s[22:23], s[4:5]
	s_cbranch_execz .LBB0_354
	s_lshl_b64 s[28:29], s[8:9], 2
	s_add_u32 s28, s24, s28
	s_addc_u32 s29, s25, s29
	s_waitcnt lgkmcnt(0)
	v_add_f32_e32 v90, v88, v89
	v_mov_b64_e32 v[88:89], s[28:29]
	global_store_dword v[88:89], v90, off

; __device__ __forceinline__ unsigned cvt_pk_bf16(float lo, float hi) { unsigned r; asm volatile("v_cvt_pk_bf16_f32 %0, %1, %2" : "=v"(r) : "v"(lo), "v"(hi)); return r; }
;     __device__ __forceinline__ void operator()(const f32x4 (&acc)[2][2][4][2], const Unit& u, int wr, int wc, int fr_, int fq_) const {
;     ...
;         const int row0 = u.pm * BM + wr * 64 + fr, col0 = u.pn * BM + wc * 32 + 4 * fq;
;         f32x4 gv[2][2], gm[2][2];
; #pragma unroll
;         for (int bj = 0; bj < 2; ++bj)
; #pragma unroll
;             for (int n = 0; n < 2; ++n) { gv[bj][n] = *(const f32x4*)(gate + col0 + bj * HALF + n * 16);
;                 if constexpr (EMIT) gm[bj][n] = *(const f32x4*)(gmv + col0 + bj * HALF + n * 16); else gm[bj][n] = gv[bj][n]; }
; #pragma unroll
;         for (int ai = 0; ai < 2; ++ai)
; #pragma unroll
;         for (int mh = 0; mh < 2; ++mh) {
;             f32x4 bs[2][2][2];
; #pragma unroll
;             for (int m = 0; m < 2; ++m) { const size_t off = (size_t)(row0 + ai * HALF + (2 * mh + m) * 16) * ldc + col0;
; #pragma unroll
;                 for (int bj = 0; bj < 2; ++bj)
; #pragma unroll
;                     for (int n = 0; n < 2; ++n) bs[m][bj][n] = *(const f32x4*)(base + off + bj * HALF + n * 16); }
;             asm volatile("" ::: "memory");
; #pragma unroll
;             for (int m = 0; m < 2; ++m) { const int row = row0 + ai * HALF + (2 * mh + m) * 16; const size_t off = (size_t)row * ldc + col0; float ss = 0.f;
; #pragma unroll
;                 for (int bj = 0; bj < 2; ++bj)
; #pragma unroll
;                     for (int n = 0; n < 2; ++n) { const f32x4 o = bs[m][bj][n] + gv[bj][n] * acc[ai][bj][2 * mh + m][n]; *(f32x4*)(out + off + bj * HALF + n * 16) = o;
;                         if constexpr (EMIT) { ss += (o[0] * o[0] + o[1] * o[1]) + (o[2] * o[2] + o[3] * o[3]); const f32x4 y = o * gm[bj][n];
;                             typedef unsigned u32x2_t __attribute__((ext_vector_type(2))); u32x2_t w; w.x = cvt_pk_bf16(y[0], y[1]); w.y = cvt_pk_bf16(y[2], y[3]); *(u32x2_t*)(A2 + off + bj * HALF + n * 16) = w; } }
;                 if constexpr (EMIT) { ss += __shfl_xor(ss, 16); ss += __shfl_xor(ss, 32); if (fq == 0) atomicAdd(ssq + row, (unsigned long long)(ss * 16777216.0f)); } }
.LBB0_500:
	v_mbcnt_lo_u32_b32 v201, -1, 0
	v_mbcnt_hi_u32_b32 v201, -1, v201
	s_lshl_b32 s5, s57, 8
	v_ashrrev_i32_e32 v64, 2, v201
	s_lshl_b32 s4, s58, 8
	s_or_b32 s5, s5, s47
	v_and_b32_e32 v64, -4, v64
	s_add_i32 s4, s4, s46
	v_add_u32_e32 v188, s5, v64
	v_ashrrev_i32_e32 v189, 31, v188
	v_and_or_b32 v192, v201, 15, s4
	v_lshlrev_b64 v[64:65], 2, v[188:189]
	v_ashrrev_i32_e32 v193, 31, v192
	v_lshl_add_u64 v[190:191], s[8:9], 0, v[64:65]
	v_lshlrev_b64 v[72:73], 13, v[192:193]
	v_lshl_add_u64 v[80:81], v[190:191], 0, v[72:73]
	v_lshl_add_u64 v[66:67], s[14:15], 0, v[64:65]
	global_load_dwordx4 v[202:205], v[80:81], off nt
	global_load_dwordx4 v[104:107], v[66:67], off nt
	global_load_dwordx4 v[92:95], v[66:67], off offset:64 nt
	global_load_dwordx4 v[206:209], v[80:81], off offset:64 nt
	global_load_dwordx4 v[210:213], v[80:81], off offset:512 nt
	global_load_dwordx4 v[84:87], v[66:67], off offset:512 nt
	global_load_dwordx4 v[72:75], v[66:67], off offset:576 nt
	global_load_dwordx4 v[214:217], v[80:81], off offset:576 nt
	v_lshl_add_u64 v[64:65], s[18:19], 0, v[64:65]
	global_load_dwordx4 v[100:103], v[64:65], off nt
	global_load_dwordx4 v[88:91], v[64:65], off offset:64 nt
	global_load_dwordx4 v[80:83], v[64:65], off offset:512 nt
	s_nop 0
	global_load_dwordx4 v[64:67], v[64:65], off offset:576 nt
	v_or_b32_e32 v194, 16, v192
	v_ashrrev_i32_e32 v195, 31, v194
	v_lshlrev_b64 v[160:161], 13, v[194:195]
	v_lshl_add_u64 v[160:161], v[190:191], 0, v[160:161]
	global_load_dwordx4 v[172:175], v[160:161], off nt
	global_load_dwordx4 v[168:171], v[160:161], off offset:64 nt
	global_load_dwordx4 v[164:167], v[160:161], off offset:512 nt
	s_nop 0
	global_load_dwordx4 v[160:163], v[160:161], off offset:576 nt
	v_and_b32_e32 v219, 64, v200
	v_xor_b32_e32 v218, 16, v200
	v_cmp_gt_u32_e32 vcc, 16, v201
	v_add_u32_e32 v201, 64, v219
	v_cmp_lt_i32_e64 s[4:5], v218, v201
	s_waitcnt vmcnt(0) lgkmcnt(0)
	v_pk_fma_f32 v[158:159], v[158:159], v[106:107], v[204:205]
	v_cndmask_b32_e64 v222, v200, v218, s[4:5]
	v_lshlrev_b64 v[218:219], 11, v[192:193]
	v_lshl_add_u64 v[218:219], v[218:219], 0, v[188:189]
	v_lshl_add_u64 v[220:221], v[218:219], 2, s[10:11]
	v_pk_fma_f32 v[156:157], v[156:157], v[104:105], v[202:203]
	v_pk_fma_f32 v[154:155], v[154:155], v[94:95], v[208:209]
	v_pk_fma_f32 v[152:153], v[152:153], v[92:93], v[206:207]
	v_pk_fma_f32 v[150:151], v[150:151], v[86:87], v[212:213]
	v_pk_fma_f32 v[148:149], v[148:149], v[84:85], v[210:211]
	v_pk_fma_f32 v[204:205], v[146:147], v[74:75], v[216:217]
	v_pk_fma_f32 v[202:203], v[144:145], v[72:73], v[214:215]
	global_store_dwordx4 v[220:221], v[156:159], off
	v_mul_f32_e32 v214, v157, v157
	v_mul_f32_e32 v215, v159, v159
	v_pk_mul_f32 v[144:145], v[102:103], v[158:159]
	v_pk_mul_f32 v[146:147], v[100:101], v[156:157]
	v_mul_f32_e32 v157, v153, v153
	v_mul_f32_e32 v159, v155, v155
	v_lshl_add_u64 v[218:219], v[218:219], 1, s[16:17]
	v_mul_f32_e32 v216, v149, v149
	v_mul_f32_e32 v217, v151, v151
	v_fmac_f32_e32 v214, v156, v156
	v_fmac_f32_e32 v215, v158, v158
	v_cvt_pk_bf16_f32 v146, v146, v147
	v_cvt_pk_bf16_f32 v147, v144, v145
	v_fmac_f32_e32 v157, v152, v152
	v_fmac_f32_e32 v159, v154, v154
	v_mul_f32_e32 v223, v203, v203
	v_mul_f32_e32 v224, v205, v205
	v_fmac_f32_e32 v216, v148, v148
	v_fmac_f32_e32 v217, v150, v150
	v_add_f32_e32 v156, v214, v215
	global_store_dwordx2 v[218:219], v[146:147], off
	global_store_dwordx4 v[220:221], v[152:155], off offset:64
	v_add_f32_e32 v146, v157, v159
	v_pk_mul_f32 v[206:207], v[90:91], v[154:155]
	v_pk_mul_f32 v[208:209], v[88:89], v[152:153]
	v_fmac_f32_e32 v223, v202, v202
	v_fmac_f32_e32 v224, v204, v204
	v_cvt_pk_bf16_f32 v144, v208, v209
	v_cvt_pk_bf16_f32 v145, v206, v207
	v_add_f32_e32 v147, v216, v217
	v_add_f32_e32 v146, v156, v146
	v_add_f32_e32 v152, v223, v224
	global_store_dwordx2 v[218:219], v[144:145], off offset:32
	global_store_dwordx4 v[220:221], v[148:151], off offset:512
	v_add_f32_e32 v145, v146, v147
	v_pk_mul_f32 v[212:213], v[80:81], v[148:149]
	v_add_f32_e32 v149, v145, v152
	v_lshlrev_b32_e32 v148, 2, v222
	v_pk_mul_f32 v[210:211], v[82:83], v[150:151]
	ds_bpermute_b32 v150, v148, v149
	v_cvt_pk_bf16_f32 v144, v212, v213
	v_cvt_pk_bf16_f32 v145, v210, v211
	global_store_dwordx2 v[218:219], v[144:145], off offset:256
	global_store_dwordx4 v[220:221], v[202:205], off offset:576
	v_xor_b32_e32 v145, 32, v200
	v_cmp_lt_i32_e64 s[4:5], v145, v201
	s_waitcnt lgkmcnt(0)
	v_add_f32_e32 v144, v149, v150
	v_pk_mul_f32 v[150:151], v[64:65], v[202:203]
	v_cndmask_b32_e64 v145, v200, v145, s[4:5]
	v_lshlrev_b32_e32 v149, 2, v145
	ds_bpermute_b32 v145, v149, v144
	v_pk_mul_f32 v[146:147], v[66:67], v[204:205]
	v_cvt_pk_bf16_f32 v150, v150, v151
	s_nop 0
	v_cvt_pk_bf16_f32 v151, v146, v147
	global_store_dwordx2 v[218:219], v[150:151], off offset:288
	s_and_saveexec_b64 s[4:5], vcc
	s_cbranch_execz .LBB0_502
	s_waitcnt lgkmcnt(0)
	v_add_f32_e32 v144, v144, v145
	v_mul_f32_e32 v144, 0x4b800000, v144
	v_trunc_f32_e32 v144, v144
	v_mul_f32_e32 v145, 0x2f800000, v144
	v_floor_f32_e32 v145, v145
	v_fmac_f32_e32 v144, 0xcf800000, v145
	v_cvt_u32_f32_e32 v144, v144
	v_cvt_u32_f32_e32 v145, v145
	v_mov_b32_e32 v226, v144
	v_mov_b32_e32 v227, v145
	v_lshl_add_u64 v[242:243], v[192:193], 3, s[20:21]

; __device__ __forceinline__ unsigned cvt_pk_bf16(float lo, float hi) { unsigned r; asm volatile("v_cvt_pk_bf16_f32 %0, %1, %2" : "=v"(r) : "v"(lo), "v"(hi)); return r; }
;     __device__ __forceinline__ void operator()(const f32x4 (&acc)[2][2][4][2], const Unit& u, int wr, int wc, int fr_, int fq_) const {
;     ...
;         for (int mh = 0; mh < 2; ++mh) {
;             f32x4 bs[2][2][2];
; #pragma unroll
;             for (int m = 0; m < 2; ++m) { const size_t off = (size_t)(row0 + ai * HALF + (2 * mh + m) * 16) * ldc + col0;
; #pragma unroll
;                 for (int bj = 0; bj < 2; ++bj)
; #pragma unroll
;                     for (int n = 0; n < 2; ++n) bs[m][bj][n] = *(const f32x4*)(base + off + bj * HALF + n * 16); }
;             asm volatile("" ::: "memory");
; #pragma unroll
;             for (int m = 0; m < 2; ++m) { const int row = row0 + ai * HALF + (2 * mh + m) * 16; const size_t off = (size_t)row * ldc + col0; float ss = 0.f;
; #pragma unroll
;                 for (int bj = 0; bj < 2; ++bj)
; #pragma unroll
;                     for (int n = 0; n < 2; ++n) { const f32x4 o = bs[m][bj][n] + gv[bj][n] * acc[ai][bj][2 * mh + m][n]; *(f32x4*)(out + off + bj * HALF + n * 16) = o;
;                         if constexpr (EMIT) { ss += (o[0] * o[0] + o[1] * o[1]) + (o[2] * o[2] + o[3] * o[3]); const f32x4 y = o * gm[bj][n];
;                             typedef unsigned u32x2_t __attribute__((ext_vector_type(2))); u32x2_t w; w.x = cvt_pk_bf16(y[0], y[1]); w.y = cvt_pk_bf16(y[2], y[3]); *(u32x2_t*)(A2 + off + bj * HALF + n * 16) = w; } }
;                 if constexpr (EMIT) { ss += __shfl_xor(ss, 16); ss += __shfl_xor(ss, 32); if (fq == 0) atomicAdd(ssq + row, (unsigned long long)(ss * 16777216.0f)); } }
.LBB0_504:
	s_or_b64 exec, exec, s[4:5]
	v_or_b32_e32 v146, 32, v192
	v_ashrrev_i32_e32 v147, 31, v146
	s_waitcnt lgkmcnt(0)
	v_lshlrev_b64 v[128:129], 13, v[146:147]
	v_lshl_add_u64 v[128:129], v[190:191], 0, v[128:129]
	global_load_dwordx4 v[150:153], v[128:129], off nt
	global_load_dwordx4 v[154:157], v[128:129], off offset:64 nt
	global_load_dwordx4 v[158:161], v[128:129], off offset:512 nt
	global_load_dwordx4 v[162:165], v[128:129], off offset:576 nt
	v_or_b32_e32 v144, 48, v192
	v_ashrrev_i32_e32 v145, 31, v144
	v_lshlrev_b64 v[128:129], 13, v[144:145]
	v_lshl_add_u64 v[128:129], v[190:191], 0, v[128:129]
	global_load_dwordx4 v[140:143], v[128:129], off nt
	global_load_dwordx4 v[136:139], v[128:129], off offset:64 nt
	global_load_dwordx4 v[132:135], v[128:129], off offset:512 nt
	s_nop 0
	global_load_dwordx4 v[128:131], v[128:129], off offset:576 nt
	v_lshlrev_b64 v[166:167], 11, v[146:147]
	v_lshl_add_u64 v[166:167], v[166:167], 0, v[188:189]
	v_lshl_add_u64 v[168:169], v[166:167], 2, s[10:11]
	v_lshl_add_u64 v[166:167], v[166:167], 1, s[16:17]
	s_waitcnt vmcnt(0) lgkmcnt(0)
	v_pk_fma_f32 v[126:127], v[126:127], v[106:107], v[152:153]
	v_pk_fma_f32 v[124:125], v[124:125], v[104:105], v[150:151]
	v_pk_fma_f32 v[122:123], v[122:123], v[94:95], v[156:157]
	v_pk_fma_f32 v[120:121], v[120:121], v[92:93], v[154:155]
	v_pk_fma_f32 v[118:119], v[118:119], v[86:87], v[160:161]
	v_pk_fma_f32 v[116:117], v[116:117], v[84:85], v[158:159]
	v_pk_fma_f32 v[152:153], v[114:115], v[74:75], v[164:165]
	v_pk_fma_f32 v[150:151], v[112:113], v[72:73], v[162:163]
	global_store_dwordx4 v[168:169], v[124:127], off
	v_mul_f32_e32 v162, v125, v125
	v_mul_f32_e32 v163, v127, v127
	v_pk_mul_f32 v[112:113], v[102:103], v[126:127]
	v_pk_mul_f32 v[114:115], v[100:101], v[124:125]
	v_mul_f32_e32 v125, v121, v121
	v_mul_f32_e32 v127, v123, v123
	v_mul_f32_e32 v164, v117, v117
	v_mul_f32_e32 v165, v119, v119
	v_fmac_f32_e32 v162, v124, v124
	v_fmac_f32_e32 v163, v126, v126
	v_cvt_pk_bf16_f32 v114, v114, v115
	v_cvt_pk_bf16_f32 v115, v112, v113
	v_fmac_f32_e32 v125, v120, v120
	v_fmac_f32_e32 v127, v122, v122
	v_mul_f32_e32 v170, v151, v151
	v_mul_f32_e32 v171, v153, v153
	v_fmac_f32_e32 v164, v116, v116
	v_fmac_f32_e32 v165, v118, v118
	v_add_f32_e32 v124, v162, v163
	global_store_dwordx2 v[166:167], v[114:115], off
	global_store_dwordx4 v[168:169], v[120:123], off offset:64
	v_add_f32_e32 v114, v125, v127
	v_pk_mul_f32 v[154:155], v[90:91], v[122:123]
	v_pk_mul_f32 v[156:157], v[88:89], v[120:121]
	v_fmac_f32_e32 v170, v150, v150
	v_fmac_f32_e32 v171, v152, v152
	v_cvt_pk_bf16_f32 v112, v156, v157
	v_cvt_pk_bf16_f32 v113, v154, v155
	v_add_f32_e32 v115, v164, v165
	v_add_f32_e32 v114, v124, v114
	global_store_dwordx2 v[166:167], v[112:113], off offset:32
	global_store_dwordx4 v[168:169], v[116:119], off offset:512
	v_add_f32_e32 v113, v114, v115
	v_add_f32_e32 v114, v170, v171
	v_pk_mul_f32 v[160:161], v[80:81], v[116:117]
	v_add_f32_e32 v116, v113, v114
	ds_bpermute_b32 v117, v148, v116
	v_pk_mul_f32 v[158:159], v[82:83], v[118:119]
	v_cvt_pk_bf16_f32 v112, v160, v161
	v_pk_mul_f32 v[114:115], v[66:67], v[152:153]
	v_cvt_pk_bf16_f32 v113, v158, v159
	global_store_dwordx2 v[166:167], v[112:113], off offset:256
	global_store_dwordx4 v[168:169], v[150:153], off offset:576
	s_waitcnt lgkmcnt(0)
	v_add_f32_e32 v112, v116, v117
	ds_bpermute_b32 v113, v149, v112
	v_pk_mul_f32 v[116:117], v[64:65], v[150:151]
	s_nop 0
	v_cvt_pk_bf16_f32 v116, v116, v117
	v_cvt_pk_bf16_f32 v117, v114, v115
	global_store_dwordx2 v[166:167], v[116:117], off offset:288
	s_and_saveexec_b64 s[4:5], vcc
	s_cbranch_execz .LBB0_506
	s_waitcnt lgkmcnt(0)
	v_add_f32_e32 v112, v112, v113
	v_mul_f32_e32 v112, 0x4b800000, v112
	v_trunc_f32_e32 v112, v112
	v_mul_f32_e32 v113, 0x2f800000, v112
	v_floor_f32_e32 v113, v113
	v_fmac_f32_e32 v112, 0xcf800000, v113
	v_cvt_u32_f32_e32 v112, v112
	v_cvt_u32_f32_e32 v113, v113
	v_mov_b32_e32 v230, v112
	v_mov_b32_e32 v231, v113

; __device__ __forceinline__ unsigned cvt_pk_bf16(float lo, float hi) { unsigned r; asm volatile("v_cvt_pk_bf16_f32 %0, %1, %2" : "=v"(r) : "v"(lo), "v"(hi)); return r; }
;     __device__ __forceinline__ void operator()(const f32x4 (&acc)[2][2][4][2], const Unit& u, int wr, int wc, int fr_, int fq_) const {
;     ...
;         for (int mh = 0; mh < 2; ++mh) {
;             f32x4 bs[2][2][2];
; #pragma unroll
;             for (int m = 0; m < 2; ++m) { const size_t off = (size_t)(row0 + ai * HALF + (2 * mh + m) * 16) * ldc + col0;
; #pragma unroll
;                 for (int bj = 0; bj < 2; ++bj)
; #pragma unroll
;                     for (int n = 0; n < 2; ++n) bs[m][bj][n] = *(const f32x4*)(base + off + bj * HALF + n * 16); }
;             asm volatile("" ::: "memory");
; #pragma unroll
;             for (int m = 0; m < 2; ++m) { const int row = row0 + ai * HALF + (2 * mh + m) * 16; const size_t off = (size_t)row * ldc + col0; float ss = 0.f;
; #pragma unroll
;                 for (int bj = 0; bj < 2; ++bj)
; #pragma unroll
;                     for (int n = 0; n < 2; ++n) { const f32x4 o = bs[m][bj][n] + gv[bj][n] * acc[ai][bj][2 * mh + m][n]; *(f32x4*)(out + off + bj * HALF + n * 16) = o;
;                         if constexpr (EMIT) { ss += (o[0] * o[0] + o[1] * o[1]) + (o[2] * o[2] + o[3] * o[3]); const f32x4 y = o * gm[bj][n];
;                             typedef unsigned u32x2_t __attribute__((ext_vector_type(2))); u32x2_t w; w.x = cvt_pk_bf16(y[0], y[1]); w.y = cvt_pk_bf16(y[2], y[3]); *(u32x2_t*)(A2 + off + bj * HALF + n * 16) = w; } }
;                 if constexpr (EMIT) { ss += __shfl_xor(ss, 16); ss += __shfl_xor(ss, 32); if (fq == 0) atomicAdd(ssq + row, (unsigned long long)(ss * 16777216.0f)); } }
.LBB0_508:
	s_or_b64 exec, exec, s[4:5]
	v_add_u32_e32 v114, 0x80, v192
	v_ashrrev_i32_e32 v115, 31, v114
	s_waitcnt lgkmcnt(0)
	v_lshlrev_b64 v[68:69], 13, v[114:115]
	v_lshl_add_u64 v[68:69], v[190:191], 0, v[68:69]
	global_load_dwordx4 v[116:119], v[68:69], off nt
	global_load_dwordx4 v[120:123], v[68:69], off offset:64 nt
	global_load_dwordx4 v[124:127], v[68:69], off offset:512 nt
	global_load_dwordx4 v[128:131], v[68:69], off offset:576 nt
	v_add_u32_e32 v112, 0x90, v192
	v_ashrrev_i32_e32 v113, 31, v112
	v_lshlrev_b64 v[68:69], 13, v[112:113]
	v_lshl_add_u64 v[68:69], v[190:191], 0, v[68:69]
	global_load_dwordx4 v[108:111], v[68:69], off nt
	global_load_dwordx4 v[96:99], v[68:69], off offset:64 nt
	global_load_dwordx4 v[76:79], v[68:69], off offset:512 nt
	s_nop 0
	global_load_dwordx4 v[68:71], v[68:69], off offset:576 nt
	v_lshlrev_b64 v[132:133], 11, v[114:115]
	v_lshl_add_u64 v[132:133], v[132:133], 0, v[188:189]
	v_lshl_add_u64 v[134:135], v[132:133], 2, s[10:11]
	v_lshl_add_u64 v[132:133], v[132:133], 1, s[16:17]
	s_waitcnt vmcnt(0) lgkmcnt(0)
	v_pk_fma_f32 v[62:63], v[62:63], v[106:107], v[118:119]
	v_pk_fma_f32 v[60:61], v[60:61], v[104:105], v[116:117]
	v_pk_fma_f32 v[58:59], v[58:59], v[94:95], v[122:123]
	v_pk_fma_f32 v[56:57], v[56:57], v[92:93], v[120:121]
	v_pk_fma_f32 v[54:55], v[54:55], v[86:87], v[126:127]
	v_pk_fma_f32 v[52:53], v[52:53], v[84:85], v[124:125]
	v_pk_fma_f32 v[118:119], v[50:51], v[74:75], v[130:131]
	v_pk_fma_f32 v[116:117], v[48:49], v[72:73], v[128:129]
	global_store_dwordx4 v[134:135], v[60:63], off
	v_mul_f32_e32 v128, v61, v61
	v_mul_f32_e32 v129, v63, v63
	v_pk_mul_f32 v[48:49], v[102:103], v[62:63]
	v_pk_mul_f32 v[50:51], v[100:101], v[60:61]
	v_mul_f32_e32 v61, v57, v57
	v_mul_f32_e32 v63, v59, v59
	v_mul_f32_e32 v130, v53, v53
	v_mul_f32_e32 v131, v55, v55
	v_fmac_f32_e32 v128, v60, v60
	v_fmac_f32_e32 v129, v62, v62
	v_cvt_pk_bf16_f32 v50, v50, v51
	v_cvt_pk_bf16_f32 v51, v48, v49
	v_fmac_f32_e32 v61, v56, v56
	v_fmac_f32_e32 v63, v58, v58
	v_mul_f32_e32 v136, v117, v117
	v_mul_f32_e32 v137, v119, v119
	v_fmac_f32_e32 v130, v52, v52
	v_fmac_f32_e32 v131, v54, v54
	v_add_f32_e32 v60, v128, v129
	global_store_dwordx2 v[132:133], v[50:51], off
	global_store_dwordx4 v[134:135], v[56:59], off offset:64
	v_add_f32_e32 v50, v61, v63
	v_pk_mul_f32 v[120:121], v[90:91], v[58:59]
	v_pk_mul_f32 v[122:123], v[88:89], v[56:57]
	v_fmac_f32_e32 v136, v116, v116
	v_fmac_f32_e32 v137, v118, v118
	v_cvt_pk_bf16_f32 v48, v122, v123
	v_cvt_pk_bf16_f32 v49, v120, v121
	v_add_f32_e32 v51, v130, v131
	v_add_f32_e32 v50, v60, v50
	global_store_dwordx2 v[132:133], v[48:49], off offset:32
	global_store_dwordx4 v[134:135], v[52:55], off offset:512
	v_add_f32_e32 v49, v50, v51
	v_add_f32_e32 v50, v136, v137
	v_pk_mul_f32 v[126:127], v[80:81], v[52:53]
	v_add_f32_e32 v52, v49, v50
	ds_bpermute_b32 v53, v148, v52
	v_pk_mul_f32 v[124:125], v[82:83], v[54:55]
	v_cvt_pk_bf16_f32 v48, v126, v127
	v_pk_mul_f32 v[50:51], v[66:67], v[118:119]
	v_cvt_pk_bf16_f32 v49, v124, v125
	global_store_dwordx2 v[132:133], v[48:49], off offset:256
	global_store_dwordx4 v[134:135], v[116:119], off offset:576
	s_waitcnt lgkmcnt(0)
	v_add_f32_e32 v48, v52, v53
	ds_bpermute_b32 v49, v149, v48
	v_pk_mul_f32 v[52:53], v[64:65], v[116:117]
	s_nop 0
	v_cvt_pk_bf16_f32 v52, v52, v53
	v_cvt_pk_bf16_f32 v53, v50, v51
	global_store_dwordx2 v[132:133], v[52:53], off offset:288
	s_and_saveexec_b64 s[4:5], vcc
	s_cbranch_execz .LBB0_510
	s_waitcnt lgkmcnt(0)
	v_add_f32_e32 v48, v48, v49
	v_mul_f32_e32 v48, 0x4b800000, v48
	v_trunc_f32_e32 v48, v48
	v_mul_f32_e32 v49, 0x2f800000, v48
	v_floor_f32_e32 v49, v49
	v_fmac_f32_e32 v48, 0xcf800000, v49
	v_cvt_u32_f32_e32 v48, v48
	v_cvt_u32_f32_e32 v49, v49
	v_mov_b32_e32 v234, v48
	v_mov_b32_e32 v235, v49

; __device__ __forceinline__ unsigned cvt_pk_bf16(float lo, float hi) { unsigned r; asm volatile("v_cvt_pk_bf16_f32 %0, %1, %2" : "=v"(r) : "v"(lo), "v"(hi)); return r; }
;     __device__ __forceinline__ void operator()(const f32x4 (&acc)[2][2][4][2], const Unit& u, int wr, int wc, int fr_, int fq_) const {
;     ...
;         for (int mh = 0; mh < 2; ++mh) {
;             f32x4 bs[2][2][2];
; #pragma unroll
;             for (int m = 0; m < 2; ++m) { const size_t off = (size_t)(row0 + ai * HALF + (2 * mh + m) * 16) * ldc + col0;
; #pragma unroll
;                 for (int bj = 0; bj < 2; ++bj)
; #pragma unroll
;                     for (int n = 0; n < 2; ++n) bs[m][bj][n] = *(const f32x4*)(base + off + bj * HALF + n * 16); }
;             asm volatile("" ::: "memory");
; #pragma unroll
;             for (int m = 0; m < 2; ++m) { const int row = row0 + ai * HALF + (2 * mh + m) * 16; const size_t off = (size_t)row * ldc + col0; float ss = 0.f;
; #pragma unroll
;                 for (int bj = 0; bj < 2; ++bj)
; #pragma unroll
;                     for (int n = 0; n < 2; ++n) { const f32x4 o = bs[m][bj][n] + gv[bj][n] * acc[ai][bj][2 * mh + m][n]; *(f32x4*)(out + off + bj * HALF + n * 16) = o;
;                         if constexpr (EMIT) { ss += (o[0] * o[0] + o[1] * o[1]) + (o[2] * o[2] + o[3] * o[3]); const f32x4 y = o * gm[bj][n];
;                             typedef unsigned u32x2_t __attribute__((ext_vector_type(2))); u32x2_t w; w.x = cvt_pk_bf16(y[0], y[1]); w.y = cvt_pk_bf16(y[2], y[3]); *(u32x2_t*)(A2 + off + bj * HALF + n * 16) = w; } }
;                 if constexpr (EMIT) { ss += __shfl_xor(ss, 16); ss += __shfl_xor(ss, 32); if (fq == 0) atomicAdd(ssq + row, (unsigned long long)(ss * 16777216.0f)); } }
.LBB0_512:
	s_or_b64 exec, exec, s[4:5]
	v_add_u32_e32 v50, 0xa0, v192
	v_ashrrev_i32_e32 v51, 31, v50
	s_waitcnt lgkmcnt(0)
	v_lshlrev_b64 v[32:33], 13, v[50:51]
	v_lshl_add_u64 v[32:33], v[190:191], 0, v[32:33]
	global_load_dwordx4 v[52:55], v[32:33], off nt
	global_load_dwordx4 v[56:59], v[32:33], off offset:64 nt
	global_load_dwordx4 v[60:63], v[32:33], off offset:512 nt
	global_load_dwordx4 v[68:71], v[32:33], off offset:576 nt
	v_add_u32_e32 v48, 0xb0, v192
	v_ashrrev_i32_e32 v49, 31, v48
	v_lshlrev_b64 v[32:33], 13, v[48:49]
	v_lshl_add_u64 v[32:33], v[190:191], 0, v[32:33]
	global_load_dwordx4 v[44:47], v[32:33], off nt
	global_load_dwordx4 v[40:43], v[32:33], off offset:64 nt
	global_load_dwordx4 v[36:39], v[32:33], off offset:512 nt
	s_nop 0
	global_load_dwordx4 v[32:35], v[32:33], off offset:576 nt
	v_lshlrev_b64 v[76:77], 11, v[50:51]
	v_lshl_add_u64 v[76:77], v[76:77], 0, v[188:189]
	v_lshl_add_u64 v[78:79], v[76:77], 2, s[10:11]
	v_lshl_add_u64 v[76:77], v[76:77], 1, s[16:17]
	s_waitcnt vmcnt(0) lgkmcnt(0)
	v_pk_fma_f32 v[30:31], v[30:31], v[106:107], v[54:55]
	v_pk_fma_f32 v[28:29], v[28:29], v[104:105], v[52:53]
	v_pk_fma_f32 v[26:27], v[26:27], v[94:95], v[58:59]
	v_pk_fma_f32 v[24:25], v[24:25], v[92:93], v[56:57]
	v_pk_fma_f32 v[22:23], v[22:23], v[86:87], v[62:63]
	v_pk_fma_f32 v[20:21], v[20:21], v[84:85], v[60:61]
	v_pk_fma_f32 v[54:55], v[18:19], v[74:75], v[70:71]
	v_pk_fma_f32 v[52:53], v[16:17], v[72:73], v[68:69]
	global_store_dwordx4 v[78:79], v[28:31], off
	v_mul_f32_e32 v68, v29, v29
	v_mul_f32_e32 v69, v31, v31
	v_pk_mul_f32 v[16:17], v[102:103], v[30:31]
	v_pk_mul_f32 v[18:19], v[100:101], v[28:29]
	v_mul_f32_e32 v29, v25, v25
	v_mul_f32_e32 v31, v27, v27
	v_mul_f32_e32 v70, v21, v21
	v_mul_f32_e32 v71, v23, v23
	v_fmac_f32_e32 v68, v28, v28
	v_fmac_f32_e32 v69, v30, v30
	v_cvt_pk_bf16_f32 v18, v18, v19
	v_cvt_pk_bf16_f32 v19, v16, v17
	v_fmac_f32_e32 v29, v24, v24
	v_fmac_f32_e32 v31, v26, v26
	v_mul_f32_e32 v96, v53, v53
	v_mul_f32_e32 v97, v55, v55
	v_fmac_f32_e32 v70, v20, v20
	v_fmac_f32_e32 v71, v22, v22
	v_add_f32_e32 v28, v68, v69
	global_store_dwordx2 v[76:77], v[18:19], off
	global_store_dwordx4 v[78:79], v[24:27], off offset:64
	v_add_f32_e32 v18, v29, v31
	v_pk_mul_f32 v[56:57], v[90:91], v[26:27]
	v_pk_mul_f32 v[58:59], v[88:89], v[24:25]
	v_fmac_f32_e32 v96, v52, v52
	v_fmac_f32_e32 v97, v54, v54
	v_cvt_pk_bf16_f32 v16, v58, v59
	v_cvt_pk_bf16_f32 v17, v56, v57
	v_add_f32_e32 v19, v70, v71
	v_add_f32_e32 v18, v28, v18
	global_store_dwordx2 v[76:77], v[16:17], off offset:32
	global_store_dwordx4 v[78:79], v[20:23], off offset:512
	v_add_f32_e32 v17, v18, v19
	v_add_f32_e32 v18, v96, v97
	v_pk_mul_f32 v[62:63], v[80:81], v[20:21]
	v_add_f32_e32 v20, v17, v18
	ds_bpermute_b32 v21, v148, v20
	v_pk_mul_f32 v[60:61], v[82:83], v[22:23]
	v_cvt_pk_bf16_f32 v16, v62, v63
	v_pk_mul_f32 v[18:19], v[66:67], v[54:55]
	v_cvt_pk_bf16_f32 v17, v60, v61
	global_store_dwordx2 v[76:77], v[16:17], off offset:256
	global_store_dwordx4 v[78:79], v[52:55], off offset:576
	s_waitcnt lgkmcnt(0)
	v_add_f32_e32 v16, v20, v21
	ds_bpermute_b32 v17, v149, v16
	v_pk_mul_f32 v[20:21], v[64:65], v[52:53]
	s_nop 0
	v_cvt_pk_bf16_f32 v20, v20, v21
	v_cvt_pk_bf16_f32 v21, v18, v19
	global_store_dwordx2 v[76:77], v[20:21], off offset:288
	s_and_saveexec_b64 s[4:5], vcc
	s_cbranch_execz .LBB0_514
	s_waitcnt lgkmcnt(0)
	v_add_f32_e32 v16, v16, v17
	v_mul_f32_e32 v16, 0x4b800000, v16
	v_trunc_f32_e32 v16, v16
	v_mul_f32_e32 v17, 0x2f800000, v16
	v_floor_f32_e32 v17, v17
	v_fmac_f32_e32 v16, 0xcf800000, v17
	v_cvt_u32_f32_e32 v16, v16
	v_cvt_u32_f32_e32 v17, v17
	v_mov_b32_e32 v238, v16
	v_mov_b32_e32 v239, v17

; __device__ __forceinline__ int lane_asm() { int l; asm volatile("v_mbcnt_lo_u32_b32 %0, -1, 0\n\tv_mbcnt_hi_u32_b32 %0, -1, %0" : "=v"(l)); return l; }
; #define INP(k) ((const float*)ldptr(L, (k)))
; __global__ void __launch_bounds__(NTHR, 2) mk_fwd(Args args) {
;     ...
;     if (IN(11)) { const int lane = lane_asm(), tid = wave * 64 + lane; (void)tid;
;         const float s1 = wave_sum((INP(13))[lane] * (INP(14))[lane]), s2 = wave_sum((INP(15))[lane] * (INP(16))[lane]);
;         const float lam_init = 0.2f, lam = expf(s1) - expf(s2) + lam_init;
;         float subln[16], ogn[16];
;         { const float* sp_ = INP(17) + (lane & 7) * 16; const float* gp_ = INP(28) + lane * 16;
; #pragma unroll
;           for (int i = 0; i < 16; ++i) { subln[i] = sp_[i]; ogn[i] = gp_[i]; } }
;         for (int row = gw; row < M; row += 2 * NGW) {
.LBB0_1232:
	s_cmp_lt_i32 s68, 12
	s_cselect_b64 s[0:1], -1, 0
	s_and_b64 s[8:9], s[0:1], s[34:35]
	s_andn2_b64 vcc, exec, s[8:9]
	s_cbranch_vccnz .LBB0_1236
	s_add_i32 s0, 0, 0x20068
	v_mov_b32_e32 v0, s0
	v_mbcnt_lo_u32_b32 v16, -1, 0
	v_mbcnt_hi_u32_b32 v16, -1, v16
	s_waitcnt lgkmcnt(0)
	ds_read2_b64 v[0:3], v0 offset1:1
	s_add_i32 s0, 0, 0x20078
	v_mov_b32_e32 v4, s0
	ds_read2_b64 v[4:7], v4 offset1:1
	v_ashrrev_i32_e32 v17, 31, v16
	s_waitcnt lgkmcnt(0)
	v_readfirstlane_b32 s0, v0
	v_readfirstlane_b32 s1, v1
	v_lshlrev_b64 v[0:1], 2, v[16:17]
	s_nop 0
	v_lshl_add_u64 v[8:9], s[0:1], 0, v[0:1]
	v_readfirstlane_b32 s0, v2
	v_readfirstlane_b32 s1, v3
	global_load_dword v8, v[8:9], off
	s_nop 0
	v_lshl_add_u64 v[2:3], s[0:1], 0, v[0:1]
	v_readfirstlane_b32 s0, v4
	v_readfirstlane_b32 s1, v5
	global_load_dword v9, v[2:3], off
	s_nop 0
	v_lshl_add_u64 v[2:3], s[0:1], 0, v[0:1]
	v_readfirstlane_b32 s0, v6
	v_readfirstlane_b32 s1, v7
	global_load_dword v4, v[2:3], off
	s_nop 0
	v_lshl_add_u64 v[0:1], s[0:1], 0, v[0:1]
	global_load_dword v5, v[0:1], off
	v_mbcnt_lo_u32_b32 v0, -1, 0
	v_mbcnt_hi_u32_b32 v6, -1, v0
	v_and_b32_e32 v7, 64, v6
	v_xor_b32_e32 v10, 1, v6
	v_add_u32_e32 v7, 64, v7
	v_cmp_lt_i32_e32 vcc, v10, v7
	v_xor_b32_e32 v11, 2, v6
	v_xor_b32_e32 v12, 4, v6
	v_cndmask_b32_e32 v10, v6, v10, vcc
	v_lshlrev_b32_e32 v130, 2, v10
	v_cmp_lt_i32_e32 vcc, v11, v7
	v_xor_b32_e32 v13, 8, v6
	v_xor_b32_e32 v14, 16, v6
	v_cndmask_b32_e32 v11, v6, v11, vcc
	v_lshlrev_b32_e32 v131, 2, v11
	v_cmp_lt_i32_e32 vcc, v12, v7
	v_xor_b32_e32 v15, 32, v6
	s_add_i32 s0, 0, 0x20088
	s_add_i32 s1, 0, 0x200e0
	v_mov_b32_e32 v0, s0
	v_mov_b32_e32 v2, s1
	ds_read_b64 v[0:1], v0
	ds_read_b64 v[2:3], v2
	s_cmpk_gt_i32 s72, 0x3fff
	s_waitcnt lgkmcnt(0)
	v_readfirstlane_b32 s0, v0
	v_readfirstlane_b32 s1, v1
	v_readfirstlane_b32 s3, v2
	v_readfirstlane_b32 s4, v3
	s_waitcnt vmcnt(0)
	v_mul_f32_e32 v10, v8, v9
	ds_bpermute_b32 v10, v130, v10
	s_waitcnt lgkmcnt(0)
	v_fmac_f32_e32 v10, v8, v9
	v_cndmask_b32_e32 v8, v6, v12, vcc
	v_mul_f32_e32 v17, v4, v5
	ds_bpermute_b32 v17, v130, v17
	v_lshlrev_b32_e32 v132, 2, v8
	v_cmp_lt_i32_e32 vcc, v13, v7
	s_waitcnt lgkmcnt(0)
	v_fmac_f32_e32 v17, v4, v5
	ds_bpermute_b32 v4, v131, v10
	ds_bpermute_b32 v5, v131, v17
	s_waitcnt lgkmcnt(1)
	v_add_f32_e32 v4, v10, v4
	s_waitcnt lgkmcnt(0)
	v_add_f32_e32 v5, v17, v5
	ds_bpermute_b32 v8, v132, v4
	ds_bpermute_b32 v9, v132, v5
	v_cndmask_b32_e32 v10, v6, v13, vcc
	v_lshlrev_b32_e32 v133, 2, v10
	v_cmp_lt_i32_e32 vcc, v14, v7
	s_waitcnt lgkmcnt(1)
	v_add_f32_e32 v4, v4, v8
	s_waitcnt lgkmcnt(0)
	v_add_f32_e32 v5, v5, v9
	ds_bpermute_b32 v8, v133, v4
	ds_bpermute_b32 v9, v133, v5
	v_cndmask_b32_e32 v10, v6, v14, vcc
	v_lshlrev_b32_e32 v134, 2, v10
	v_cmp_lt_i32_e32 vcc, v15, v7
	s_waitcnt lgkmcnt(1)
	v_add_f32_e32 v4, v4, v8
	s_waitcnt lgkmcnt(0)
	v_add_f32_e32 v5, v5, v9
	ds_bpermute_b32 v8, v134, v4
	ds_bpermute_b32 v9, v134, v5
	v_cndmask_b32_e32 v6, v6, v15, vcc
	v_lshlrev_b32_e32 v135, 2, v6
	s_waitcnt lgkmcnt(1)
	v_add_f32_e32 v34, v4, v8
	s_waitcnt lgkmcnt(0)
	v_add_f32_e32 v32, v5, v9
	ds_bpermute_b32 v35, v135, v34
	ds_bpermute_b32 v33, v135, v32
	s_cbranch_scc1 .LBB0_1236
	v_lshlrev_b32_e32 v0, 6, v16
	v_lshlrev_b32_e32 v38, 4, v16
	v_and_b32_e32 v0, 0x1c0, v0
	v_mov_b32_e32 v1, 0
	v_mov_b32_e32 v16, s3
	v_mov_b32_e32 v17, s4
	v_ashrrev_i32_e32 v39, 31, v38
	v_lshl_add_u64 v[18:19], s[0:1], 0, v[0:1]
	v_lshl_add_u64 v[36:37], v[38:39], 2, v[16:17]
	global_load_dwordx4 v[0:3], v[18:19], off offset:32 nt
	global_load_dwordx4 v[4:7], v[18:19], off offset:48 nt
	global_load_dwordx4 v[8:11], v[18:19], off offset:16 nt
	global_load_dwordx4 v[12:15], v[18:19], off nt
	s_nop 0
	global_load_dwordx4 v[16:19], v[36:37], off offset:32 nt
	global_load_dwordx4 v[20:23], v[36:37], off offset:48 nt
	global_load_dwordx4 v[24:27], v[36:37], off nt
	global_load_dwordx4 v[28:31], v[36:37], off offset:16 nt
	s_waitcnt lgkmcnt(0)
	v_add_f32_e32 v34, v34, v35
	s_mov_b32 s0, 0x3fb8aa3b
	v_add_f32_e32 v32, v32, v33
	v_mul_f32_e32 v33, 0x3fb8aa3b, v34
	v_mul_f32_e32 v36, 0x3fb8aa3b, v32
	v_fma_f32 v37, v34, s0, -v33
	v_rndne_f32_e32 v42, v33
	v_fma_f32 v43, v32, s0, -v36
	v_rndne_f32_e32 v44, v36
	v_fmac_f32_e32 v37, 0x32a5705f, v34
	v_sub_f32_e32 v33, v33, v42
	v_fmac_f32_e32 v43, 0x32a5705f, v32
	v_sub_f32_e32 v36, v36, v44
	v_add_f32_e32 v33, v33, v37
	v_cvt_i32_f32_e32 v42, v42
	v_add_f32_e32 v36, v36, v43
	v_exp_f32_e32 v33, v33
	v_cvt_i32_f32_e32 v44, v44
	v_exp_f32_e32 v36, v36
	s_mov_b32 s1, 0xc2ce8ed0
	v_ldexp_f32 v33, v33, v42
	v_cmp_ngt_f32_e32 vcc, s1, v34
	s_mov_b32 s3, 0x42b17218
	v_ldexp_f32 v36, v36, v44
	v_cndmask_b32_e32 v33, 0, v33, vcc
	v_cmp_ngt_f32_e32 vcc, s1, v32
	v_mov_b32_e32 v35, 0x7f800000
	s_lshl_b32 s10, s70, 4
	v_cndmask_b32_e32 v36, 0, v36, vcc
	v_cmp_nlt_f32_e32 vcc, s3, v34
	s_ashr_i32 s73, s72, 31
	s_ashr_i32 s11, s10, 31
	v_cndmask_b32_e32 v33, v35, v33, vcc
	v_cmp_nlt_f32_e32 vcc, s3, v32
	s_lshl_b64 s[12:13], s[72:73], 12
	s_lshl_b64 s[14:15], s[72:73], 11
	v_cndmask_b32_e32 v32, v35, v36, vcc
	v_sub_f32_e32 v32, v33, v32
	v_add_f32_e32 v42, 0x3e4ccccd, v32
	v_lshlrev_b64 v[40:41], 1, v[38:39]
	s_lshl_b64 s[16:17], s[10:11], 12
	s_lshl_b64 s[18:19], s[10:11], 11
	v_mov_b32_e32 v43, v42
	s_add_i32 s3, 0, 0x20118
	s_mov_b32 s11, 0xc600000
	s_mov_b32 s26, 0xe600000
	s_mov_b32 s27, 0x10600000
	s_mov_b32 s28, 0xffff0000
	v_mov_b32_e32 v136, 0x358637bd
	s_mov_b32 s29, 0xf800000
	v_mov_b32_e32 v137, 0x260
	s_mov_b32 s30, 0x3f4ccccd
	s_movk_i32 s31, 0x7fff
	s_mov_b32 s33, 0x12600000
	s_mov_b64 s[20:21], 0x12600000
	s_mov_b64 s[22:23], 0x12600800
	s_waitcnt vmcnt(0)
	v_mov_b32_e32 v44, v1
	v_mov_b32_e32 v45, v3
	v_mov_b32_e32 v1, v2
	v_mov_b32_e32 v2, v5
	v_mov_b32_e32 v3, v7
	v_mov_b32_e32 v5, v6
	v_mov_b32_e32 v6, v13
	v_mov_b32_e32 v7, v15
	v_mov_b32_e32 v13, v14
	v_mov_b32_e32 v14, v9
	v_mov_b32_e32 v15, v11
	v_mov_b32_e32 v9, v10
	v_mov_b32_e32 v10, v17
	v_mov_b32_e32 v11, v19
	v_mov_b32_e32 v17, v18
	v_mov_b32_e32 v18, v21
	v_mov_b32_e32 v19, v23
	v_mov_b32_e32 v21, v22
	v_mov_b32_e32 v22, v25
	v_mov_b32_e32 v23, v27
	v_mov_b32_e32 v25, v26
	v_mov_b32_e32 v26, v29
	v_mov_b32_e32 v27, v31
	v_mov_b32_e32 v29, v30
; __global__ void __launch_bounds__(NTHR, 2) mk_fwd(Args args) {
;     ...
;         for (int row = gw; row < M; row += 2 * NGW) {
;             const int r1 = (row + NGW < M) ? row + NGW : row;
;             v4u w[2][6];
; #pragma unroll
;             for (int q = 0; q < 2; ++q) { const size_t ro = (size_t)(q == 0 ? row : r1) * 1024 + lane * 16;
;                 w[q][0] = *(const v4u*)(p_O32 + ro); w[q][1] = *(const v4u*)(p_O32 + ro + 8);
;                 w[q][2] = *(const v4u*)(p_O32 + (size_t)M * 1024 + ro); w[q][3] = *(const v4u*)(p_O32 + (size_t)M * 1024 + ro + 8);
;                 w[q][4] = *(const v4u*)(p_Y2 + ro); w[q][5] = *(const v4u*)(p_Y2 + ro + 8); }
; #pragma unroll
;             for (int q = 0; q < 2; ++q) { const int r = (q == 0 ? row : r1);
;                 float a[16], b[16];
;     ...
;                 UNP(a, w[q][0], w[q][1]); UNP(b, w[q][2], w[q][3]);
;                 float ss = 0.f;
; #pragma unroll
;                 for (int i = 0; i < 16; ++i) { a[i] = a[i] - lam * b[i]; ss += a[i] * a[i]; }
;                 ss += __shfl_xor(ss, 1); ss += __shfl_xor(ss, 2); ss += __shfl_xor(ss, 4);
;                 const float rstd = (1.0f - lam_init) / sqrtf(ss * (1.0f / 128.0f) + 1e-6f);
; #pragma unroll
;                 for (int i = 0; i < 16; ++i) a[i] = a[i] * rstd * subln[i];
;                 pack16(p_MIX + (size_t)r * DMODEL + lane * 16, a);
.LBB0_1235:
	v_mov_b32_e32 v138, s3
	ds_read_b64 v[30:31], v138
	s_add_i32 s0, s80, s72
	s_cmpk_lt_i32 s0, 0x4000
	s_cselect_b32 s0, s0, s72
	s_ashr_i32 s1, s0, 31
	s_lshl_b64 s[4:5], s[0:1], 10
	s_lshl_b64 s[24:25], s[0:1], 12
	s_waitcnt lgkmcnt(0)
	v_readfirstlane_b32 s0, v30
	v_readfirstlane_b32 s1, v31
	v_lshl_add_u64 v[32:33], s[4:5], 0, v[38:39]
	s_nop 0
	v_lshl_add_u64 v[30:31], s[0:1], 0, v[40:41]
	v_lshl_add_u64 v[34:35], v[30:31], 0, s[14:15]
	v_add_co_u32_e32 v36, vcc, 0xc600000, v34
	v_lshl_add_u64 v[30:31], v[30:31], 0, s[12:13]
	s_nop 0
	v_addc_co_u32_e32 v37, vcc, 0, v35, vcc
	v_lshl_add_u64 v[32:33], v[32:33], 1, s[0:1]
	v_add_co_u32_e64 v46, s[0:1], s33, v30
	v_add_co_u32_e32 v30, vcc, 0xe600000, v34
	s_nop 0
	v_addc_co_u32_e64 v47, s[0:1], 0, v31, s[0:1]
	v_addc_co_u32_e32 v31, vcc, 0, v35, vcc
	v_add_co_u32_e32 v34, vcc, 0x10600000, v34
	global_load_dwordx4 v[48:51], v[36:37], off offset:16 nt
	global_load_dwordx4 v[52:55], v[36:37], off nt
	v_addc_co_u32_e32 v35, vcc, 0, v35, vcc
	global_load_dwordx4 v[56:59], v[30:31], off offset:16 nt
	global_load_dwordx4 v[60:63], v[30:31], off nt
	v_add_co_u32_e32 v30, vcc, s11, v32
	global_load_dwordx4 v[72:75], v[34:35], off offset:16 nt
	global_load_dwordx4 v[76:79], v[34:35], off nt
	v_addc_co_u32_e32 v31, vcc, 0, v33, vcc
	v_add_co_u32_e32 v34, vcc, s26, v32
	global_load_dwordx4 v[88:91], v[30:31], off nt
	global_load_dwordx4 v[92:95], v[30:31], off offset:16 nt
	v_addc_co_u32_e32 v35, vcc, 0, v33, vcc
	global_load_dwordx4 v[96:99], v[34:35], off nt
	global_load_dwordx4 v[100:103], v[34:35], off offset:16 nt
	v_add_co_u32_e32 v64, vcc, s27, v32
	s_waitcnt vmcnt(0) lgkmcnt(0)
	v_lshlrev_b32_e32 v69, 16, v51
	v_addc_co_u32_e32 v65, vcc, 0, v33, vcc
	global_load_dwordx4 v[30:33], v[64:65], off nt
	global_load_dwordx4 v[34:37], v[64:65], off offset:16 nt
	v_lshlrev_b32_e32 v81, 16, v53
	v_lshlrev_b32_e32 v80, 16, v52
	v_and_b32_e32 v53, 0xffff0000, v53
	v_and_b32_e32 v52, 0xffff0000, v52
	v_lshlrev_b32_e32 v83, 16, v61
	v_lshlrev_b32_e32 v82, 16, v60
	v_and_b32_e32 v61, 0xffff0000, v61
	v_and_b32_e32 v60, 0xffff0000, v60
	v_lshlrev_b32_e32 v65, 16, v49
	v_lshlrev_b32_e32 v64, 16, v48
	v_and_b32_e32 v49, 0xffff0000, v49
	v_and_b32_e32 v48, 0xffff0000, v48
	v_lshlrev_b32_e32 v68, 16, v50
	v_and_b32_e32 v51, 0xffff0000, v51
	v_and_b32_e32 v50, 0xffff0000, v50
	v_lshlrev_b32_e32 v85, 16, v55
	v_lshlrev_b32_e32 v84, 16, v54
	v_and_b32_e32 v55, 0xffff0000, v55
	v_and_b32_e32 v54, 0xffff0000, v54
	v_lshlrev_b32_e32 v67, 16, v57
	v_lshlrev_b32_e32 v66, 16, v56
	v_and_b32_e32 v57, 0xffff0000, v57
	v_and_b32_e32 v56, 0xffff0000, v56
	v_lshlrev_b32_e32 v71, 16, v59
	v_lshlrev_b32_e32 v70, 16, v58
	v_and_b32_e32 v59, 0xffff0000, v59
	v_and_b32_e32 v58, 0xffff0000, v58
	v_lshlrev_b32_e32 v87, 16, v63
	v_lshlrev_b32_e32 v86, 16, v62
	v_and_b32_e32 v63, 0xffff0000, v63
	v_and_b32_e32 v62, 0xffff0000, v62
	v_pk_fma_f32 v[80:81], v[42:43], v[82:83], v[80:81] neg_lo:[1,0,0] neg_hi:[1,0,0]
	v_pk_fma_f32 v[82:83], v[42:43], v[60:61], v[52:53] neg_lo:[1,0,0] neg_hi:[1,0,0]
	v_pk_fma_f32 v[64:65], v[42:43], v[66:67], v[64:65] neg_lo:[1,0,0] neg_hi:[1,0,0]
	v_pk_fma_f32 v[66:67], v[42:43], v[56:57], v[48:49] neg_lo:[1,0,0] neg_hi:[1,0,0]
	v_pk_fma_f32 v[68:69], v[42:43], v[70:71], v[68:69] neg_lo:[1,0,0] neg_hi:[1,0,0]
	v_pk_fma_f32 v[70:71], v[42:43], v[58:59], v[50:51] neg_lo:[1,0,0] neg_hi:[1,0,0]
	v_pk_fma_f32 v[84:85], v[42:43], v[86:87], v[84:85] neg_lo:[1,0,0] neg_hi:[1,0,0]
	v_pk_fma_f32 v[86:87], v[42:43], v[62:63], v[54:55] neg_lo:[1,0,0] neg_hi:[1,0,0]
	v_lshlrev_b32_e32 v53, 16, v75
	v_and_b32_e32 v55, 0xffff0000, v75
	v_lshlrev_b32_e32 v57, 16, v77
	v_lshlrev_b32_e32 v56, 16, v76
	v_and_b32_e32 v59, 0xffff0000, v77
	v_and_b32_e32 v58, 0xffff0000, v76
	v_pk_mul_f32 v[76:77], v[80:81], v[80:81]
	v_pk_mul_f32 v[120:121], v[82:83], v[82:83]
	v_lshlrev_b32_e32 v61, 16, v79
	v_lshlrev_b32_e32 v60, 16, v78
	v_and_b32_e32 v63, 0xffff0000, v79
	v_and_b32_e32 v62, 0xffff0000, v78
	v_mov_b32_e32 v78, v53
	v_mov_b32_e32 v79, v55
	v_pk_mul_f32 v[140:141], v[56:57], v[56:57]
	v_pk_mul_f32 v[122:123], v[58:59], v[58:59]
	v_add_f32_e32 v76, v76, v120
	v_lshlrev_b32_e32 v49, 16, v73
	v_lshlrev_b32_e32 v48, 16, v72
	v_and_b32_e32 v51, 0xffff0000, v73
	v_and_b32_e32 v50, 0xffff0000, v72
	v_lshlrev_b32_e32 v52, 16, v74
	v_and_b32_e32 v54, 0xffff0000, v74
	v_mov_b32_e32 v72, v68
	v_mov_b32_e32 v73, v70
	v_mov_b32_e32 v74, v69
	v_mov_b32_e32 v75, v71
	v_lshlrev_b32_e32 v145, 16, v95
	v_lshlrev_b32_e32 v144, 16, v94
	v_and_b32_e32 v95, 0xffff0000, v95
	v_and_b32_e32 v94, 0xffff0000, v94
	v_lshlrev_b32_e32 v147, 16, v89
	v_lshlrev_b32_e32 v146, 16, v88
	v_and_b32_e32 v149, 0xffff0000, v89
	v_and_b32_e32 v148, 0xffff0000, v88
	v_lshlrev_b32_e32 v151, 16, v91
	v_lshlrev_b32_e32 v150, 16, v90
	v_and_b32_e32 v153, 0xffff0000, v91
	v_and_b32_e32 v152, 0xffff0000, v90
	v_pk_mul_f32 v[126:127], v[78:79], v[78:79]
	v_add_f32_e32 v120, v140, v122
	v_lshlrev_b32_e32 v79, 16, v103
	v_lshlrev_b32_e32 v78, 16, v102
	v_and_b32_e32 v89, 0xffff0000, v103
	v_and_b32_e32 v88, 0xffff0000, v102
	v_lshlrev_b32_e32 v91, 16, v97
	v_lshlrev_b32_e32 v90, 16, v96
	v_and_b32_e32 v97, 0xffff0000, v97
	v_and_b32_e32 v96, 0xffff0000, v96
	v_add_f32_e32 v122, v76, v77
	v_pk_mul_f32 v[114:115], v[84:85], v[84:85]
	v_lshlrev_b32_e32 v143, 16, v93
	v_lshlrev_b32_e32 v142, 16, v92
	v_and_b32_e32 v93, 0xffff0000, v93
	v_and_b32_e32 v92, 0xffff0000, v92
	v_pk_mul_f32 v[128:129], v[72:73], v[72:73]
	v_pk_mul_f32 v[124:125], v[74:75], v[74:75]
	v_lshlrev_b32_e32 v73, 16, v101
	v_lshlrev_b32_e32 v72, 16, v100
	v_and_b32_e32 v75, 0xffff0000, v101
	v_and_b32_e32 v74, 0xffff0000, v100
	v_lshlrev_b32_e32 v101, 16, v99
	v_lshlrev_b32_e32 v100, 16, v98
	v_add_f32_e32 v120, v120, v141
	v_pk_fma_f32 v[76:77], v[42:43], v[78:79], v[144:145] neg_lo:[1,0,0] neg_hi:[1,0,0]
	v_pk_fma_f32 v[78:79], v[42:43], v[88:89], v[94:95] neg_lo:[1,0,0] neg_hi:[1,0,0]
	v_pk_fma_f32 v[88:89], v[42:43], v[90:91], v[146:147] neg_lo:[1,0,0] neg_hi:[1,0,0]
	v_pk_fma_f32 v[90:91], v[42:43], v[96:97], v[148:149] neg_lo:[1,0,0] neg_hi:[1,0,0]
	v_add_f32_e32 v139, v122, v121
	v_pk_mul_f32 v[112:113], v[86:87], v[86:87]
	v_pk_mul_f32 v[118:119], v[60:61], v[60:61]
	v_pk_fma_f32 v[74:75], v[42:43], v[74:75], v[92:93] neg_lo:[1,0,0] neg_hi:[1,0,0]
	v_pk_fma_f32 v[92:93], v[42:43], v[100:101], v[150:151] neg_lo:[1,0,0] neg_hi:[1,0,0]
	s_waitcnt vmcnt(0) lgkmcnt(0)
; __global__ void __launch_bounds__(NTHR, 2) mk_fwd(Args args) {
;     ...
;                 float ss = 0.f;
; #pragma unroll
;                 for (int i = 0; i < 16; ++i) { a[i] = a[i] - lam * b[i]; ss += a[i] * a[i]; }
;                 ss += __shfl_xor(ss, 1); ss += __shfl_xor(ss, 2); ss += __shfl_xor(ss, 4);
;                 const float rstd = (1.0f - lam_init) / sqrtf(ss * (1.0f / 128.0f) + 1e-6f);
; #pragma unroll
;                 for (int i = 0; i < 16; ++i) a[i] = a[i] * rstd * subln[i];
;                 pack16(p_MIX + (size_t)r * DMODEL + lane * 16, a);
;                 UNP(b, w[q][4], w[q][5]); float s3 = 0.f;
;     ...
; #pragma unroll
;                 for (int i = 0; i < 16; ++i) s3 += b[i] * b[i];
;                 const float r2 = 1.0f / sqrtf(wave_sum(s3) * (1.0f / 1024.0f) + 1e-6f);
	v_lshlrev_b32_e32 v101, 16, v31
	v_lshlrev_b32_e32 v100, 16, v30
	v_and_b32_e32 v31, 0xffff0000, v31
	v_and_b32_e32 v30, 0xffff0000, v30
	v_add_f32_e32 v166, v120, v123
	v_pk_mul_f32 v[144:145], v[88:89], v[88:89]
	v_pk_mul_f32 v[146:147], v[90:91], v[90:91]
	v_add_f32_e32 v114, v139, v114
	v_pk_mul_f32 v[116:117], v[62:63], v[62:63]
	v_pk_mul_f32 v[158:159], v[100:101], v[100:101]
	v_pk_mul_f32 v[160:161], v[30:31], v[30:31]
	v_add_f32_e32 v118, v166, v118
	v_add_f32_e32 v139, v144, v146
	v_add_f32_e32 v112, v114, v112
	v_and_b32_e32 v99, 0xffff0000, v99
	v_and_b32_e32 v98, 0xffff0000, v98
	v_add_f32_e32 v144, v158, v160
	v_add_f32_e32 v114, v118, v116
	v_add_f32_e32 v116, v139, v145
	v_add_f32_e32 v112, v112, v115
	v_pk_mul_f32 v[106:107], v[64:65], v[64:65]
	v_pk_fma_f32 v[94:95], v[42:43], v[98:99], v[152:153] neg_lo:[1,0,0] neg_hi:[1,0,0]
	v_lshlrev_b32_e32 v103, 16, v33
	v_lshlrev_b32_e32 v102, 16, v32
	v_pk_mul_f32 v[148:149], v[92:93], v[92:93]
	v_add_f32_e32 v118, v144, v159
	v_add_f32_e32 v114, v114, v119
	v_add_f32_e32 v115, v116, v147
	v_add_f32_e32 v112, v112, v113
	v_pk_mul_f32 v[104:105], v[66:67], v[66:67]
	v_pk_mul_f32 v[110:111], v[48:49], v[48:49]
	v_and_b32_e32 v33, 0xffff0000, v33
	v_and_b32_e32 v32, 0xffff0000, v32
	v_pk_mul_f32 v[150:151], v[94:95], v[94:95]
	v_pk_mul_f32 v[162:163], v[102:103], v[102:103]
	v_add_f32_e32 v116, v118, v161
	v_add_f32_e32 v113, v114, v117
	v_add_f32_e32 v114, v115, v148
	v_add_f32_e32 v106, v112, v106
	v_pk_mul_f32 v[108:109], v[50:51], v[50:51]
	v_pk_mul_f32 v[164:165], v[32:33], v[32:33]
	v_add_f32_e32 v115, v116, v162
	v_add_f32_e32 v110, v113, v110
	v_add_f32_e32 v112, v114, v150
	v_add_f32_e32 v104, v106, v104
	v_pk_fma_f32 v[72:73], v[42:43], v[72:73], v[142:143] neg_lo:[1,0,0] neg_hi:[1,0,0]
	v_add_f32_e32 v113, v115, v164
	v_add_f32_e32 v106, v110, v108
	v_add_f32_e32 v108, v112, v149
	v_add_f32_e32 v104, v104, v107
	v_lshlrev_b32_e32 v97, 16, v35
	v_lshlrev_b32_e32 v96, 16, v34
	v_pk_mul_f32 v[120:121], v[72:73], v[72:73]
	v_add_f32_e32 v110, v113, v163
	v_add_f32_e32 v106, v106, v111
	v_add_f32_e32 v107, v108, v151
	v_add_f32_e32 v104, v104, v105
	v_and_b32_e32 v35, 0xffff0000, v35
	v_and_b32_e32 v34, 0xffff0000, v34
	v_pk_mul_f32 v[122:123], v[74:75], v[74:75]
	v_pk_mul_f32 v[152:153], v[96:97], v[96:97]
	v_add_f32_e32 v108, v110, v165
	v_add_f32_e32 v105, v106, v109
	v_add_f32_e32 v106, v107, v120
	v_add_f32_e32 v104, v104, v128
	v_pk_mul_f32 v[154:155], v[34:35], v[34:35]
	v_add_f32_e32 v107, v108, v152
	v_fmac_f32_e32 v105, v52, v52
	v_add_f32_e32 v106, v106, v122
	v_add_f32_e32 v104, v104, v129
	v_mov_b32_e32 v140, v76
	v_mov_b32_e32 v141, v78
	v_add_f32_e32 v107, v107, v154
	v_fmac_f32_e32 v105, v54, v54
	v_add_f32_e32 v106, v106, v121
	v_add_f32_e32 v104, v104, v124
	v_pk_mul_f32 v[140:141], v[140:141], v[140:141]
	v_add_f32_e32 v107, v107, v153
	v_add_f32_e32 v105, v105, v126
	v_add_f32_e32 v106, v106, v123
	v_add_f32_e32 v104, v104, v125
	v_lshlrev_b32_e32 v99, 16, v37
	v_lshlrev_b32_e32 v98, 16, v36
	v_and_b32_e32 v37, 0xffff0000, v37
	v_mov_b32_e32 v142, v77
	v_mov_b32_e32 v143, v79
	v_add_f32_e32 v107, v107, v155
	v_add_f32_e32 v105, v105, v127
	v_add_f32_e32 v106, v106, v140
	ds_bpermute_b32 v108, v130, v104
	v_and_b32_e32 v36, 0xffff0000, v36
	v_mov_b32_e32 v156, v99
	v_mov_b32_e32 v157, v37
	v_pk_mul_f32 v[142:143], v[142:143], v[142:143]
	v_fmac_f32_e32 v107, v98, v98
	ds_bpermute_b32 v109, v130, v105
	v_add_f32_e32 v106, v106, v141
	v_pk_mul_f32 v[156:157], v[156:157], v[156:157]
	v_fmac_f32_e32 v107, v36, v36
	v_add_f32_e32 v106, v106, v142
	v_add_f32_e32 v107, v107, v156
	v_add_f32_e32 v106, v106, v143
	v_add_f32_e32 v107, v107, v157
	ds_bpermute_b32 v110, v130, v106
	ds_bpermute_b32 v111, v130, v107
	s_waitcnt lgkmcnt(3)
	v_add_f32_e32 v104, v104, v108
	s_waitcnt lgkmcnt(2)
	v_add_f32_e32 v105, v105, v109
	ds_bpermute_b32 v108, v131, v104
	ds_bpermute_b32 v109, v131, v105
	s_waitcnt lgkmcnt(3)
	v_add_f32_e32 v106, v106, v110
	s_waitcnt lgkmcnt(2)
	v_add_f32_e32 v107, v107, v111
	ds_bpermute_b32 v110, v131, v106
	ds_bpermute_b32 v111, v131, v107
	s_waitcnt lgkmcnt(3)
	v_add_f32_e32 v104, v104, v108
	s_waitcnt lgkmcnt(2)
	v_add_f32_e32 v105, v105, v109
	ds_bpermute_b32 v108, v132, v104
	ds_bpermute_b32 v109, v132, v105
	s_waitcnt lgkmcnt(3)
	v_add_f32_e32 v106, v106, v110
	s_waitcnt lgkmcnt(2)
	v_add_f32_e32 v107, v107, v111
	ds_bpermute_b32 v110, v132, v106
	ds_bpermute_b32 v111, v132, v107
	s_waitcnt lgkmcnt(3)
	v_add_f32_e32 v104, v104, v108
	s_waitcnt lgkmcnt(2)
	v_add_f32_e32 v105, v105, v109
	v_fmamk_f32 v104, v104, 0x3c000000, v136
	ds_bpermute_b32 v108, v133, v105
	v_mul_f32_e32 v109, 0x4f800000, v104
	v_cmp_gt_f32_e32 vcc, s29, v104
	s_waitcnt lgkmcnt(2)
	v_add_f32_e32 v106, v106, v110
	s_waitcnt lgkmcnt(1)
	v_add_f32_e32 v107, v107, v111
	v_cndmask_b32_e32 v104, v104, v109, vcc
	v_sqrt_f32_e32 v109, v104
	v_fmamk_f32 v106, v106, 0x3c000000, v136
	ds_bpermute_b32 v110, v133, v107
	v_mul_f32_e32 v111, 0x4f800000, v106
	v_cmp_gt_f32_e64 s[0:1], s29, v106
	s_waitcnt lgkmcnt(1)
	v_add_f32_e32 v105, v105, v108
	ds_bpermute_b32 v108, v134, v105
	v_cndmask_b32_e64 v106, v106, v111, s[0:1]
	v_sqrt_f32_e32 v111, v106
	v_add_u32_e32 v112, -1, v109
	v_add_u32_e32 v113, 1, v109
	v_fma_f32 v114, -v112, v109, v104
	v_fma_f32 v115, -v113, v109, v104
	v_cmp_ge_f32_e64 s[4:5], 0, v114
	s_waitcnt lgkmcnt(1)
	v_add_f32_e32 v107, v107, v110
	ds_bpermute_b32 v110, v134, v107
	v_cndmask_b32_e64 v109, v109, v112, s[4:5]
	v_cmp_lt_f32_e64 s[4:5], 0, v115
	v_add_u32_e32 v112, -1, v111
	s_waitcnt lgkmcnt(1)
; __global__ void __launch_bounds__(NTHR, 2) mk_fwd(Args args) {
;     ...
;                 for (int i = 0; i < 16; ++i) { a[i] = a[i] - lam * b[i]; ss += a[i] * a[i]; }
;                 ss += __shfl_xor(ss, 1); ss += __shfl_xor(ss, 2); ss += __shfl_xor(ss, 4);
;                 const float rstd = (1.0f - lam_init) / sqrtf(ss * (1.0f / 128.0f) + 1e-6f);
; #pragma unroll
;                 for (int i = 0; i < 16; ++i) a[i] = a[i] * rstd * subln[i];
;                 pack16(p_MIX + (size_t)r * DMODEL + lane * 16, a);
;                 UNP(b, w[q][4], w[q][5]); float s3 = 0.f;
;     ...
; #pragma unroll
;                 for (int i = 0; i < 16; ++i) s3 += b[i] * b[i];
;                 const float r2 = 1.0f / sqrtf(wave_sum(s3) * (1.0f / 1024.0f) + 1e-6f);
; #pragma unroll
;                 for (int i = 0; i < 16; ++i) b[i] = b[i] * r2 * ogn[i];
;                 pack16(p_MIX + (size_t)r * DMODEL + 1024 + lane * 16, b); }
	v_add_f32_e32 v105, v105, v108
	v_cndmask_b32_e64 v109, v109, v113, s[4:5]
	v_add_u32_e32 v113, 1, v111
	v_mul_f32_e32 v114, 0x37800000, v109
	v_fma_f32 v108, -v112, v111, v106
	v_fma_f32 v115, -v113, v111, v106
	v_cndmask_b32_e32 v109, v109, v114, vcc
	ds_bpermute_b32 v114, v135, v105
	v_cmp_ge_f32_e32 vcc, 0, v108
	v_cmp_class_f32_e64 s[4:5], v104, v137
	s_waitcnt lgkmcnt(1)
	v_add_f32_e32 v107, v107, v110
	v_cndmask_b32_e32 v108, v111, v112, vcc
	v_cmp_lt_f32_e32 vcc, 0, v115
	v_cndmask_b32_e64 v104, v109, v104, s[4:5]
	v_div_scale_f32 v109, s[4:5], v104, v104, s30
	v_cndmask_b32_e32 v108, v108, v113, vcc
	v_mul_f32_e32 v112, 0x37800000, v108
	v_rcp_f32_e32 v110, v109
	v_cndmask_b32_e64 v108, v108, v112, s[0:1]
	ds_bpermute_b32 v112, v135, v107
	s_waitcnt lgkmcnt(1)
	v_add_f32_e32 v105, v105, v114
	v_cmp_class_f32_e64 s[0:1], v106, v137
	v_fmamk_f32 v105, v105, 0x3a800000, v136
	v_fma_f32 v115, -v109, v110, 1.0
	v_cndmask_b32_e64 v106, v108, v106, s[0:1]
	v_mul_f32_e32 v116, 0x4f800000, v105
	v_cmp_gt_f32_e64 s[6:7], s29, v105
	v_div_scale_f32 v111, vcc, s30, v104, s30
	v_div_scale_f32 v108, s[0:1], v106, v106, s30
	v_fmac_f32_e32 v110, v115, v110
	v_cndmask_b32_e64 v105, v105, v116, s[6:7]
	v_rcp_f32_e32 v114, v108
	s_waitcnt lgkmcnt(0)
	v_add_f32_e32 v107, v107, v112
	v_mul_f32_e32 v112, v111, v110
	v_sqrt_f32_e32 v115, v105
	v_fmamk_f32 v107, v107, 0x3a800000, v136
	v_fma_f32 v116, -v109, v112, v111
	v_mul_f32_e32 v118, 0x4f800000, v107
	v_cmp_gt_f32_e64 s[4:5], s29, v107
	v_fmac_f32_e32 v112, v116, v110
	v_fma_f32 v109, -v109, v112, v111
	v_cndmask_b32_e64 v107, v107, v118, s[4:5]
	v_fma_f32 v117, -v108, v114, 1.0
	v_sqrt_f32_e32 v116, v107
	v_div_fmas_f32 v109, v109, v110, v112
	v_add_u32_e32 v110, -1, v115
	v_div_scale_f32 v113, s[0:1], s30, v106, s30
	v_fmac_f32_e32 v114, v117, v114
	v_add_u32_e32 v112, 1, v115
	v_div_fixup_f32 v104, v109, v104, s30
	v_fma_f32 v109, -v110, v115, v105
	v_mul_f32_e32 v111, v113, v114
	v_fma_f32 v118, -v112, v115, v105
	v_cmp_ge_f32_e32 vcc, 0, v109
	v_fma_f32 v117, -v108, v111, v113
	v_pk_mul_f32 v[80:81], v[104:105], v[80:81] op_sel_hi:[0,1]
	v_pk_mul_f32 v[82:83], v[104:105], v[82:83] op_sel_hi:[0,1]
	v_pk_mul_f32 v[84:85], v[104:105], v[84:85] op_sel_hi:[0,1]
	v_pk_mul_f32 v[86:87], v[104:105], v[86:87] op_sel_hi:[0,1]
	v_pk_mul_f32 v[64:65], v[104:105], v[64:65] op_sel_hi:[0,1]
	v_pk_mul_f32 v[66:67], v[104:105], v[66:67] op_sel_hi:[0,1]
	v_pk_mul_f32 v[68:69], v[104:105], v[68:69] op_sel_hi:[0,1]
	v_pk_mul_f32 v[70:71], v[104:105], v[70:71] op_sel_hi:[0,1]
	v_cndmask_b32_e32 v104, v115, v110, vcc
	v_cmp_lt_f32_e32 vcc, 0, v118
	v_fmac_f32_e32 v111, v117, v114
	v_pk_mul_f32 v[80:81], v[80:81], v[12:13]
	v_pk_mul_f32 v[84:85], v[84:85], v[8:9]
	v_pk_mul_f32 v[86:87], v[86:87], v[14:15]
	v_pk_mul_f32 v[66:67], v[66:67], v[44:45]
	v_pk_mul_f32 v[68:69], v[68:69], v[4:5]
	v_cndmask_b32_e32 v104, v104, v112, vcc
	v_add_u32_e32 v109, -1, v116
	v_fma_f32 v108, -v108, v111, v113
	v_pk_mul_f32 v[82:83], v[82:83], v[6:7]
	v_pk_mul_f32 v[64:65], v[64:65], v[0:1]
	v_add_u32_e32 v110, 1, v116
	v_bfe_u32 v113, v86, 16, 1
	v_bfe_u32 v118, v80, 16, 1
	v_bfe_u32 v119, v81, 16, 1
	v_bfe_u32 v120, v84, 16, 1
	v_bfe_u32 v121, v85, 16, 1
	v_bfe_u32 v124, v67, 16, 1
	v_bfe_u32 v128, v68, 16, 1
	v_mul_f32_e32 v139, 0x37800000, v104
	v_fma_f32 v140, -v109, v116, v107
	v_pk_mul_f32 v[70:71], v[70:71], v[2:3]
	v_bfe_u32 v112, v87, 16, 1
	v_bfe_u32 v115, v83, 16, 1
	v_bfe_u32 v117, v82, 16, 1
	v_bfe_u32 v125, v66, 16, 1
	v_bfe_u32 v126, v64, 16, 1
	v_bfe_u32 v127, v65, 16, 1
	v_bfe_u32 v129, v69, 16, 1
	v_fma_f32 v141, -v110, v116, v107
	v_add3_u32 v86, v86, v113, s31
	v_add3_u32 v85, v85, v121, s31
	v_add3_u32 v84, v84, v120, s31
	v_add3_u32 v81, v81, v119, s31
	v_add3_u32 v80, v80, v118, s31
	v_add3_u32 v113, v67, v124, s31
	v_add3_u32 v67, v68, v128, s31
	v_cndmask_b32_e64 v68, v104, v139, s[6:7]
	v_cmp_class_f32_e32 vcc, v105, v137
	v_cmp_ge_f32_e64 s[6:7], 0, v140
	v_bfe_u32 v122, v71, 16, 1
	v_bfe_u32 v123, v70, 16, 1
	v_add3_u32 v82, v82, v117, s31
	v_add3_u32 v83, v83, v115, s31
	v_add3_u32 v87, v87, v112, s31
	v_add3_u32 v112, v66, v125, s31
	v_add3_u32 v66, v69, v129, s31
	v_add3_u32 v65, v65, v127, s31
	v_add3_u32 v64, v64, v126, s31
	v_cndmask_b32_e64 v69, v116, v109, s[6:7]
	v_cmp_lt_f32_e64 s[6:7], 0, v141
	v_lshrrev_b32_e32 v80, 16, v80
	v_lshrrev_b32_e32 v81, 16, v81
	v_lshrrev_b32_e32 v84, 16, v84
	v_lshrrev_b32_e32 v85, 16, v85
	v_cndmask_b32_e32 v105, v68, v105, vcc
	v_add3_u32 v70, v70, v123, s31
	v_add3_u32 v71, v71, v122, s31
	v_lshrrev_b32_e32 v104, 16, v64
	v_lshrrev_b32_e32 v109, 16, v65
	v_lshrrev_b32_e32 v115, 16, v67
	v_lshrrev_b32_e32 v116, 16, v66
	v_cndmask_b32_e64 v110, v69, v110, s[6:7]
	v_and_or_b32 v67, v87, s28, v85
	v_and_or_b32 v66, v86, s28, v84
	v_and_or_b32 v65, v83, s28, v81
	v_and_or_b32 v64, v82, s28, v80
	v_div_scale_f32 v80, s[6:7], v105, v105, 1.0
	v_and_or_b32 v71, v71, s28, v116
	v_and_or_b32 v70, v70, s28, v115
	v_and_or_b32 v69, v113, s28, v109
	v_and_or_b32 v68, v112, s28, v104
	v_mul_f32_e32 v82, 0x37800000, v110
	global_store_dwordx4 v[46:47], v[64:67], off
	global_store_dwordx4 v[46:47], v[68:71], off offset:16
	v_div_scale_f32 v81, vcc, 1.0, v105, 1.0
	v_rcp_f32_e32 v64, v80
	v_cndmask_b32_e64 v65, v110, v82, s[4:5]
	v_cmp_class_f32_e64 s[4:5], v107, v137
	ds_read_b64 v[46:47], v138
	v_fma_f32 v67, -v80, v64, 1.0
	v_cndmask_b32_e64 v82, v65, v107, s[4:5]
	v_div_scale_f32 v65, s[4:5], v82, v82, 1.0
	v_rcp_f32_e32 v83, v65
	v_fmac_f32_e32 v64, v67, v64
	v_mul_f32_e32 v67, v81, v64
	v_fma_f32 v68, -v80, v67, v81
	v_fma_f32 v69, -v65, v83, 1.0
	v_fmac_f32_e32 v67, v68, v64
	v_div_scale_f32 v66, s[4:5], 1.0, v82, 1.0
	v_fmac_f32_e32 v83, v69, v83
	v_fma_f32 v68, -v80, v67, v81
	v_mul_f32_e32 v84, v66, v83
	v_div_fmas_f32 v64, v68, v64, v67
	v_fma_f32 v67, -v65, v84, v66
	v_div_fixup_f32 v64, v64, v105, 1.0
	s_mov_b64 vcc, s[0:1]
	v_div_fmas_f32 v68, v108, v114, v111
	v_fmac_f32_e32 v84, v67, v83
	v_pk_mul_f32 v[56:57], v[64:65], v[56:57] op_sel_hi:[0,1]
	v_pk_mul_f32 v[58:59], v[64:65], v[58:59] op_sel_hi:[0,1]
	v_pk_mul_f32 v[60:61], v[64:65], v[60:61] op_sel_hi:[0,1]
	s_waitcnt lgkmcnt(0)
; __global__ void __launch_bounds__(NTHR, 2) mk_fwd(Args args) {
;     ...
;                 for (int i = 0; i < 16; ++i) { a[i] = a[i] - lam * b[i]; ss += a[i] * a[i]; }
;                 ss += __shfl_xor(ss, 1); ss += __shfl_xor(ss, 2); ss += __shfl_xor(ss, 4);
;                 const float rstd = (1.0f - lam_init) / sqrtf(ss * (1.0f / 128.0f) + 1e-6f);
; #pragma unroll
;                 for (int i = 0; i < 16; ++i) a[i] = a[i] * rstd * subln[i];
;                 pack16(p_MIX + (size_t)r * DMODEL + lane * 16, a);
;                 UNP(b, w[q][4], w[q][5]); float s3 = 0.f;
;     ...
; #pragma unroll
;                 for (int i = 0; i < 16; ++i) s3 += b[i] * b[i];
;                 const float r2 = 1.0f / sqrtf(wave_sum(s3) * (1.0f / 1024.0f) + 1e-6f);
; #pragma unroll
;                 for (int i = 0; i < 16; ++i) b[i] = b[i] * r2 * ogn[i];
;                 pack16(p_MIX + (size_t)r * DMODEL + 1024 + lane * 16, b); }
	v_readfirstlane_b32 s6, v46
	v_readfirstlane_b32 s7, v47
	v_pk_mul_f32 v[62:63], v[64:65], v[62:63] op_sel_hi:[0,1]
	v_pk_mul_f32 v[48:49], v[64:65], v[48:49] op_sel_hi:[0,1]
	v_pk_mul_f32 v[50:51], v[64:65], v[50:51] op_sel_hi:[0,1]
	v_pk_mul_f32 v[52:53], v[64:65], v[52:53] op_sel_hi:[0,1]
	v_pk_mul_f32 v[54:55], v[64:65], v[54:55] op_sel_hi:[0,1]
	v_div_fixup_f32 v64, v68, v106, s30
	v_fma_f32 v85, -v65, v84, v66
	v_pk_mul_f32 v[56:57], v[56:57], v[24:25]
	v_pk_mul_f32 v[58:59], v[58:59], v[22:23]
	v_pk_mul_f32 v[60:61], v[60:61], v[28:29]
	s_mov_b64 vcc, s[4:5]
	v_lshl_add_u64 v[46:47], s[6:7], 0, v[40:41]
	v_pk_mul_f32 v[62:63], v[62:63], v[26:27]
	v_pk_mul_f32 v[48:49], v[48:49], v[16:17]
	v_pk_mul_f32 v[50:51], v[50:51], v[10:11]
	v_pk_mul_f32 v[52:53], v[52:53], v[20:21]
	v_pk_mul_f32 v[54:55], v[54:55], v[18:19]
	v_pk_mul_f32 v[66:67], v[64:65], v[88:89] op_sel_hi:[0,1]
	v_pk_mul_f32 v[68:69], v[64:65], v[90:91] op_sel_hi:[0,1]
	v_pk_mul_f32 v[80:81], v[64:65], v[94:95] op_sel_hi:[0,1]
	v_div_fmas_f32 v83, v85, v83, v84
	v_bfe_u32 v86, v59, 16, 1
	v_bfe_u32 v87, v58, 16, 1
	v_bfe_u32 v88, v56, 16, 1
	v_bfe_u32 v89, v57, 16, 1
	v_bfe_u32 v90, v60, 16, 1
	v_bfe_u32 v91, v61, 16, 1
	v_lshl_add_u64 v[46:47], v[46:47], 0, s[12:13]
	v_pk_mul_f32 v[70:71], v[64:65], v[92:93] op_sel_hi:[0,1]
	v_pk_mul_f32 v[72:73], v[64:65], v[72:73] op_sel_hi:[0,1]
	v_pk_mul_f32 v[74:75], v[64:65], v[74:75] op_sel_hi:[0,1]
	v_pk_mul_f32 v[76:77], v[64:65], v[76:77] op_sel_hi:[0,1]
	v_pk_mul_f32 v[64:65], v[64:65], v[78:79] op_sel_hi:[0,1]
	v_bfe_u32 v84, v63, 16, 1
	v_bfe_u32 v85, v62, 16, 1
	v_bfe_u32 v92, v55, 16, 1
	v_bfe_u32 v93, v54, 16, 1
	v_bfe_u32 v94, v51, 16, 1
	v_bfe_u32 v95, v50, 16, 1
	v_bfe_u32 v104, v48, 16, 1
	v_bfe_u32 v105, v49, 16, 1
	v_bfe_u32 v106, v52, 16, 1
	v_bfe_u32 v107, v53, 16, 1
	v_pk_mul_f32 v[78:79], v[80:81], v[14:15]
	v_div_fixup_f32 v80, v83, v82, 1.0
	v_add3_u32 v81, v58, v87, s31
	v_add3_u32 v82, v59, v86, s31
	v_add3_u32 v58, v61, v91, s31
	v_add3_u32 v59, v60, v90, s31
	v_add3_u32 v57, v57, v89, s31
	v_add3_u32 v56, v56, v88, s31
	v_add_co_u32_e64 v46, s[6:7], s33, v46
	v_pk_mul_f32 v[66:67], v[66:67], v[12:13]
	v_pk_mul_f32 v[68:69], v[68:69], v[6:7]
	v_pk_mul_f32 v[70:71], v[70:71], v[8:9]
	v_add3_u32 v83, v62, v85, s31
	v_add3_u32 v84, v63, v84, s31
	v_add3_u32 v85, v50, v95, s31
	v_add3_u32 v86, v51, v94, s31
	v_add3_u32 v87, v54, v93, s31
	v_add3_u32 v88, v55, v92, s31
	v_add3_u32 v60, v53, v107, s31
	v_add3_u32 v61, v52, v106, s31
	v_add3_u32 v62, v49, v105, s31
	v_add3_u32 v63, v48, v104, s31
	v_pk_mul_f32 v[48:49], v[80:81], v[100:101] op_sel_hi:[0,1]
	v_pk_mul_f32 v[30:31], v[80:81], v[30:31] op_sel_hi:[0,1]
	v_pk_mul_f32 v[50:51], v[80:81], v[102:103] op_sel_hi:[0,1]
	v_pk_mul_f32 v[32:33], v[80:81], v[32:33] op_sel_hi:[0,1]
	v_pk_mul_f32 v[52:53], v[80:81], v[96:97] op_sel_hi:[0,1]
	v_pk_mul_f32 v[34:35], v[80:81], v[34:35] op_sel_hi:[0,1]
	v_pk_mul_f32 v[54:55], v[80:81], v[98:99] op_sel_hi:[0,1]
	v_pk_mul_f32 v[36:37], v[80:81], v[36:37] op_sel_hi:[0,1]
	v_lshrrev_b32_e32 v80, 16, v56
	v_lshrrev_b32_e32 v96, 16, v57
	v_lshrrev_b32_e32 v97, 16, v59
	v_lshrrev_b32_e32 v98, 16, v58
	v_addc_co_u32_e64 v47, s[6:7], 0, v47, s[6:7]
	v_bfe_u32 v89, v79, 16, 1
	v_bfe_u32 v90, v78, 16, 1
	v_bfe_u32 v91, v69, 16, 1
	v_bfe_u32 v94, v67, 16, 1
	v_bfe_u32 v95, v70, 16, 1
	v_lshrrev_b32_e32 v99, 16, v63
	v_lshrrev_b32_e32 v100, 16, v62
	v_lshrrev_b32_e32 v101, 16, v61
	v_lshrrev_b32_e32 v102, 16, v60
	v_pk_mul_f32 v[56:57], v[30:31], v[22:23]
	v_pk_mul_f32 v[58:59], v[32:33], v[26:27]
	v_pk_mul_f32 v[60:61], v[34:35], v[10:11]
	v_pk_mul_f32 v[54:55], v[54:55], v[20:21]
	v_pk_mul_f32 v[62:63], v[36:37], v[18:19]
	v_and_or_b32 v33, v84, s28, v98
	v_and_or_b32 v32, v83, s28, v97
	v_and_or_b32 v31, v82, s28, v96
	v_and_or_b32 v30, v81, s28, v80
	v_add3_u32 v69, v69, v91, s31
	v_add3_u32 v78, v78, v90, s31
	v_add3_u32 v79, v79, v89, s31
	v_add3_u32 v70, v70, v95, s31
	v_add3_u32 v67, v67, v94, s31
	v_and_or_b32 v37, v88, s28, v102
	v_and_or_b32 v36, v87, s28, v101
	v_and_or_b32 v35, v86, s28, v100
	v_and_or_b32 v34, v85, s28, v99
	v_bfe_u32 v80, v59, 16, 1
	v_bfe_u32 v81, v58, 16, 1
	v_bfe_u32 v82, v57, 16, 1
	v_bfe_u32 v83, v56, 16, 1
	v_bfe_u32 v88, v63, 16, 1
	v_bfe_u32 v89, v62, 16, 1
	v_bfe_u32 v90, v61, 16, 1
	v_bfe_u32 v91, v60, 16, 1
	v_bfe_u32 v94, v54, 16, 1
	v_bfe_u32 v95, v55, 16, 1
	global_store_dwordx4 v[46:47], v[30:33], off offset:2048
	global_store_dwordx4 v[46:47], v[34:37], off offset:2064
	v_add3_u32 v46, v56, v83, s31
	v_add3_u32 v47, v57, v82, s31
	v_add3_u32 v56, v58, v81, s31
	v_add3_u32 v57, v59, v80, s31
	v_add3_u32 v58, v60, v91, s31
	v_add3_u32 v59, v61, v90, s31
	v_add3_u32 v60, v62, v89, s31
	v_add3_u32 v61, v63, v88, s31
	v_add3_u32 v62, v55, v95, s31
	v_add3_u32 v63, v54, v94, s31
	ds_read_b64 v[54:55], v138
	v_pk_mul_f32 v[76:77], v[76:77], v[4:5]
	v_pk_mul_f32 v[64:65], v[64:65], v[2:3]
	v_bfe_u32 v111, v76, 16, 1
	v_bfe_u32 v112, v77, 16, 1
	v_pk_mul_f32 v[48:49], v[48:49], v[24:25]
	v_pk_mul_f32 v[50:51], v[50:51], v[28:29]
	s_waitcnt lgkmcnt(0)
; __global__ void __launch_bounds__(NTHR, 2) mk_fwd(Args args) {
;     ...
; #pragma unroll
;                 for (int i = 0; i < 16; ++i) a[i] = a[i] * rstd * subln[i];
;                 pack16(p_MIX + (size_t)r * DMODEL + lane * 16, a);
;                 UNP(b, w[q][4], w[q][5]); float s3 = 0.f;
;     ...
; #pragma unroll
;                 for (int i = 0; i < 16; ++i) s3 += b[i] * b[i];
;                 const float r2 = 1.0f / sqrtf(wave_sum(s3) * (1.0f / 1024.0f) + 1e-6f);
; #pragma unroll
;                 for (int i = 0; i < 16; ++i) b[i] = b[i] * r2 * ogn[i];
;                 pack16(p_MIX + (size_t)r * DMODEL + 1024 + lane * 16, b); }
;         }
	v_readfirstlane_b32 s0, v54
	v_bfe_u32 v105, v65, 16, 1
	v_bfe_u32 v106, v64, 16, 1
	v_add3_u32 v77, v77, v112, s31
	v_add3_u32 v76, v76, v111, s31
	v_bfe_u32 v84, v48, 16, 1
	v_bfe_u32 v85, v49, 16, 1
	v_bfe_u32 v86, v50, 16, 1
	v_bfe_u32 v87, v51, 16, 1
	v_readfirstlane_b32 s1, v55
	s_add_u32 s0, s0, s24
	v_pk_mul_f32 v[72:73], v[72:73], v[0:1]
	v_bfe_u32 v93, v66, 16, 1
	v_bfe_u32 v104, v71, 16, 1
	v_add3_u32 v64, v64, v106, s31
	v_add3_u32 v65, v65, v105, s31
	v_lshrrev_b32_e32 v76, 16, v76
	v_lshrrev_b32_e32 v77, 16, v77
	v_add3_u32 v51, v51, v87, s31
	v_add3_u32 v50, v50, v86, s31
	v_add3_u32 v49, v49, v85, s31
	v_add3_u32 v48, v48, v84, s31
	s_addc_u32 s1, s1, s25
	v_pk_mul_f32 v[74:75], v[74:75], v[44:45]
	v_bfe_u32 v92, v68, 16, 1
	v_bfe_u32 v109, v72, 16, 1
	v_bfe_u32 v110, v73, 16, 1
	v_add3_u32 v71, v71, v104, s31
	v_add3_u32 v66, v66, v93, s31
	v_and_or_b32 v37, v65, s28, v77
	v_and_or_b32 v36, v64, s28, v76
	v_lshrrev_b32_e32 v64, 16, v48
	v_lshrrev_b32_e32 v65, 16, v49
	v_lshrrev_b32_e32 v48, 16, v50
	v_lshrrev_b32_e32 v49, 16, v51
	v_lshl_add_u64 v[54:55], s[0:1], 0, v[40:41]
	v_bfe_u32 v107, v75, 16, 1
	v_bfe_u32 v108, v74, 16, 1
	v_add3_u32 v68, v68, v92, s31
	v_add3_u32 v73, v73, v110, s31
	v_add3_u32 v72, v72, v109, s31
	v_lshrrev_b32_e32 v66, 16, v66
	v_lshrrev_b32_e32 v67, 16, v67
	v_lshrrev_b32_e32 v70, 16, v70
	v_lshrrev_b32_e32 v71, 16, v71
	v_and_or_b32 v49, v57, s28, v49
	v_and_or_b32 v48, v56, s28, v48
	v_lshl_add_u64 v[56:57], v[54:55], 0, s[20:21]
	v_add_co_u32_e32 v54, vcc, s33, v54
	v_add3_u32 v74, v74, v108, s31
	v_add3_u32 v75, v75, v107, s31
	v_lshrrev_b32_e32 v72, 16, v72
	v_lshrrev_b32_e32 v73, 16, v73
	v_and_or_b32 v33, v79, s28, v71
	v_and_or_b32 v32, v78, s28, v70
	v_and_or_b32 v31, v69, s28, v67
	v_and_or_b32 v30, v68, s28, v66
	v_addc_co_u32_e32 v55, vcc, 0, v55, vcc
	v_and_or_b32 v35, v75, s28, v73
	v_and_or_b32 v34, v74, s28, v72
	global_store_dwordx4 v[54:55], v[30:33], off
	global_store_dwordx4 v[56:57], v[34:37], off offset:16
	ds_read_b64 v[30:31], v138
	v_pk_mul_f32 v[52:53], v[52:53], v[16:17]
	v_and_or_b32 v47, v47, s28, v65
	v_bfe_u32 v92, v52, 16, 1
	v_bfe_u32 v93, v53, 16, 1
	s_waitcnt lgkmcnt(0)
	v_readfirstlane_b32 s0, v30
	v_readfirstlane_b32 s1, v31
	s_add_u32 s0, s0, s24
	s_addc_u32 s1, s1, s25
	s_add_i32 s72, s72, s10
	s_add_u32 s12, s12, s16
	s_addc_u32 s13, s13, s17
	v_add3_u32 v53, v53, v93, s31
	v_add3_u32 v52, v52, v92, s31
	v_lshl_add_u64 v[30:31], s[0:1], 0, v[40:41]
	s_add_u32 s14, s14, s18
	v_lshrrev_b32_e32 v50, 16, v52
	v_lshrrev_b32_e32 v51, 16, v53
	v_lshrrev_b32_e32 v52, 16, v63
	v_lshrrev_b32_e32 v53, 16, v62
	v_lshl_add_u64 v[32:33], v[30:31], 0, s[22:23]
	v_add_co_u32_e32 v30, vcc, s33, v30
	s_addc_u32 s15, s15, s19
	v_and_or_b32 v46, v46, s28, v64
	v_and_or_b32 v53, v61, s28, v53
	v_and_or_b32 v52, v60, s28, v52
	v_and_or_b32 v51, v59, s28, v51
	v_and_or_b32 v50, v58, s28, v50
	v_addc_co_u32_e32 v31, vcc, 0, v31, vcc
	s_cmpk_lt_i32 s72, 0x4000
	global_store_dwordx4 v[32:33], v[50:53], off offset:16
	global_store_dwordx4 v[30:31], v[46:49], off offset:2048
	s_cbranch_scc1 .LBB0_1235

; __device__ __forceinline__ unsigned cvt_pk_bf16(float lo, float hi) { unsigned r; asm volatile("v_cvt_pk_bf16_f32 %0, %1, %2" : "=v"(r) : "v"(lo), "v"(hi)); return r; }
;     __device__ __forceinline__ void operator()(const f32x4 (&acc)[2][2][4][2], const Unit& u, int wr, int wc, int fr_, int fq_) const {
;     ...
;         const int row0 = u.pm * BM + wr * 64 + fr, col0 = u.pn * BM + wc * 32 + 4 * fq;
;         f32x4 gv[2][2], gm[2][2];
; #pragma unroll
;         for (int bj = 0; bj < 2; ++bj)
; #pragma unroll
;             for (int n = 0; n < 2; ++n) { gv[bj][n] = *(const f32x4*)(gate + col0 + bj * HALF + n * 16);
;                 if constexpr (EMIT) gm[bj][n] = *(const f32x4*)(gmv + col0 + bj * HALF + n * 16); else gm[bj][n] = gv[bj][n]; }
; #pragma unroll
;         for (int ai = 0; ai < 2; ++ai)
; #pragma unroll
;         for (int mh = 0; mh < 2; ++mh) {
;             f32x4 bs[2][2][2];
; #pragma unroll
;             for (int m = 0; m < 2; ++m) { const size_t off = (size_t)(row0 + ai * HALF + (2 * mh + m) * 16) * ldc + col0;
; #pragma unroll
;                 for (int bj = 0; bj < 2; ++bj)
; #pragma unroll
;                     for (int n = 0; n < 2; ++n) bs[m][bj][n] = *(const f32x4*)(base + off + bj * HALF + n * 16); }
;             asm volatile("" ::: "memory");
; #pragma unroll
;             for (int m = 0; m < 2; ++m) { const int row = row0 + ai * HALF + (2 * mh + m) * 16; const size_t off = (size_t)row * ldc + col0; float ss = 0.f;
; #pragma unroll
;                 for (int bj = 0; bj < 2; ++bj)
; #pragma unroll
;                     for (int n = 0; n < 2; ++n) { const f32x4 o = bs[m][bj][n] + gv[bj][n] * acc[ai][bj][2 * mh + m][n]; *(f32x4*)(out + off + bj * HALF + n * 16) = o;
;                         if constexpr (EMIT) { ss += (o[0] * o[0] + o[1] * o[1]) + (o[2] * o[2] + o[3] * o[3]); const f32x4 y = o * gm[bj][n];
;                             typedef unsigned u32x2_t __attribute__((ext_vector_type(2))); u32x2_t w; w.x = cvt_pk_bf16(y[0], y[1]); w.y = cvt_pk_bf16(y[2], y[3]); *(u32x2_t*)(A2 + off + bj * HALF + n * 16) = w; } }
;                 if constexpr (EMIT) { ss += __shfl_xor(ss, 16); ss += __shfl_xor(ss, 32); if (fq == 0) atomicAdd(ssq + row, (unsigned long long)(ss * 16777216.0f)); } }
.LBB0_1307:
	v_mbcnt_lo_u32_b32 v203, -1, 0
	v_mbcnt_hi_u32_b32 v203, -1, v203
	s_lshl_b32 s4, s4, 8
	v_ashrrev_i32_e32 v64, 2, v203
	s_lshl_b32 s5, s34, 8
	s_or_b32 s4, s4, s50
	v_and_b32_e32 v64, -4, v64
	s_add_i32 s5, s5, s49
	v_add_u32_e32 v188, s4, v64
	v_ashrrev_i32_e32 v189, 31, v188
	v_and_or_b32 v192, v203, 15, s5
	v_lshlrev_b64 v[64:65], 2, v[188:189]
	v_ashrrev_i32_e32 v193, 31, v192
	v_lshl_add_u64 v[190:191], s[8:9], 0, v[64:65]
	v_lshlrev_b64 v[72:73], 13, v[192:193]
	v_lshl_add_u64 v[220:221], v[190:191], 0, v[72:73]
	v_lshl_add_u64 v[66:67], s[12:13], 0, v[64:65]
	global_load_dwordx4 v[204:207], v[220:221], off nt
	global_load_dwordx4 v[104:107], v[66:67], off nt
	global_load_dwordx4 v[92:95], v[66:67], off offset:64 nt
	global_load_dwordx4 v[208:211], v[220:221], off offset:64 nt
	global_load_dwordx4 v[212:215], v[220:221], off offset:512 nt
	global_load_dwordx4 v[84:87], v[66:67], off offset:512 nt
	global_load_dwordx4 v[72:75], v[66:67], off offset:576 nt
	global_load_dwordx4 v[216:219], v[220:221], off offset:576 nt
	v_lshl_add_u64 v[64:65], s[16:17], 0, v[64:65]
	global_load_dwordx4 v[100:103], v[64:65], off nt
	global_load_dwordx4 v[88:91], v[64:65], off offset:64 nt
	global_load_dwordx4 v[80:83], v[64:65], off offset:512 nt
	s_nop 0
	global_load_dwordx4 v[64:67], v[64:65], off offset:576 nt
	v_or_b32_e32 v194, 16, v192
	v_ashrrev_i32_e32 v195, 31, v194
	v_lshlrev_b64 v[160:161], 13, v[194:195]
	v_lshl_add_u64 v[196:197], v[190:191], 0, v[160:161]
	global_load_dwordx4 v[172:175], v[196:197], off nt
	global_load_dwordx4 v[168:171], v[196:197], off offset:64 nt
	global_load_dwordx4 v[164:167], v[196:197], off offset:512 nt
	global_load_dwordx4 v[160:163], v[196:197], off offset:576 nt
	v_and_b32_e32 v223, 64, v202
	v_xor_b32_e32 v222, 16, v202
	v_add_u32_e32 v224, 64, v223
	v_cmp_lt_i32_e64 s[4:5], v222, v224
	v_cmp_gt_u32_e32 vcc, 16, v203
	s_waitcnt vmcnt(0) lgkmcnt(0)
	v_pk_fma_f32 v[158:159], v[158:159], v[106:107], v[206:207]
	v_cndmask_b32_e64 v203, v202, v222, s[4:5]
	v_lshlrev_b64 v[222:223], 11, v[192:193]
	v_pk_fma_f32 v[156:157], v[156:157], v[104:105], v[204:205]
	v_pk_fma_f32 v[154:155], v[154:155], v[94:95], v[210:211]
	v_pk_fma_f32 v[152:153], v[152:153], v[92:93], v[208:209]
	v_lshl_add_u64 v[222:223], v[222:223], 0, v[188:189]
	v_pk_fma_f32 v[150:151], v[150:151], v[86:87], v[214:215]
	v_pk_fma_f32 v[148:149], v[148:149], v[84:85], v[212:213]
	v_pk_fma_f32 v[206:207], v[146:147], v[74:75], v[218:219]
	v_pk_fma_f32 v[204:205], v[144:145], v[72:73], v[216:217]
	global_store_dwordx4 v[220:221], v[156:159], off
	v_mul_f32_e32 v218, v157, v157
	v_mul_f32_e32 v219, v159, v159
	v_pk_mul_f32 v[144:145], v[102:103], v[158:159]
	v_pk_mul_f32 v[146:147], v[100:101], v[156:157]
	v_mul_f32_e32 v157, v153, v153
	v_mul_f32_e32 v159, v155, v155
	v_lshl_add_u64 v[222:223], v[222:223], 1, s[14:15]
	v_mul_f32_e32 v225, v149, v149
	v_mul_f32_e32 v226, v151, v151
	v_fmac_f32_e32 v218, v156, v156
	v_fmac_f32_e32 v219, v158, v158
	v_cvt_pk_bf16_f32 v146, v146, v147
	v_cvt_pk_bf16_f32 v147, v144, v145
	v_fmac_f32_e32 v157, v152, v152
	v_fmac_f32_e32 v159, v154, v154
	v_mul_f32_e32 v227, v205, v205
	v_mul_f32_e32 v228, v207, v207
	v_fmac_f32_e32 v225, v148, v148
	v_fmac_f32_e32 v226, v150, v150
	v_add_f32_e32 v156, v218, v219
	global_store_dwordx2 v[222:223], v[146:147], off
	global_store_dwordx4 v[220:221], v[152:155], off offset:64
	v_add_f32_e32 v146, v157, v159
	v_pk_mul_f32 v[208:209], v[90:91], v[154:155]
	v_pk_mul_f32 v[210:211], v[88:89], v[152:153]
	v_fmac_f32_e32 v227, v204, v204
	v_fmac_f32_e32 v228, v206, v206
	v_cvt_pk_bf16_f32 v144, v210, v211
	v_cvt_pk_bf16_f32 v145, v208, v209
	v_add_f32_e32 v147, v225, v226
	v_add_f32_e32 v146, v156, v146
	v_add_f32_e32 v152, v227, v228
	global_store_dwordx2 v[222:223], v[144:145], off offset:32
	global_store_dwordx4 v[220:221], v[148:151], off offset:512
	v_add_f32_e32 v144, v146, v147
	v_lshlrev_b32_e32 v203, 2, v203
	v_add_f32_e32 v146, v144, v152
	ds_bpermute_b32 v147, v203, v146
	v_pk_mul_f32 v[212:213], v[82:83], v[150:151]
	v_pk_mul_f32 v[214:215], v[80:81], v[148:149]
	v_pk_mul_f32 v[216:217], v[66:67], v[206:207]
	v_cvt_pk_bf16_f32 v144, v214, v215
	v_cvt_pk_bf16_f32 v145, v212, v213
	global_store_dwordx2 v[222:223], v[144:145], off offset:256
	global_store_dwordx4 v[220:221], v[204:207], off offset:576
	v_xor_b32_e32 v145, 32, v202
	v_cmp_lt_i32_e64 s[4:5], v145, v224
	s_waitcnt lgkmcnt(0)
	v_add_f32_e32 v144, v146, v147
	v_pk_mul_f32 v[146:147], v[64:65], v[204:205]
	v_cndmask_b32_e64 v145, v202, v145, s[4:5]
	v_lshlrev_b32_e32 v150, 2, v145
	ds_bpermute_b32 v145, v150, v144
	v_cvt_pk_bf16_f32 v146, v146, v147
	v_cvt_pk_bf16_f32 v147, v216, v217
	global_store_dwordx2 v[222:223], v[146:147], off offset:288
	s_and_saveexec_b64 s[4:5], vcc
	s_cbranch_execz .LBB0_1309
	s_waitcnt lgkmcnt(0)
	v_add_f32_e32 v144, v144, v145
	v_mul_f32_e32 v144, 0x4b800000, v144
	v_trunc_f32_e32 v144, v144
	v_mul_f32_e32 v145, 0x2f800000, v144
	v_floor_f32_e32 v145, v145
	v_fmac_f32_e32 v144, 0xcf800000, v145
	v_cvt_u32_f32_e32 v144, v144
	v_cvt_u32_f32_e32 v145, v145
	v_mov_b32_e32 v230, v144
	v_mov_b32_e32 v231, v145
	v_lshl_add_u64 v[246:247], v[192:193], 3, s[18:19]

; __device__ __forceinline__ unsigned cvt_pk_bf16(float lo, float hi) { unsigned r; asm volatile("v_cvt_pk_bf16_f32 %0, %1, %2" : "=v"(r) : "v"(lo), "v"(hi)); return r; }
;     __device__ __forceinline__ void operator()(const f32x4 (&acc)[2][2][4][2], const Unit& u, int wr, int wc, int fr_, int fq_) const {
;     ...
;         for (int mh = 0; mh < 2; ++mh) {
;             f32x4 bs[2][2][2];
; #pragma unroll
;             for (int m = 0; m < 2; ++m) { const size_t off = (size_t)(row0 + ai * HALF + (2 * mh + m) * 16) * ldc + col0;
; #pragma unroll
;                 for (int bj = 0; bj < 2; ++bj)
; #pragma unroll
;                     for (int n = 0; n < 2; ++n) bs[m][bj][n] = *(const f32x4*)(base + off + bj * HALF + n * 16); }
;             asm volatile("" ::: "memory");
; #pragma unroll
;             for (int m = 0; m < 2; ++m) { const int row = row0 + ai * HALF + (2 * mh + m) * 16; const size_t off = (size_t)row * ldc + col0; float ss = 0.f;
; #pragma unroll
;                 for (int bj = 0; bj < 2; ++bj)
; #pragma unroll
;                     for (int n = 0; n < 2; ++n) { const f32x4 o = bs[m][bj][n] + gv[bj][n] * acc[ai][bj][2 * mh + m][n]; *(f32x4*)(out + off + bj * HALF + n * 16) = o;
;                         if constexpr (EMIT) { ss += (o[0] * o[0] + o[1] * o[1]) + (o[2] * o[2] + o[3] * o[3]); const f32x4 y = o * gm[bj][n];
;                             typedef unsigned u32x2_t __attribute__((ext_vector_type(2))); u32x2_t w; w.x = cvt_pk_bf16(y[0], y[1]); w.y = cvt_pk_bf16(y[2], y[3]); *(u32x2_t*)(A2 + off + bj * HALF + n * 16) = w; } }
;                 if constexpr (EMIT) { ss += __shfl_xor(ss, 16); ss += __shfl_xor(ss, 32); if (fq == 0) atomicAdd(ssq + row, (unsigned long long)(ss * 16777216.0f)); } }
.LBB0_1311:
	s_or_b64 exec, exec, s[4:5]
	v_or_b32_e32 v148, 32, v192
	v_ashrrev_i32_e32 v149, 31, v148
	s_waitcnt lgkmcnt(0)
	v_lshlrev_b64 v[128:129], 13, v[148:149]
	v_lshl_add_u64 v[168:169], v[190:191], 0, v[128:129]
	global_load_dwordx4 v[152:155], v[168:169], off nt
	global_load_dwordx4 v[156:159], v[168:169], off offset:64 nt
	global_load_dwordx4 v[160:163], v[168:169], off offset:512 nt
	global_load_dwordx4 v[164:167], v[168:169], off offset:576 nt
	v_or_b32_e32 v144, 48, v192
	v_ashrrev_i32_e32 v145, 31, v144
	v_lshlrev_b64 v[128:129], 13, v[144:145]
	v_lshl_add_u64 v[146:147], v[190:191], 0, v[128:129]
	global_load_dwordx4 v[140:143], v[146:147], off nt
	global_load_dwordx4 v[136:139], v[146:147], off offset:64 nt
	global_load_dwordx4 v[132:135], v[146:147], off offset:512 nt
	global_load_dwordx4 v[128:131], v[146:147], off offset:576 nt
	v_lshlrev_b64 v[170:171], 11, v[148:149]
	v_lshl_add_u64 v[170:171], v[170:171], 0, v[188:189]
	v_lshl_add_u64 v[170:171], v[170:171], 1, s[14:15]
	s_waitcnt vmcnt(0) lgkmcnt(0)
	v_pk_fma_f32 v[126:127], v[126:127], v[106:107], v[154:155]
	v_pk_fma_f32 v[124:125], v[124:125], v[104:105], v[152:153]
	v_pk_fma_f32 v[122:123], v[122:123], v[94:95], v[158:159]
	v_pk_fma_f32 v[120:121], v[120:121], v[92:93], v[156:157]
	v_pk_fma_f32 v[118:119], v[118:119], v[86:87], v[162:163]
	v_pk_fma_f32 v[116:117], v[116:117], v[84:85], v[160:161]
	v_pk_fma_f32 v[154:155], v[114:115], v[74:75], v[166:167]
	v_pk_fma_f32 v[152:153], v[112:113], v[72:73], v[164:165]
	global_store_dwordx4 v[168:169], v[124:127], off
	v_mul_f32_e32 v151, v125, v125
	v_mul_f32_e32 v164, v127, v127
	v_pk_mul_f32 v[112:113], v[102:103], v[126:127]
	v_pk_mul_f32 v[114:115], v[100:101], v[124:125]
	v_mul_f32_e32 v125, v121, v121
	v_mul_f32_e32 v127, v123, v123
	v_mul_f32_e32 v165, v117, v117
	v_mul_f32_e32 v166, v119, v119
	v_fmac_f32_e32 v151, v124, v124
	v_fmac_f32_e32 v164, v126, v126
	v_cvt_pk_bf16_f32 v114, v114, v115
	v_cvt_pk_bf16_f32 v115, v112, v113
	v_fmac_f32_e32 v125, v120, v120
	v_fmac_f32_e32 v127, v122, v122
	v_mul_f32_e32 v167, v153, v153
	v_mul_f32_e32 v172, v155, v155
	v_fmac_f32_e32 v165, v116, v116
	v_fmac_f32_e32 v166, v118, v118
	v_add_f32_e32 v124, v151, v164
	global_store_dwordx2 v[170:171], v[114:115], off
	global_store_dwordx4 v[168:169], v[120:123], off offset:64
	v_add_f32_e32 v114, v125, v127
	v_pk_mul_f32 v[156:157], v[90:91], v[122:123]
	v_pk_mul_f32 v[158:159], v[88:89], v[120:121]
	v_fmac_f32_e32 v167, v152, v152
	v_fmac_f32_e32 v172, v154, v154
	v_cvt_pk_bf16_f32 v112, v158, v159
	v_cvt_pk_bf16_f32 v113, v156, v157
	v_add_f32_e32 v115, v165, v166
	v_add_f32_e32 v114, v124, v114
	global_store_dwordx2 v[170:171], v[112:113], off offset:32
	global_store_dwordx4 v[168:169], v[116:119], off offset:512
	v_add_f32_e32 v113, v114, v115
	v_add_f32_e32 v114, v167, v172
	v_pk_mul_f32 v[162:163], v[80:81], v[116:117]
	v_add_f32_e32 v116, v113, v114
	ds_bpermute_b32 v117, v203, v116
	v_pk_mul_f32 v[160:161], v[82:83], v[118:119]
	v_cvt_pk_bf16_f32 v112, v162, v163
	v_pk_mul_f32 v[114:115], v[66:67], v[154:155]
	v_cvt_pk_bf16_f32 v113, v160, v161
	global_store_dwordx2 v[170:171], v[112:113], off offset:256
	global_store_dwordx4 v[168:169], v[152:155], off offset:576
	s_waitcnt lgkmcnt(0)
	v_add_f32_e32 v112, v116, v117
	ds_bpermute_b32 v113, v150, v112
	v_pk_mul_f32 v[116:117], v[64:65], v[152:153]
	s_nop 0
	v_cvt_pk_bf16_f32 v116, v116, v117
	v_cvt_pk_bf16_f32 v117, v114, v115
	global_store_dwordx2 v[170:171], v[116:117], off offset:288
	s_and_saveexec_b64 s[4:5], vcc
	s_cbranch_execz .LBB0_1313
	s_waitcnt lgkmcnt(0)
	v_add_f32_e32 v112, v112, v113
	v_mul_f32_e32 v112, 0x4b800000, v112
	v_trunc_f32_e32 v112, v112
	v_mul_f32_e32 v113, 0x2f800000, v112
	v_floor_f32_e32 v113, v113
	v_fmac_f32_e32 v112, 0xcf800000, v113
	v_cvt_u32_f32_e32 v112, v112
	v_cvt_u32_f32_e32 v113, v113
	v_mov_b32_e32 v234, v112
	v_mov_b32_e32 v235, v113

; __device__ __forceinline__ unsigned cvt_pk_bf16(float lo, float hi) { unsigned r; asm volatile("v_cvt_pk_bf16_f32 %0, %1, %2" : "=v"(r) : "v"(lo), "v"(hi)); return r; }
;     __device__ __forceinline__ void operator()(const f32x4 (&acc)[2][2][4][2], const Unit& u, int wr, int wc, int fr_, int fq_) const {
;     ...
;         for (int mh = 0; mh < 2; ++mh) {
;             f32x4 bs[2][2][2];
; #pragma unroll
;             for (int m = 0; m < 2; ++m) { const size_t off = (size_t)(row0 + ai * HALF + (2 * mh + m) * 16) * ldc + col0;
; #pragma unroll
;                 for (int bj = 0; bj < 2; ++bj)
; #pragma unroll
;                     for (int n = 0; n < 2; ++n) bs[m][bj][n] = *(const f32x4*)(base + off + bj * HALF + n * 16); }
;             asm volatile("" ::: "memory");
; #pragma unroll
;             for (int m = 0; m < 2; ++m) { const int row = row0 + ai * HALF + (2 * mh + m) * 16; const size_t off = (size_t)row * ldc + col0; float ss = 0.f;
; #pragma unroll
;                 for (int bj = 0; bj < 2; ++bj)
; #pragma unroll
;                     for (int n = 0; n < 2; ++n) { const f32x4 o = bs[m][bj][n] + gv[bj][n] * acc[ai][bj][2 * mh + m][n]; *(f32x4*)(out + off + bj * HALF + n * 16) = o;
;                         if constexpr (EMIT) { ss += (o[0] * o[0] + o[1] * o[1]) + (o[2] * o[2] + o[3] * o[3]); const f32x4 y = o * gm[bj][n];
;                             typedef unsigned u32x2_t __attribute__((ext_vector_type(2))); u32x2_t w; w.x = cvt_pk_bf16(y[0], y[1]); w.y = cvt_pk_bf16(y[2], y[3]); *(u32x2_t*)(A2 + off + bj * HALF + n * 16) = w; } }
;                 if constexpr (EMIT) { ss += __shfl_xor(ss, 16); ss += __shfl_xor(ss, 32); if (fq == 0) atomicAdd(ssq + row, (unsigned long long)(ss * 16777216.0f)); } }
.LBB0_1315:
	s_or_b64 exec, exec, s[4:5]
	v_add_u32_e32 v116, 0x80, v192
	v_ashrrev_i32_e32 v117, 31, v116
	s_waitcnt lgkmcnt(0)
	v_lshlrev_b64 v[68:69], 13, v[116:117]
	v_lshl_add_u64 v[134:135], v[190:191], 0, v[68:69]
	global_load_dwordx4 v[118:121], v[134:135], off nt
	global_load_dwordx4 v[122:125], v[134:135], off offset:64 nt
	global_load_dwordx4 v[126:129], v[134:135], off offset:512 nt
	global_load_dwordx4 v[130:133], v[134:135], off offset:576 nt
	v_add_u32_e32 v112, 0x90, v192
	v_ashrrev_i32_e32 v113, 31, v112
	v_lshlrev_b64 v[68:69], 13, v[112:113]
	v_lshl_add_u64 v[114:115], v[190:191], 0, v[68:69]
	global_load_dwordx4 v[108:111], v[114:115], off nt
	global_load_dwordx4 v[96:99], v[114:115], off offset:64 nt
	global_load_dwordx4 v[76:79], v[114:115], off offset:512 nt
	global_load_dwordx4 v[68:71], v[114:115], off offset:576 nt
	v_lshlrev_b64 v[136:137], 11, v[116:117]
	v_lshl_add_u64 v[136:137], v[136:137], 0, v[188:189]
	v_lshl_add_u64 v[136:137], v[136:137], 1, s[14:15]
	s_waitcnt vmcnt(0) lgkmcnt(0)
	v_pk_fma_f32 v[62:63], v[62:63], v[106:107], v[120:121]
	v_pk_fma_f32 v[60:61], v[60:61], v[104:105], v[118:119]
	v_pk_fma_f32 v[58:59], v[58:59], v[94:95], v[124:125]
	v_pk_fma_f32 v[56:57], v[56:57], v[92:93], v[122:123]
	v_pk_fma_f32 v[54:55], v[54:55], v[86:87], v[128:129]
	v_pk_fma_f32 v[52:53], v[52:53], v[84:85], v[126:127]
	v_pk_fma_f32 v[120:121], v[50:51], v[74:75], v[132:133]
	v_pk_fma_f32 v[118:119], v[48:49], v[72:73], v[130:131]
	global_store_dwordx4 v[134:135], v[60:63], off
	v_mul_f32_e32 v130, v61, v61
	v_mul_f32_e32 v131, v63, v63
	v_pk_mul_f32 v[48:49], v[102:103], v[62:63]
	v_pk_mul_f32 v[50:51], v[100:101], v[60:61]
	v_mul_f32_e32 v61, v57, v57
	v_mul_f32_e32 v63, v59, v59
	v_mul_f32_e32 v132, v53, v53
	v_mul_f32_e32 v133, v55, v55
	v_fmac_f32_e32 v130, v60, v60
	v_fmac_f32_e32 v131, v62, v62
	v_cvt_pk_bf16_f32 v50, v50, v51
	v_cvt_pk_bf16_f32 v51, v48, v49
	v_fmac_f32_e32 v61, v56, v56
	v_fmac_f32_e32 v63, v58, v58
	v_mul_f32_e32 v138, v119, v119
	v_mul_f32_e32 v139, v121, v121
	v_fmac_f32_e32 v132, v52, v52
	v_fmac_f32_e32 v133, v54, v54
	v_add_f32_e32 v60, v130, v131
	global_store_dwordx2 v[136:137], v[50:51], off
	global_store_dwordx4 v[134:135], v[56:59], off offset:64
	v_add_f32_e32 v50, v61, v63
	v_pk_mul_f32 v[122:123], v[90:91], v[58:59]
	v_pk_mul_f32 v[124:125], v[88:89], v[56:57]
	v_fmac_f32_e32 v138, v118, v118
	v_fmac_f32_e32 v139, v120, v120
	v_cvt_pk_bf16_f32 v48, v124, v125
	v_cvt_pk_bf16_f32 v49, v122, v123
	v_add_f32_e32 v51, v132, v133
	v_add_f32_e32 v50, v60, v50
	global_store_dwordx2 v[136:137], v[48:49], off offset:32
	global_store_dwordx4 v[134:135], v[52:55], off offset:512
	v_add_f32_e32 v49, v50, v51
	v_add_f32_e32 v50, v138, v139
	v_pk_mul_f32 v[128:129], v[80:81], v[52:53]
	v_add_f32_e32 v52, v49, v50
	ds_bpermute_b32 v53, v203, v52
	v_pk_mul_f32 v[126:127], v[82:83], v[54:55]
	v_cvt_pk_bf16_f32 v48, v128, v129
	v_pk_mul_f32 v[50:51], v[66:67], v[120:121]
	v_cvt_pk_bf16_f32 v49, v126, v127
	global_store_dwordx2 v[136:137], v[48:49], off offset:256
	global_store_dwordx4 v[134:135], v[118:121], off offset:576
	s_waitcnt lgkmcnt(0)
	v_add_f32_e32 v48, v52, v53
	ds_bpermute_b32 v49, v150, v48
	v_pk_mul_f32 v[52:53], v[64:65], v[118:119]
	s_nop 0
	v_cvt_pk_bf16_f32 v52, v52, v53
	v_cvt_pk_bf16_f32 v53, v50, v51
	global_store_dwordx2 v[136:137], v[52:53], off offset:288
	s_and_saveexec_b64 s[4:5], vcc
	s_cbranch_execz .LBB0_1317
	s_waitcnt lgkmcnt(0)
	v_add_f32_e32 v48, v48, v49
	v_mul_f32_e32 v48, 0x4b800000, v48
	v_trunc_f32_e32 v48, v48
	v_mul_f32_e32 v49, 0x2f800000, v48
	v_floor_f32_e32 v49, v49
	v_fmac_f32_e32 v48, 0xcf800000, v49
	v_cvt_u32_f32_e32 v48, v48
	v_cvt_u32_f32_e32 v49, v49
	v_mov_b32_e32 v238, v48
	v_mov_b32_e32 v239, v49

; __device__ __forceinline__ unsigned cvt_pk_bf16(float lo, float hi) { unsigned r; asm volatile("v_cvt_pk_bf16_f32 %0, %1, %2" : "=v"(r) : "v"(lo), "v"(hi)); return r; }
;     __device__ __forceinline__ void operator()(const f32x4 (&acc)[2][2][4][2], const Unit& u, int wr, int wc, int fr_, int fq_) const {
;     ...
;         for (int mh = 0; mh < 2; ++mh) {
;             f32x4 bs[2][2][2];
; #pragma unroll
;             for (int m = 0; m < 2; ++m) { const size_t off = (size_t)(row0 + ai * HALF + (2 * mh + m) * 16) * ldc + col0;
; #pragma unroll
;                 for (int bj = 0; bj < 2; ++bj)
; #pragma unroll
;                     for (int n = 0; n < 2; ++n) bs[m][bj][n] = *(const f32x4*)(base + off + bj * HALF + n * 16); }
;             asm volatile("" ::: "memory");
; #pragma unroll
;             for (int m = 0; m < 2; ++m) { const int row = row0 + ai * HALF + (2 * mh + m) * 16; const size_t off = (size_t)row * ldc + col0; float ss = 0.f;
; #pragma unroll
;                 for (int bj = 0; bj < 2; ++bj)
; #pragma unroll
;                     for (int n = 0; n < 2; ++n) { const f32x4 o = bs[m][bj][n] + gv[bj][n] * acc[ai][bj][2 * mh + m][n]; *(f32x4*)(out + off + bj * HALF + n * 16) = o;
;                         if constexpr (EMIT) { ss += (o[0] * o[0] + o[1] * o[1]) + (o[2] * o[2] + o[3] * o[3]); const f32x4 y = o * gm[bj][n];
;                             typedef unsigned u32x2_t __attribute__((ext_vector_type(2))); u32x2_t w; w.x = cvt_pk_bf16(y[0], y[1]); w.y = cvt_pk_bf16(y[2], y[3]); *(u32x2_t*)(A2 + off + bj * HALF + n * 16) = w; } }
;                 if constexpr (EMIT) { ss += __shfl_xor(ss, 16); ss += __shfl_xor(ss, 32); if (fq == 0) atomicAdd(ssq + row, (unsigned long long)(ss * 16777216.0f)); } }
.LBB0_1319:
	s_or_b64 exec, exec, s[4:5]
	v_add_u32_e32 v52, 0xa0, v192
	v_ashrrev_i32_e32 v53, 31, v52
	s_waitcnt lgkmcnt(0)
	v_lshlrev_b64 v[32:33], 13, v[52:53]
	v_lshl_add_u64 v[62:63], v[190:191], 0, v[32:33]
	global_load_dwordx4 v[54:57], v[62:63], off nt
	global_load_dwordx4 v[58:61], v[62:63], off offset:64 nt
	global_load_dwordx4 v[68:71], v[62:63], off offset:512 nt
	global_load_dwordx4 v[76:79], v[62:63], off offset:576 nt
	v_add_u32_e32 v48, 0xb0, v192
	v_ashrrev_i32_e32 v49, 31, v48
	v_lshlrev_b64 v[32:33], 13, v[48:49]
	v_lshl_add_u64 v[50:51], v[190:191], 0, v[32:33]
	global_load_dwordx4 v[44:47], v[50:51], off nt
	global_load_dwordx4 v[40:43], v[50:51], off offset:64 nt
	global_load_dwordx4 v[36:39], v[50:51], off offset:512 nt
	global_load_dwordx4 v[32:35], v[50:51], off offset:576 nt
	v_lshlrev_b64 v[96:97], 11, v[52:53]
	v_lshl_add_u64 v[96:97], v[96:97], 0, v[188:189]
	v_lshl_add_u64 v[96:97], v[96:97], 1, s[14:15]
	s_waitcnt vmcnt(0) lgkmcnt(0)
	v_pk_fma_f32 v[30:31], v[30:31], v[106:107], v[56:57]
	v_pk_fma_f32 v[28:29], v[28:29], v[104:105], v[54:55]
	v_pk_fma_f32 v[26:27], v[26:27], v[94:95], v[60:61]
	v_pk_fma_f32 v[24:25], v[24:25], v[92:93], v[58:59]
	v_pk_fma_f32 v[22:23], v[22:23], v[86:87], v[70:71]
	v_pk_fma_f32 v[20:21], v[20:21], v[84:85], v[68:69]
	v_pk_fma_f32 v[56:57], v[18:19], v[74:75], v[78:79]
	v_pk_fma_f32 v[54:55], v[16:17], v[72:73], v[76:77]
	global_store_dwordx4 v[62:63], v[28:31], off
	v_mul_f32_e32 v76, v29, v29
	v_mul_f32_e32 v77, v31, v31
	v_pk_mul_f32 v[16:17], v[102:103], v[30:31]
	v_pk_mul_f32 v[18:19], v[100:101], v[28:29]
	v_mul_f32_e32 v29, v25, v25
	v_mul_f32_e32 v31, v27, v27
	v_mul_f32_e32 v78, v21, v21
	v_mul_f32_e32 v79, v23, v23
	v_fmac_f32_e32 v76, v28, v28
	v_fmac_f32_e32 v77, v30, v30
	v_cvt_pk_bf16_f32 v18, v18, v19
	v_cvt_pk_bf16_f32 v19, v16, v17
	v_fmac_f32_e32 v29, v24, v24
	v_fmac_f32_e32 v31, v26, v26
	v_mul_f32_e32 v98, v55, v55
	v_mul_f32_e32 v99, v57, v57
	v_fmac_f32_e32 v78, v20, v20
	v_fmac_f32_e32 v79, v22, v22
	v_add_f32_e32 v28, v76, v77
	global_store_dwordx2 v[96:97], v[18:19], off
	global_store_dwordx4 v[62:63], v[24:27], off offset:64
	v_add_f32_e32 v18, v29, v31
	v_pk_mul_f32 v[58:59], v[90:91], v[26:27]
	v_pk_mul_f32 v[60:61], v[88:89], v[24:25]
	v_fmac_f32_e32 v98, v54, v54
	v_fmac_f32_e32 v99, v56, v56
	v_cvt_pk_bf16_f32 v16, v60, v61
	v_cvt_pk_bf16_f32 v17, v58, v59
	v_add_f32_e32 v19, v78, v79
	v_add_f32_e32 v18, v28, v18
	global_store_dwordx2 v[96:97], v[16:17], off offset:32
	global_store_dwordx4 v[62:63], v[20:23], off offset:512
	v_add_f32_e32 v17, v18, v19
	v_add_f32_e32 v18, v98, v99
	v_pk_mul_f32 v[70:71], v[80:81], v[20:21]
	v_add_f32_e32 v20, v17, v18
	ds_bpermute_b32 v21, v203, v20
	v_pk_mul_f32 v[68:69], v[82:83], v[22:23]
	v_cvt_pk_bf16_f32 v16, v70, v71
	v_pk_mul_f32 v[18:19], v[66:67], v[56:57]
	v_cvt_pk_bf16_f32 v17, v68, v69
	global_store_dwordx2 v[96:97], v[16:17], off offset:256
	global_store_dwordx4 v[62:63], v[54:57], off offset:576
	s_waitcnt lgkmcnt(0)
	v_add_f32_e32 v16, v20, v21
	ds_bpermute_b32 v17, v150, v16
	v_pk_mul_f32 v[20:21], v[64:65], v[54:55]
	s_nop 0
	v_cvt_pk_bf16_f32 v20, v20, v21
	v_cvt_pk_bf16_f32 v21, v18, v19
	global_store_dwordx2 v[96:97], v[20:21], off offset:288
	s_and_saveexec_b64 s[4:5], vcc
	s_cbranch_execz .LBB0_1321
	s_waitcnt lgkmcnt(0)
	v_add_f32_e32 v16, v16, v17
	v_mul_f32_e32 v16, 0x4b800000, v16
	v_trunc_f32_e32 v16, v16
	v_mul_f32_e32 v17, 0x2f800000, v16
	v_floor_f32_e32 v17, v17
	v_fmac_f32_e32 v16, 0xcf800000, v17
	v_cvt_u32_f32_e32 v16, v16
	v_cvt_u32_f32_e32 v17, v17
	v_mov_b32_e32 v242, v16
	v_mov_b32_e32 v243, v17

;     __device__ __forceinline__ void operator()(const f32x4 (&acc)[2][2][4][2], const Unit& u, int wr, int wc, int fr_, int fq_) const {
;     ...
;         const int row0 = u.pm * BM + wr * 64 + fr, col0 = u.pn * BM + wc * 32 + 4 * fq;
;         f32x4 gv[2][2], gm[2][2];
; #pragma unroll
;         for (int bj = 0; bj < 2; ++bj)
; #pragma unroll
;             for (int n = 0; n < 2; ++n) { gv[bj][n] = *(const f32x4*)(gate + col0 + bj * HALF + n * 16);
;                 if constexpr (EMIT) gm[bj][n] = *(const f32x4*)(gmv + col0 + bj * HALF + n * 16); else gm[bj][n] = gv[bj][n]; }
; #pragma unroll
;         for (int ai = 0; ai < 2; ++ai)
; #pragma unroll
;         for (int mh = 0; mh < 2; ++mh) {
;             f32x4 bs[2][2][2];
; #pragma unroll
;             for (int m = 0; m < 2; ++m) { const size_t off = (size_t)(row0 + ai * HALF + (2 * mh + m) * 16) * ldc + col0;
; #pragma unroll
;                 for (int bj = 0; bj < 2; ++bj)
; #pragma unroll
;                     for (int n = 0; n < 2; ++n) bs[m][bj][n] = *(const f32x4*)(base + off + bj * HALF + n * 16); }
;             asm volatile("" ::: "memory");
; #pragma unroll
;             for (int m = 0; m < 2; ++m) { const int row = row0 + ai * HALF + (2 * mh + m) * 16; const size_t off = (size_t)row * ldc + col0; float ss = 0.f;
; #pragma unroll
;                 for (int bj = 0; bj < 2; ++bj)
; #pragma unroll
;                     for (int n = 0; n < 2; ++n) { const f32x4 o = bs[m][bj][n] + gv[bj][n] * acc[ai][bj][2 * mh + m][n]; *(f32x4*)(out + off + bj * HALF + n * 16) = o;
.LBB0_1465:
	v_mbcnt_lo_u32_b32 v158, -1, 0
	v_mbcnt_hi_u32_b32 v158, -1, v158
	s_lshl_b32 s26, s54, 8
	s_lshl_b32 s27, s55, 8
	v_ashrrev_i32_e32 v128, 2, v158
	s_add_i32 s26, s26, s45
	s_or_b32 s27, s27, s46
	v_and_b32_e32 v128, -4, v128
	v_add_u32_e32 v128, s27, v128
	v_and_or_b32 v198, v158, 15, s26
	v_ashrrev_i32_e32 v129, 31, v128
	v_or_b32_e32 v182, 16, v198
	v_lshlrev_b64 v[156:157], 2, v[128:129]
	v_ashrrev_i32_e32 v199, 31, v198
	v_ashrrev_i32_e32 v183, 31, v182
	v_lshl_add_u64 v[158:159], s[6:7], 0, v[156:157]
	v_lshlrev_b64 v[160:161], 13, v[198:199]
	v_lshlrev_b64 v[200:201], 13, v[182:183]
	v_lshl_add_u64 v[128:129], s[12:13], 0, v[156:157]
	v_lshl_add_u64 v[178:179], v[158:159], 0, v[160:161]
	v_lshl_add_u64 v[194:195], v[158:159], 0, v[200:201]
	global_load_dwordx4 v[140:143], v[128:129], off nt
	global_load_dwordx4 v[136:139], v[128:129], off offset:64 nt
	global_load_dwordx4 v[132:135], v[128:129], off offset:512 nt
	s_nop 0
	global_load_dwordx4 v[128:131], v[128:129], off offset:576 nt
	s_nop 0
	global_load_dwordx4 v[166:169], v[178:179], off nt
	global_load_dwordx4 v[170:173], v[178:179], off offset:64 nt
	global_load_dwordx4 v[174:177], v[178:179], off offset:512 nt
	s_nop 0
	global_load_dwordx4 v[178:181], v[178:179], off offset:576 nt
	s_nop 0
	global_load_dwordx4 v[182:185], v[194:195], off nt
	global_load_dwordx4 v[186:189], v[194:195], off offset:64 nt
	global_load_dwordx4 v[190:193], v[194:195], off offset:512 nt
	s_nop 0
	global_load_dwordx4 v[194:197], v[194:195], off offset:576 nt
	v_lshl_add_u64 v[204:205], s[6:7], 0, v[160:161]
	v_or_b32_e32 v202, 32, v198
	v_lshl_add_u64 v[204:205], v[204:205], 0, v[156:157]
	v_lshl_add_u64 v[200:201], s[6:7], 0, v[200:201]
	v_ashrrev_i32_e32 v203, 31, v202
	v_lshl_add_u64 v[200:201], v[200:201], 0, v[156:157]
	v_lshlrev_b64 v[202:203], 13, v[202:203]
	v_lshl_add_u64 v[206:207], v[158:159], 0, v[202:203]
	s_and_b64 vcc, exec, s[0:1]
	s_mov_b64 s[0:1], -1
	s_waitcnt vmcnt(0) lgkmcnt(0)
	v_pk_fma_f32 v[126:127], v[126:127], v[142:143], v[168:169]
	v_pk_fma_f32 v[124:125], v[124:125], v[140:141], v[166:167]
	v_pk_fma_f32 v[108:109], v[108:109], v[132:133], v[174:175]
	v_pk_fma_f32 v[122:123], v[122:123], v[138:139], v[172:173]
	v_pk_fma_f32 v[120:121], v[120:121], v[136:137], v[170:171]
	v_pk_fma_f32 v[110:111], v[110:111], v[134:135], v[176:177]
	v_pk_fma_f32 v[106:107], v[106:107], v[130:131], v[180:181]
	v_pk_fma_f32 v[104:105], v[104:105], v[128:129], v[178:179]
	v_pk_fma_f32 v[118:119], v[118:119], v[142:143], v[184:185]
	v_pk_fma_f32 v[116:117], v[116:117], v[140:141], v[182:183]
	v_pk_fma_f32 v[114:115], v[114:115], v[138:139], v[188:189]
	v_pk_fma_f32 v[112:113], v[112:113], v[136:137], v[186:187]
	v_pk_fma_f32 v[102:103], v[102:103], v[134:135], v[192:193]
	v_pk_fma_f32 v[100:101], v[100:101], v[132:133], v[190:191]
	v_pk_fma_f32 v[98:99], v[98:99], v[130:131], v[196:197]
	v_pk_fma_f32 v[96:97], v[96:97], v[128:129], v[194:195]
	global_store_dwordx4 v[204:205], v[124:127], off
	global_store_dwordx4 v[204:205], v[120:123], off offset:64
	global_store_dwordx4 v[204:205], v[108:111], off offset:512
	global_store_dwordx4 v[204:205], v[104:107], off offset:576
	global_store_dwordx4 v[200:201], v[116:119], off
	global_store_dwordx4 v[200:201], v[112:115], off offset:64
	global_store_dwordx4 v[200:201], v[100:103], off offset:512
	global_store_dwordx4 v[200:201], v[96:99], off offset:576
	v_or_b32_e32 v108, 48, v198
	v_ashrrev_i32_e32 v109, 31, v108
	v_lshlrev_b64 v[166:167], 13, v[108:109]
	global_load_dwordx4 v[96:99], v[206:207], off nt
	global_load_dwordx4 v[100:103], v[206:207], off offset:64 nt
	v_lshl_add_u64 v[124:125], v[158:159], 0, v[166:167]
	global_load_dwordx4 v[104:107], v[206:207], off offset:512 nt
	global_load_dwordx4 v[108:111], v[206:207], off offset:576 nt
	global_load_dwordx4 v[112:115], v[124:125], off nt
	global_load_dwordx4 v[116:119], v[124:125], off offset:64 nt
	global_load_dwordx4 v[120:123], v[124:125], off offset:512 nt
	s_nop 0
	global_load_dwordx4 v[124:127], v[124:125], off offset:576 nt
	v_lshl_add_u64 v[170:171], s[6:7], 0, v[202:203]
	v_lshl_add_u64 v[166:167], s[6:7], 0, v[166:167]
	v_lshl_add_u64 v[170:171], v[170:171], 0, v[156:157]
	v_lshl_add_u64 v[168:169], v[160:161], 0, s[18:19]
	v_lshl_add_u64 v[166:167], v[166:167], 0, v[156:157]
	v_lshl_add_u64 v[172:173], v[158:159], 0, v[168:169]
	s_waitcnt vmcnt(0) lgkmcnt(0)
; __device__ __forceinline__ unsigned cvt_pk_bf16(float lo, float hi) { unsigned r; asm volatile("v_cvt_pk_bf16_f32 %0, %1, %2" : "=v"(r) : "v"(lo), "v"(hi)); return r; }
;     __device__ __forceinline__ void operator()(const f32x4 (&acc)[2][2][4][2], const Unit& u, int wr, int wc, int fr_, int fq_) const {
;     ...
;         for (int ai = 0; ai < 2; ++ai)
; #pragma unroll
;         for (int mh = 0; mh < 2; ++mh) {
;             f32x4 bs[2][2][2];
; #pragma unroll
;             for (int m = 0; m < 2; ++m) { const size_t off = (size_t)(row0 + ai * HALF + (2 * mh + m) * 16) * ldc + col0;
; #pragma unroll
;                 for (int bj = 0; bj < 2; ++bj)
; #pragma unroll
;                     for (int n = 0; n < 2; ++n) bs[m][bj][n] = *(const f32x4*)(base + off + bj * HALF + n * 16); }
;             asm volatile("" ::: "memory");
; #pragma unroll
;             for (int m = 0; m < 2; ++m) { const int row = row0 + ai * HALF + (2 * mh + m) * 16; const size_t off = (size_t)row * ldc + col0; float ss = 0.f;
; #pragma unroll
;                 for (int bj = 0; bj < 2; ++bj)
; #pragma unroll
;                     for (int n = 0; n < 2; ++n) { const f32x4 o = bs[m][bj][n] + gv[bj][n] * acc[ai][bj][2 * mh + m][n]; *(f32x4*)(out + off + bj * HALF + n * 16) = o;
;                         if constexpr (EMIT) { ss += (o[0] * o[0] + o[1] * o[1]) + (o[2] * o[2] + o[3] * o[3]); const f32x4 y = o * gm[bj][n];
;                             typedef unsigned u32x2_t __attribute__((ext_vector_type(2))); u32x2_t w; w.x = cvt_pk_bf16(y[0], y[1]); w.y = cvt_pk_bf16(y[2], y[3]); *(u32x2_t*)(A2 + off + bj * HALF + n * 16) = w; } }
;                 if constexpr (EMIT) { ss += __shfl_xor(ss, 16); ss += __shfl_xor(ss, 32); if (fq == 0) atomicAdd(ssq + row, (unsigned long long)(ss * 16777216.0f)); } }
;             asm volatile("" ::: "memory");
	v_pk_fma_f32 v[94:95], v[94:95], v[142:143], v[98:99]
	v_pk_fma_f32 v[92:93], v[92:93], v[140:141], v[96:97]
	v_pk_fma_f32 v[90:91], v[90:91], v[138:139], v[102:103]
	v_pk_fma_f32 v[88:89], v[88:89], v[136:137], v[100:101]
	v_pk_fma_f32 v[78:79], v[78:79], v[134:135], v[106:107]
	v_pk_fma_f32 v[76:77], v[76:77], v[132:133], v[104:105]
	v_pk_fma_f32 v[74:75], v[74:75], v[130:131], v[110:111]
	v_pk_fma_f32 v[72:73], v[72:73], v[128:129], v[108:109]
	v_pk_fma_f32 v[86:87], v[86:87], v[142:143], v[114:115]
	v_pk_fma_f32 v[84:85], v[84:85], v[140:141], v[112:113]
	v_pk_fma_f32 v[82:83], v[82:83], v[138:139], v[118:119]
	v_pk_fma_f32 v[80:81], v[80:81], v[136:137], v[116:117]
	v_pk_fma_f32 v[70:71], v[70:71], v[134:135], v[122:123]
	v_pk_fma_f32 v[68:69], v[68:69], v[132:133], v[120:121]
	v_pk_fma_f32 v[66:67], v[66:67], v[130:131], v[126:127]
	v_pk_fma_f32 v[64:65], v[64:65], v[128:129], v[124:125]
	global_store_dwordx4 v[170:171], v[92:95], off
	global_store_dwordx4 v[170:171], v[88:91], off offset:64
	global_store_dwordx4 v[170:171], v[76:79], off offset:512
	global_store_dwordx4 v[170:171], v[72:75], off offset:576
	global_store_dwordx4 v[166:167], v[84:87], off
	global_store_dwordx4 v[166:167], v[80:83], off offset:64
	global_store_dwordx4 v[166:167], v[68:71], off offset:512
	global_store_dwordx4 v[166:167], v[64:67], off offset:576
	v_lshl_add_u64 v[96:97], v[160:161], 0, s[20:21]
	v_lshl_add_u64 v[92:93], v[158:159], 0, v[96:97]
	global_load_dwordx4 v[64:67], v[172:173], off nt
	global_load_dwordx4 v[68:71], v[172:173], off offset:64 nt
	global_load_dwordx4 v[72:75], v[172:173], off offset:512 nt
	global_load_dwordx4 v[76:79], v[172:173], off offset:576 nt
	global_load_dwordx4 v[80:83], v[92:93], off nt
	global_load_dwordx4 v[84:87], v[92:93], off offset:64 nt
	global_load_dwordx4 v[88:91], v[92:93], off offset:512 nt
	s_nop 0
	global_load_dwordx4 v[92:95], v[92:93], off offset:576 nt
	v_lshl_add_u64 v[100:101], s[6:7], 0, v[168:169]
	v_lshl_add_u64 v[96:97], s[6:7], 0, v[96:97]
	v_lshl_add_u64 v[100:101], v[100:101], 0, v[156:157]
	v_lshl_add_u64 v[98:99], v[160:161], 0, s[22:23]
	v_lshl_add_u64 v[96:97], v[96:97], 0, v[156:157]
	v_lshl_add_u64 v[102:103], v[158:159], 0, v[98:99]
	s_waitcnt vmcnt(0) lgkmcnt(0)
	v_pk_fma_f32 v[62:63], v[62:63], v[142:143], v[66:67]
	v_pk_fma_f32 v[60:61], v[60:61], v[140:141], v[64:65]
	v_pk_fma_f32 v[58:59], v[58:59], v[138:139], v[70:71]
	v_pk_fma_f32 v[56:57], v[56:57], v[136:137], v[68:69]
	v_pk_fma_f32 v[46:47], v[46:47], v[134:135], v[74:75]
	v_pk_fma_f32 v[44:45], v[44:45], v[132:133], v[72:73]
	v_pk_fma_f32 v[42:43], v[42:43], v[130:131], v[78:79]
	v_pk_fma_f32 v[40:41], v[40:41], v[128:129], v[76:77]
	v_pk_fma_f32 v[54:55], v[54:55], v[142:143], v[82:83]
	v_pk_fma_f32 v[52:53], v[52:53], v[140:141], v[80:81]
	v_pk_fma_f32 v[50:51], v[50:51], v[138:139], v[86:87]
	v_pk_fma_f32 v[48:49], v[48:49], v[136:137], v[84:85]
	v_pk_fma_f32 v[38:39], v[38:39], v[134:135], v[90:91]
	v_pk_fma_f32 v[36:37], v[36:37], v[132:133], v[88:89]
	v_pk_fma_f32 v[34:35], v[34:35], v[130:131], v[94:95]
	v_pk_fma_f32 v[32:33], v[32:33], v[128:129], v[92:93]
	global_store_dwordx4 v[100:101], v[60:63], off
	global_store_dwordx4 v[100:101], v[56:59], off offset:64
	global_store_dwordx4 v[100:101], v[44:47], off offset:512
	global_store_dwordx4 v[100:101], v[40:43], off offset:576
	global_store_dwordx4 v[96:97], v[52:55], off
	global_store_dwordx4 v[96:97], v[48:51], off offset:64
	global_store_dwordx4 v[96:97], v[36:39], off offset:512
	global_store_dwordx4 v[96:97], v[32:35], off offset:576
	v_lshl_add_u64 v[64:65], v[160:161], 0, s[8:9]
	v_lshl_add_u64 v[66:67], v[158:159], 0, v[64:65]
	global_load_dwordx4 v[32:35], v[102:103], off nt
	global_load_dwordx4 v[36:39], v[102:103], off offset:64 nt
	global_load_dwordx4 v[40:43], v[102:103], off offset:512 nt
	global_load_dwordx4 v[44:47], v[102:103], off offset:576 nt
	global_load_dwordx4 v[48:51], v[66:67], off nt
	global_load_dwordx4 v[52:55], v[66:67], off offset:64 nt
	global_load_dwordx4 v[56:59], v[66:67], off offset:512 nt
	global_load_dwordx4 v[60:63], v[66:67], off offset:576 nt
	v_lshl_add_u64 v[66:67], s[6:7], 0, v[98:99]
	v_lshl_add_u64 v[64:65], s[6:7], 0, v[64:65]
	v_lshl_add_u64 v[66:67], v[66:67], 0, v[156:157]
	v_lshl_add_u64 v[64:65], v[64:65], 0, v[156:157]
	s_waitcnt vmcnt(0) lgkmcnt(0)
	v_pk_fma_f32 v[30:31], v[30:31], v[142:143], v[34:35]
	v_pk_fma_f32 v[28:29], v[28:29], v[140:141], v[32:33]
	v_pk_fma_f32 v[26:27], v[26:27], v[138:139], v[38:39]
	v_pk_fma_f32 v[24:25], v[24:25], v[136:137], v[36:37]
	v_pk_fma_f32 v[14:15], v[14:15], v[134:135], v[42:43]
	v_pk_fma_f32 v[12:13], v[12:13], v[132:133], v[40:41]
	v_pk_fma_f32 v[10:11], v[10:11], v[130:131], v[46:47]
	v_pk_fma_f32 v[8:9], v[8:9], v[128:129], v[44:45]
	v_pk_fma_f32 v[22:23], v[22:23], v[142:143], v[50:51]
	v_pk_fma_f32 v[20:21], v[20:21], v[140:141], v[48:49]
	v_pk_fma_f32 v[18:19], v[18:19], v[138:139], v[54:55]
	v_pk_fma_f32 v[16:17], v[16:17], v[136:137], v[52:53]
	v_pk_fma_f32 v[6:7], v[6:7], v[134:135], v[58:59]
	v_pk_fma_f32 v[4:5], v[4:5], v[132:133], v[56:57]
	v_pk_fma_f32 v[2:3], v[2:3], v[130:131], v[62:63]
	v_pk_fma_f32 v[0:1], v[0:1], v[128:129], v[60:61]
	global_store_dwordx4 v[66:67], v[28:31], off
	global_store_dwordx4 v[66:67], v[24:27], off offset:64
	global_store_dwordx4 v[66:67], v[12:15], off offset:512
	global_store_dwordx4 v[66:67], v[8:11], off offset:576
	global_store_dwordx4 v[64:65], v[20:23], off
	global_store_dwordx4 v[64:65], v[16:19], off offset:64
	global_store_dwordx4 v[64:65], v[4:7], off offset:512
	global_store_dwordx4 v[64:65], v[0:3], off offset:576
	s_cbranch_vccnz .LBB0_1450
	s_andn2_b64 vcc, exec, s[10:11]
	s_cbranch_vccnz .LBB0_1449
	s_barrier
	s_branch .LBB0_1449
